# GEMM main loops: 48 back-to-back s_setprio 0 / s_setprio 1 pairs between adjacent MFMA clusters removed (priority held across the merged cluster)
# speedup vs baseline: 1.0159x; 1.0159x over previous
; #define PG8_STAGE(bufoff, gbase, voff) do { _Pragma("unroll") for (int _i = 0; _i < 2; ++_i) \
;         __builtin_amdgcn_global_load_lds((const unsigned*)((const char*)(gbase) + (voff)[_i]), (LAS unsigned*)(lds + (bufoff) + ldsw + _i * 8192), 16, 0, 0); } while (0)
; #define PG8_LDA(dst, b, h) do { _Pragma("unroll") for (int m = 0; m < 4; ++m) _Pragma("unroll") for (int k = 0; k < 2; ++k) dst[m][k] = *(const LAS bf16x8*)(lds + PG8_SA(b, h) + aoff + m * 2048 + k * 1024); } while (0)
; #define PG8_LDB(dst, b, h) do { _Pragma("unroll") for (int n = 0; n < 2; ++n) _Pragma("unroll") for (int k = 0; k < 2; ++k) dst[n][k] = *(const LAS bf16x8*)(lds + PG8_SB(b, h) + boff + n * 2048 + k * 1024); } while (0)
; #define PG8_MMA(ai, bj, At, Bt) do { __builtin_amdgcn_s_setprio(1); _Pragma("unroll") for (int m = 0; m < 4; ++m) _Pragma("unroll") for (int n = 0; n < 2; ++n) _Pragma("unroll") for (int k = 0; k < 2; ++k) \
;         acc[ai][bj][m][n] = __builtin_amdgcn_mfma_f32_16x16x32_bf16(Bt[n][k], At[m][k], acc[ai][bj][m][n], 0, 0, 0); __builtin_amdgcn_s_setprio(0); } while (0)
; #define PG8_WAIT_V(n) asm volatile("s_waitcnt vmcnt(" #n ")" ::: "memory")
; #define PG8_WAIT_L(n) asm volatile("s_waitcnt lgkmcnt(" #n ")" ::: "memory")
; #define PG8_BAR __builtin_amdgcn_s_barrier()
; #define PG8_SCHED __builtin_amdgcn_sched_barrier(0)
; template <class Epi>
; __device__ __forceinline__ void gemm_phase(LAS unsigned char* lds, const Gemm g, const Sched& S, const Epi& E, const int tid) {
;     ...
;         for (int t = 0; t < nt; t += 2) {
;             const bool last = (t == nt - 2);
;             const char* a1 = cA + (size_t)(t + 1) * kstep;
;             const char* a2 = last ? nA : cA + (size_t)(t + 2) * kstep; const char* b2 = last ? nB : cB + (size_t)(t + 2) * kstep;
;             const char* a3 = a2 + kstep; const char* b3 = b2 + kstep;
;             PG8_LDB(B0, 0, 0); PG8_LDB(B1, 0, 1); PG8_SCHED; PG8_LDA(At, 0, 0); PG8_STAGE(PG8_SA(1, 1), a1 + hA, voffA);
;             PG8_WAIT_V(8); PG8_WAIT_L(0); PG8_BAR; PG8_MMA(0, 0, At, B0); PG8_MMA(0, 1, At, B1); PG8_BAR; PG8_SCHED;
;             PG8_LDA(At, 0, 1); PG8_STAGE(PG8_SB(0, 0), b2, voffB); PG8_STAGE(PG8_SB(0, 1), b2 + hB, voffB); PG8_STAGE(PG8_SA(0, 0), a2, voffA);
;             PG8_WAIT_V(8); PG8_WAIT_L(0); PG8_BAR; PG8_MMA(1, 0, At, B0); PG8_MMA(1, 1, At, B1); PG8_BAR; PG8_SCHED;
.LBB0_332:
	s_add_u32 s10, s10, 0x40080
	s_addc_u32 s11, s11, 0
	s_add_u32 s9, s74, 0x100
	s_addc_u32 s19, s75, 0
	s_mov_b32 s21, -2
	s_add_u32 s35, s10, 0xfffc0080
	s_addc_u32 s37, s11, -1
	s_add_i32 vcc_lo, 0, 0x10000
	s_cmp_eq_u32 s21, 12
	s_cselect_b32 s77, s23, s37
	s_cselect_b32 s76, s22, s35
	s_cselect_b32 s75, s73, s19
	s_cselect_b32 s74, s72, s9
	s_add_i32 s35, 0, 0x14000
	v_add_u32_e32 v156, vcc_lo, v145
	v_add_u32_e32 v172, s35, v145
	ds_read_b128 v[140:143], v156
	ds_read_b128 v[148:151], v156 offset:1024
	ds_read_b128 v[152:155], v156 offset:2048
	ds_read_b128 v[156:159], v156 offset:3072
	ds_read_b128 v[160:163], v172
	ds_read_b128 v[164:167], v172 offset:1024
	ds_read_b128 v[168:171], v172 offset:2048
	ds_read_b128 v[172:175], v172 offset:3072
	v_lshl_add_u64 v[190:191], s[10:11], 0, v[136:137]
	s_add_i32 m0, s13, 0xc000
	ds_read_b128 v[178:181], v147
	ds_read_b128 v[182:185], v147 offset:1024
	ds_read_b128 v[186:189], v147 offset:2048
	ds_read_b128 v[194:197], v147 offset:3072
	ds_read_b128 v[198:201], v147 offset:4096
	ds_read_b128 v[202:205], v147 offset:5120
	ds_read_b128 v[206:209], v147 offset:6144
	ds_read_b128 v[210:213], v147 offset:7168
	global_load_lds_dwordx4 v[190:191], off
	v_lshl_add_u64 v[190:191], s[10:11], 0, v[138:139]
	s_add_i32 m0, s13, 0xe000
	s_nop 0
	global_load_lds_dwordx4 v[190:191], off
	s_waitcnt vmcnt(8)
	s_waitcnt lgkmcnt(0)
	s_barrier
	s_setprio 1
	s_waitcnt lgkmcnt(0)
	v_mfma_f32_16x16x32_bf16 v[124:127], v[140:143], v[178:181], 0
	v_mfma_f32_16x16x32_bf16 v[120:123], v[152:155], v[178:181], 0
	v_mfma_f32_16x16x32_bf16 v[116:119], v[140:143], v[186:189], 0
	v_mfma_f32_16x16x32_bf16 v[108:111], v[152:155], v[186:189], 0
	v_mfma_f32_16x16x32_bf16 v[92:95], v[140:143], v[198:201], 0
	v_mfma_f32_16x16x32_bf16 v[88:91], v[152:155], v[198:201], 0
	v_mfma_f32_16x16x32_bf16 v[84:87], v[140:143], v[206:209], 0
	v_mfma_f32_16x16x32_bf16 v[76:79], v[152:155], v[206:209], 0
	v_mfma_f32_16x16x32_bf16 v[124:127], v[148:151], v[182:185], v[124:127]
	v_mfma_f32_16x16x32_bf16 v[120:123], v[156:159], v[182:185], v[120:123]
	v_mfma_f32_16x16x32_bf16 v[116:119], v[148:151], v[194:197], v[116:119]
	v_mfma_f32_16x16x32_bf16 v[108:111], v[156:159], v[194:197], v[108:111]
	v_mfma_f32_16x16x32_bf16 v[92:95], v[148:151], v[202:205], v[92:95]
	v_mfma_f32_16x16x32_bf16 v[88:91], v[156:159], v[202:205], v[88:91]
	v_mfma_f32_16x16x32_bf16 v[84:87], v[148:151], v[210:213], v[84:87]
	v_mfma_f32_16x16x32_bf16 v[76:79], v[156:159], v[210:213], v[76:79]
	v_mfma_f32_16x16x32_bf16 v[112:115], v[160:163], v[178:181], 0
	v_mfma_f32_16x16x32_bf16 v[104:107], v[168:171], v[178:181], 0
	v_mfma_f32_16x16x32_bf16 v[100:103], v[160:163], v[186:189], 0
	v_mfma_f32_16x16x32_bf16 v[96:99], v[168:171], v[186:189], 0
	v_mfma_f32_16x16x32_bf16 v[80:83], v[160:163], v[198:201], 0
	v_mfma_f32_16x16x32_bf16 v[72:75], v[168:171], v[198:201], 0
	v_mfma_f32_16x16x32_bf16 v[68:71], v[160:163], v[206:209], 0
	v_mfma_f32_16x16x32_bf16 v[64:67], v[168:171], v[206:209], 0
	v_mfma_f32_16x16x32_bf16 v[112:115], v[164:167], v[182:185], v[112:115]
	v_mfma_f32_16x16x32_bf16 v[104:107], v[172:175], v[182:185], v[104:107]
	v_mfma_f32_16x16x32_bf16 v[100:103], v[164:167], v[194:197], v[100:103]
	v_mfma_f32_16x16x32_bf16 v[96:99], v[172:175], v[194:197], v[96:99]
	v_mfma_f32_16x16x32_bf16 v[80:83], v[164:167], v[202:205], v[80:83]
	v_mfma_f32_16x16x32_bf16 v[72:75], v[172:175], v[202:205], v[72:75]
	v_mfma_f32_16x16x32_bf16 v[68:71], v[164:167], v[210:213], v[68:71]
	v_mfma_f32_16x16x32_bf16 v[64:67], v[172:175], v[210:213], v[64:67]
	s_setprio 0
	s_barrier
	s_add_i32 s37, vcc_lo, s39
	v_lshl_add_u64 v[190:191], s[74:75], 0, v[192:193]
	s_mov_b32 m0, s37
	ds_read_b128 v[178:181], v147 offset:16384
	ds_read_b128 v[182:185], v147 offset:17408
	ds_read_b128 v[186:189], v147 offset:18432
	ds_read_b128 v[194:197], v147 offset:19456
	ds_read_b128 v[198:201], v147 offset:20480
	ds_read_b128 v[202:205], v147 offset:21504
	ds_read_b128 v[206:209], v147 offset:22528
	ds_read_b128 v[210:213], v147 offset:23552
	global_load_lds_dwordx4 v[190:191], off
	s_add_i32 m0, s37, 0x2000
	s_add_u32 vcc_lo, s74, 0x40000
	v_lshl_add_u64 v[214:215], s[74:75], 0, v[132:133]
	s_addc_u32 vcc_hi, s75, 0
	s_add_i32 s35, s35, s39
	global_load_lds_dwordx4 v[214:215], off
	v_lshl_add_u64 v[216:217], vcc, 0, v[192:193]
	s_mov_b32 m0, s35
	v_lshl_add_u64 v[218:219], s[76:77], 0, v[130:131]
	global_load_lds_dwordx4 v[216:217], off
	v_lshl_add_u64 v[216:217], vcc, 0, v[132:133]
	s_add_i32 m0, s35, 0x2000
	s_nop 0
	global_load_lds_dwordx4 v[216:217], off
	v_lshl_add_u64 v[216:217], s[76:77], 0, v[128:129]
	s_mov_b32 m0, s13
	s_nop 0
	global_load_lds_dwordx4 v[216:217], off
	s_mov_b32 m0, s40
	s_nop 0
	global_load_lds_dwordx4 v[218:219], off
	s_waitcnt vmcnt(8)
	s_waitcnt lgkmcnt(0)
	s_barrier
; #define PG8_STAGE(bufoff, gbase, voff) do { _Pragma("unroll") for (int _i = 0; _i < 2; ++_i) \
;         __builtin_amdgcn_global_load_lds((const unsigned*)((const char*)(gbase) + (voff)[_i]), (LAS unsigned*)(lds + (bufoff) + ldsw + _i * 8192), 16, 0, 0); } while (0)
; #define PG8_LDA(dst, b, h) do { _Pragma("unroll") for (int m = 0; m < 4; ++m) _Pragma("unroll") for (int k = 0; k < 2; ++k) dst[m][k] = *(const LAS bf16x8*)(lds + PG8_SA(b, h) + aoff + m * 2048 + k * 1024); } while (0)
; #define PG8_LDB(dst, b, h) do { _Pragma("unroll") for (int n = 0; n < 2; ++n) _Pragma("unroll") for (int k = 0; k < 2; ++k) dst[n][k] = *(const LAS bf16x8*)(lds + PG8_SB(b, h) + boff + n * 2048 + k * 1024); } while (0)
; #define PG8_MMA(ai, bj, At, Bt) do { __builtin_amdgcn_s_setprio(1); _Pragma("unroll") for (int m = 0; m < 4; ++m) _Pragma("unroll") for (int n = 0; n < 2; ++n) _Pragma("unroll") for (int k = 0; k < 2; ++k) \
;         acc[ai][bj][m][n] = __builtin_amdgcn_mfma_f32_16x16x32_bf16(Bt[n][k], At[m][k], acc[ai][bj][m][n], 0, 0, 0); __builtin_amdgcn_s_setprio(0); } while (0)
; #define PG8_WAIT_V(n) asm volatile("s_waitcnt vmcnt(" #n ")" ::: "memory")
; #define PG8_WAIT_L(n) asm volatile("s_waitcnt lgkmcnt(" #n ")" ::: "memory")
; #define PG8_BAR __builtin_amdgcn_s_barrier()
; #define PG8_SCHED __builtin_amdgcn_sched_barrier(0)
; template <class Epi>
; __device__ __forceinline__ void gemm_phase(LAS unsigned char* lds, const Gemm g, const Sched& S, const Epi& E, const int tid) {
;     ...
;             PG8_WAIT_V(8); PG8_WAIT_L(0); PG8_BAR; PG8_MMA(1, 0, At, B0); PG8_MMA(1, 1, At, B1); PG8_BAR; PG8_SCHED;
;             PG8_LDB(B0, 1, 0); PG8_LDB(B1, 1, 1); PG8_SCHED; PG8_LDA(At, 1, 0); PG8_STAGE(PG8_SA(0, 1), a2 + hA, voffA);
;             PG8_WAIT_V(8); PG8_WAIT_L(0); PG8_BAR; PG8_MMA(0, 0, At, B0); PG8_MMA(0, 1, At, B1); PG8_BAR; PG8_SCHED;
	s_setprio 1
	s_waitcnt lgkmcnt(0)
	v_mfma_f32_16x16x32_bf16 v[60:63], v[140:143], v[178:181], 0
	v_mfma_f32_16x16x32_bf16 v[56:59], v[152:155], v[178:181], 0
	v_mfma_f32_16x16x32_bf16 v[52:55], v[140:143], v[186:189], 0
	v_mfma_f32_16x16x32_bf16 v[44:47], v[152:155], v[186:189], 0
	v_mfma_f32_16x16x32_bf16 v[28:31], v[140:143], v[198:201], 0
	v_mfma_f32_16x16x32_bf16 v[24:27], v[152:155], v[198:201], 0
	v_mfma_f32_16x16x32_bf16 v[20:23], v[140:143], v[206:209], 0
	v_mfma_f32_16x16x32_bf16 v[12:15], v[152:155], v[206:209], 0
	v_mfma_f32_16x16x32_bf16 v[60:63], v[148:151], v[182:185], v[60:63]
	v_mfma_f32_16x16x32_bf16 v[56:59], v[156:159], v[182:185], v[56:59]
	v_mfma_f32_16x16x32_bf16 v[52:55], v[148:151], v[194:197], v[52:55]
	v_mfma_f32_16x16x32_bf16 v[44:47], v[156:159], v[194:197], v[44:47]
	v_mfma_f32_16x16x32_bf16 v[28:31], v[148:151], v[202:205], v[28:31]
	v_mfma_f32_16x16x32_bf16 v[24:27], v[156:159], v[202:205], v[24:27]
	v_mfma_f32_16x16x32_bf16 v[20:23], v[148:151], v[210:213], v[20:23]
	v_mfma_f32_16x16x32_bf16 v[12:15], v[156:159], v[210:213], v[12:15]
	v_mfma_f32_16x16x32_bf16 v[48:51], v[160:163], v[178:181], 0
	v_mfma_f32_16x16x32_bf16 v[40:43], v[168:171], v[178:181], 0
	v_mfma_f32_16x16x32_bf16 v[36:39], v[160:163], v[186:189], 0
	v_mfma_f32_16x16x32_bf16 v[32:35], v[168:171], v[186:189], 0
	v_mfma_f32_16x16x32_bf16 v[16:19], v[160:163], v[198:201], 0
	v_mfma_f32_16x16x32_bf16 v[8:11], v[168:171], v[198:201], 0
	v_mfma_f32_16x16x32_bf16 v[4:7], v[160:163], v[206:209], 0
	v_mfma_f32_16x16x32_bf16 v[0:3], v[168:171], v[206:209], 0
	v_mfma_f32_16x16x32_bf16 v[48:51], v[164:167], v[182:185], v[48:51]
	v_mfma_f32_16x16x32_bf16 v[40:43], v[172:175], v[182:185], v[40:43]
	v_mfma_f32_16x16x32_bf16 v[36:39], v[164:167], v[194:197], v[36:39]
	v_mfma_f32_16x16x32_bf16 v[32:35], v[172:175], v[194:197], v[32:35]
	v_mfma_f32_16x16x32_bf16 v[16:19], v[164:167], v[202:205], v[16:19]
	v_mfma_f32_16x16x32_bf16 v[8:11], v[172:175], v[202:205], v[8:11]
	v_mfma_f32_16x16x32_bf16 v[4:7], v[164:167], v[210:213], v[4:7]
	v_mfma_f32_16x16x32_bf16 v[0:3], v[172:175], v[210:213], v[0:3]
	s_setprio 0
	s_barrier
	s_add_i32 s35, 0, 0x18000
	s_add_i32 s37, 0, 0x1c000
	v_add_u32_e32 v156, s35, v145
	v_add_u32_e32 v172, s37, v145
	ds_read_b128 v[140:143], v156
	ds_read_b128 v[148:151], v156 offset:1024
	ds_read_b128 v[152:155], v156 offset:2048
	ds_read_b128 v[156:159], v156 offset:3072
	ds_read_b128 v[160:163], v172
	ds_read_b128 v[164:167], v172 offset:1024
	ds_read_b128 v[168:171], v172 offset:2048
	ds_read_b128 v[172:175], v172 offset:3072
	s_add_u32 s76, s76, 0x40000
	s_addc_u32 s77, s77, 0
	s_mov_b32 m0, s45
	v_lshl_add_u64 v[224:225], s[76:77], 0, v[128:129]
	ds_read_b128 v[178:181], v147 offset:32768
	ds_read_b128 v[182:185], v147 offset:33792
	ds_read_b128 v[186:189], v147 offset:34816
	ds_read_b128 v[194:197], v147 offset:35840
	ds_read_b128 v[198:201], v147 offset:36864
	ds_read_b128 v[202:205], v147 offset:37888
	ds_read_b128 v[206:209], v147 offset:38912
	ds_read_b128 v[210:213], v147 offset:39936
	global_load_lds_dwordx4 v[224:225], off
	v_lshl_add_u64 v[224:225], s[76:77], 0, v[130:131]
	s_mov_b32 m0, s47
	s_nop 0
	global_load_lds_dwordx4 v[224:225], off
	s_waitcnt vmcnt(8)
	s_waitcnt lgkmcnt(0)
	s_barrier
	s_setprio 1
	s_waitcnt lgkmcnt(0)
	v_mfma_f32_16x16x32_bf16 v[124:127], v[140:143], v[178:181], v[124:127]
	v_mfma_f32_16x16x32_bf16 v[120:123], v[152:155], v[178:181], v[120:123]
	v_mfma_f32_16x16x32_bf16 v[116:119], v[140:143], v[186:189], v[116:119]
	v_mfma_f32_16x16x32_bf16 v[108:111], v[152:155], v[186:189], v[108:111]
	v_mfma_f32_16x16x32_bf16 v[92:95], v[140:143], v[198:201], v[92:95]
	v_mfma_f32_16x16x32_bf16 v[88:91], v[152:155], v[198:201], v[88:91]
	v_mfma_f32_16x16x32_bf16 v[84:87], v[140:143], v[206:209], v[84:87]
	v_mfma_f32_16x16x32_bf16 v[76:79], v[152:155], v[206:209], v[76:79]
	v_mfma_f32_16x16x32_bf16 v[124:127], v[148:151], v[182:185], v[124:127]
	v_mfma_f32_16x16x32_bf16 v[120:123], v[156:159], v[182:185], v[120:123]
	v_mfma_f32_16x16x32_bf16 v[116:119], v[148:151], v[194:197], v[116:119]
	v_mfma_f32_16x16x32_bf16 v[108:111], v[156:159], v[194:197], v[108:111]
	v_mfma_f32_16x16x32_bf16 v[92:95], v[148:151], v[202:205], v[92:95]
	v_mfma_f32_16x16x32_bf16 v[88:91], v[156:159], v[202:205], v[88:91]
	v_mfma_f32_16x16x32_bf16 v[84:87], v[148:151], v[210:213], v[84:87]
	v_mfma_f32_16x16x32_bf16 v[76:79], v[156:159], v[210:213], v[76:79]
	v_mfma_f32_16x16x32_bf16 v[112:115], v[160:163], v[178:181], v[112:115]
	v_mfma_f32_16x16x32_bf16 v[104:107], v[168:171], v[178:181], v[104:107]
	v_mfma_f32_16x16x32_bf16 v[100:103], v[160:163], v[186:189], v[100:103]
	v_mfma_f32_16x16x32_bf16 v[96:99], v[168:171], v[186:189], v[96:99]
	v_mfma_f32_16x16x32_bf16 v[80:83], v[160:163], v[198:201], v[80:83]
	v_mfma_f32_16x16x32_bf16 v[72:75], v[168:171], v[198:201], v[72:75]
	v_mfma_f32_16x16x32_bf16 v[68:71], v[160:163], v[206:209], v[68:71]
	v_mfma_f32_16x16x32_bf16 v[64:67], v[168:171], v[206:209], v[64:67]
	v_mfma_f32_16x16x32_bf16 v[112:115], v[164:167], v[182:185], v[112:115]
	v_mfma_f32_16x16x32_bf16 v[104:107], v[172:175], v[182:185], v[104:107]
	v_mfma_f32_16x16x32_bf16 v[100:103], v[164:167], v[194:197], v[100:103]
	v_mfma_f32_16x16x32_bf16 v[96:99], v[172:175], v[194:197], v[96:99]
	v_mfma_f32_16x16x32_bf16 v[80:83], v[164:167], v[202:205], v[80:83]
	v_mfma_f32_16x16x32_bf16 v[72:75], v[172:175], v[202:205], v[72:75]
	v_mfma_f32_16x16x32_bf16 v[68:71], v[164:167], v[210:213], v[68:71]
	v_mfma_f32_16x16x32_bf16 v[64:67], v[172:175], v[210:213], v[64:67]
	s_setprio 0
	s_barrier
; #define PG8_STAGE(bufoff, gbase, voff) do { _Pragma("unroll") for (int _i = 0; _i < 2; ++_i) \
;         __builtin_amdgcn_global_load_lds((const unsigned*)((const char*)(gbase) + (voff)[_i]), (LAS unsigned*)(lds + (bufoff) + ldsw + _i * 8192), 16, 0, 0); } while (0)
; #define PG8_LDA(dst, b, h) do { _Pragma("unroll") for (int m = 0; m < 4; ++m) _Pragma("unroll") for (int k = 0; k < 2; ++k) dst[m][k] = *(const LAS bf16x8*)(lds + PG8_SA(b, h) + aoff + m * 2048 + k * 1024); } while (0)
; #define PG8_LDB(dst, b, h) do { _Pragma("unroll") for (int n = 0; n < 2; ++n) _Pragma("unroll") for (int k = 0; k < 2; ++k) dst[n][k] = *(const LAS bf16x8*)(lds + PG8_SB(b, h) + boff + n * 2048 + k * 1024); } while (0)
; #define PG8_MMA(ai, bj, At, Bt) do { __builtin_amdgcn_s_setprio(1); _Pragma("unroll") for (int m = 0; m < 4; ++m) _Pragma("unroll") for (int n = 0; n < 2; ++n) _Pragma("unroll") for (int k = 0; k < 2; ++k) \
;         acc[ai][bj][m][n] = __builtin_amdgcn_mfma_f32_16x16x32_bf16(Bt[n][k], At[m][k], acc[ai][bj][m][n], 0, 0, 0); __builtin_amdgcn_s_setprio(0); } while (0)
; #define PG8_WAIT_V(n) asm volatile("s_waitcnt vmcnt(" #n ")" ::: "memory")
; #define PG8_WAIT_L(n) asm volatile("s_waitcnt lgkmcnt(" #n ")" ::: "memory")
; #define PG8_BAR __builtin_amdgcn_s_barrier()
; #define PG8_SCHED __builtin_amdgcn_sched_barrier(0)
; template <class Epi>
; __device__ __forceinline__ void gemm_phase(LAS unsigned char* lds, const Gemm g, const Sched& S, const Epi& E, const int tid) {
;     ...
;         for (int t = 0; t < nt; t += 2) {
;             const bool last = (t == nt - 2);
;             const char* a1 = cA + (size_t)(t + 1) * kstep;
;             const char* a2 = last ? nA : cA + (size_t)(t + 2) * kstep; const char* b2 = last ? nB : cB + (size_t)(t + 2) * kstep;
;             const char* a3 = a2 + kstep; const char* b3 = b2 + kstep;
;             PG8_LDB(B0, 0, 0); PG8_LDB(B1, 0, 1); PG8_SCHED; PG8_LDA(At, 0, 0); PG8_STAGE(PG8_SA(1, 1), a1 + hA, voffA);
;     ...
;             PG8_LDA(At, 1, 1); PG8_STAGE(PG8_SB(1, 0), b3, voffB); PG8_STAGE(PG8_SB(1, 1), b3 + hB, voffB); PG8_STAGE(PG8_SA(1, 0), a3, voffA);
;             PG8_WAIT_V(8); PG8_WAIT_L(0); PG8_BAR; PG8_MMA(1, 0, At, B0); PG8_MMA(1, 1, At, B1); PG8_BAR; PG8_SCHED;
	s_add_i32 s35, s35, s39
	v_lshl_add_u64 v[190:191], v[190:191], 0, s[94:95]
	s_mov_b32 m0, s35
	ds_read_b128 v[178:181], v147 offset:49152
	ds_read_b128 v[182:185], v147 offset:50176
	ds_read_b128 v[186:189], v147 offset:51200
	ds_read_b128 v[194:197], v147 offset:52224
	ds_read_b128 v[198:201], v147 offset:53248
	ds_read_b128 v[202:205], v147 offset:54272
	ds_read_b128 v[206:209], v147 offset:55296
	ds_read_b128 v[210:213], v147 offset:56320
	global_load_lds_dwordx4 v[190:191], off
	s_add_i32 m0, s35, 0x2000
	s_add_u32 s74, s74, 0x40080
	v_lshl_add_u64 v[190:191], v[214:215], 0, s[94:95]
	s_addc_u32 s75, s75, 0
	s_add_i32 s35, s37, s39
	global_load_lds_dwordx4 v[190:191], off
	v_lshl_add_u64 v[190:191], s[74:75], 0, v[192:193]
	s_mov_b32 m0, s35
	s_nop 0
	global_load_lds_dwordx4 v[190:191], off
	v_lshl_add_u64 v[190:191], s[74:75], 0, v[132:133]
	s_add_i32 m0, s35, 0x2000
	s_nop 0
	global_load_lds_dwordx4 v[190:191], off
	v_lshl_add_u64 v[190:191], v[216:217], 0, s[94:95]
	s_mov_b32 m0, s78
	s_nop 0
	global_load_lds_dwordx4 v[190:191], off
	v_lshl_add_u64 v[190:191], v[218:219], 0, s[94:95]
	s_mov_b32 m0, s80
	s_nop 0
	global_load_lds_dwordx4 v[190:191], off
	s_waitcnt vmcnt(8)
	s_waitcnt lgkmcnt(0)
	s_barrier
	s_setprio 1
	s_waitcnt lgkmcnt(0)
	v_mfma_f32_16x16x32_bf16 v[60:63], v[140:143], v[178:181], v[60:63]
	v_mfma_f32_16x16x32_bf16 v[56:59], v[152:155], v[178:181], v[56:59]
	v_mfma_f32_16x16x32_bf16 v[52:55], v[140:143], v[186:189], v[52:55]
	v_mfma_f32_16x16x32_bf16 v[44:47], v[152:155], v[186:189], v[44:47]
	v_mfma_f32_16x16x32_bf16 v[28:31], v[140:143], v[198:201], v[28:31]
	v_mfma_f32_16x16x32_bf16 v[24:27], v[152:155], v[198:201], v[24:27]
	v_mfma_f32_16x16x32_bf16 v[20:23], v[140:143], v[206:209], v[20:23]
	v_mfma_f32_16x16x32_bf16 v[12:15], v[152:155], v[206:209], v[12:15]
	v_mfma_f32_16x16x32_bf16 v[60:63], v[148:151], v[182:185], v[60:63]
	v_mfma_f32_16x16x32_bf16 v[56:59], v[156:159], v[182:185], v[56:59]
	v_mfma_f32_16x16x32_bf16 v[52:55], v[148:151], v[194:197], v[52:55]
	v_mfma_f32_16x16x32_bf16 v[44:47], v[156:159], v[194:197], v[44:47]
	v_mfma_f32_16x16x32_bf16 v[28:31], v[148:151], v[202:205], v[28:31]
	v_mfma_f32_16x16x32_bf16 v[24:27], v[156:159], v[202:205], v[24:27]
	v_mfma_f32_16x16x32_bf16 v[20:23], v[148:151], v[210:213], v[20:23]
	v_mfma_f32_16x16x32_bf16 v[12:15], v[156:159], v[210:213], v[12:15]
	v_mfma_f32_16x16x32_bf16 v[48:51], v[160:163], v[178:181], v[48:51]
	v_mfma_f32_16x16x32_bf16 v[40:43], v[168:171], v[178:181], v[40:43]
	v_mfma_f32_16x16x32_bf16 v[36:39], v[160:163], v[186:189], v[36:39]
	v_mfma_f32_16x16x32_bf16 v[32:35], v[168:171], v[186:189], v[32:35]
	v_mfma_f32_16x16x32_bf16 v[16:19], v[160:163], v[198:201], v[16:19]
	v_mfma_f32_16x16x32_bf16 v[8:11], v[168:171], v[198:201], v[8:11]
	v_mfma_f32_16x16x32_bf16 v[4:7], v[160:163], v[206:209], v[4:7]
	v_mfma_f32_16x16x32_bf16 v[0:3], v[168:171], v[206:209], v[0:3]
	v_mfma_f32_16x16x32_bf16 v[48:51], v[164:167], v[182:185], v[48:51]
	v_mfma_f32_16x16x32_bf16 v[40:43], v[172:175], v[182:185], v[40:43]
	v_mfma_f32_16x16x32_bf16 v[36:39], v[164:167], v[194:197], v[36:39]
	v_mfma_f32_16x16x32_bf16 v[32:35], v[172:175], v[194:197], v[32:35]
	v_mfma_f32_16x16x32_bf16 v[16:19], v[164:167], v[202:205], v[16:19]
	v_mfma_f32_16x16x32_bf16 v[8:11], v[172:175], v[202:205], v[8:11]
	v_mfma_f32_16x16x32_bf16 v[4:7], v[164:167], v[210:213], v[4:7]
	v_mfma_f32_16x16x32_bf16 v[0:3], v[172:175], v[210:213], v[0:3]
	s_setprio 0
	s_barrier
	s_add_i32 s21, s21, 2
	s_add_u32 s10, s10, 0x100
	s_addc_u32 s11, s11, 0
	s_add_u32 s9, s9, 0x100
	s_addc_u32 s19, s19, 0
	s_cmp_gt_u32 s21, 13
	s_cbranch_scc1 .Lgk_exit_0
.LBB0_333:
	s_add_u32 s35, s10, 0xfffc0080
	s_addc_u32 s37, s11, -1
	s_add_i32 vcc_lo, 0, 0x10000
	s_cmp_eq_u32 s21, 12
	s_cselect_b32 s77, s23, s37
	s_cselect_b32 s76, s22, s35
	s_cselect_b32 s75, s73, s19
	s_cselect_b32 s74, s72, s9
	s_add_i32 s35, 0, 0x14000
	v_add_u32_e32 v156, vcc_lo, v145
	v_add_u32_e32 v172, s35, v145
	ds_read_b128 v[140:143], v156
	ds_read_b128 v[148:151], v156 offset:1024
	ds_read_b128 v[152:155], v156 offset:2048
	ds_read_b128 v[156:159], v156 offset:3072
	ds_read_b128 v[160:163], v172
	ds_read_b128 v[164:167], v172 offset:1024
	ds_read_b128 v[168:171], v172 offset:2048
	ds_read_b128 v[172:175], v172 offset:3072
	v_lshl_add_u64 v[190:191], s[10:11], 0, v[136:137]
	s_add_i32 m0, s13, 0xc000
	ds_read_b128 v[178:181], v147
	ds_read_b128 v[182:185], v147 offset:1024
	ds_read_b128 v[186:189], v147 offset:2048
	ds_read_b128 v[194:197], v147 offset:3072
	ds_read_b128 v[198:201], v147 offset:4096
	ds_read_b128 v[202:205], v147 offset:5120
	ds_read_b128 v[206:209], v147 offset:6144
	ds_read_b128 v[210:213], v147 offset:7168
	global_load_lds_dwordx4 v[190:191], off
	v_lshl_add_u64 v[190:191], s[10:11], 0, v[138:139]
	s_add_i32 m0, s13, 0xe000
	s_nop 0
	global_load_lds_dwordx4 v[190:191], off
	s_waitcnt vmcnt(8)
	s_waitcnt lgkmcnt(0)
	s_barrier
; #define PG8_STAGE(bufoff, gbase, voff) do { _Pragma("unroll") for (int _i = 0; _i < 2; ++_i) \
;         __builtin_amdgcn_global_load_lds((const unsigned*)((const char*)(gbase) + (voff)[_i]), (LAS unsigned*)(lds + (bufoff) + ldsw + _i * 8192), 16, 0, 0); } while (0)
; #define PG8_LDA(dst, b, h) do { _Pragma("unroll") for (int m = 0; m < 4; ++m) _Pragma("unroll") for (int k = 0; k < 2; ++k) dst[m][k] = *(const LAS bf16x8*)(lds + PG8_SA(b, h) + aoff + m * 2048 + k * 1024); } while (0)
; #define PG8_MMA(ai, bj, At, Bt) do { __builtin_amdgcn_s_setprio(1); _Pragma("unroll") for (int m = 0; m < 4; ++m) _Pragma("unroll") for (int n = 0; n < 2; ++n) _Pragma("unroll") for (int k = 0; k < 2; ++k) \
;         acc[ai][bj][m][n] = __builtin_amdgcn_mfma_f32_16x16x32_bf16(Bt[n][k], At[m][k], acc[ai][bj][m][n], 0, 0, 0); __builtin_amdgcn_s_setprio(0); } while (0)
; #define PG8_WAIT_V(n) asm volatile("s_waitcnt vmcnt(" #n ")" ::: "memory")
; #define PG8_WAIT_L(n) asm volatile("s_waitcnt lgkmcnt(" #n ")" ::: "memory")
; #define PG8_BAR __builtin_amdgcn_s_barrier()
; #define PG8_SCHED __builtin_amdgcn_sched_barrier(0)
; template <class Epi>
; __device__ __forceinline__ void gemm_phase(LAS unsigned char* lds, const Gemm g, const Sched& S, const Epi& E, const int tid) {
;     ...
;             PG8_WAIT_V(8); PG8_WAIT_L(0); PG8_BAR; PG8_MMA(0, 0, At, B0); PG8_MMA(0, 1, At, B1); PG8_BAR; PG8_SCHED;
;             PG8_LDA(At, 0, 1); PG8_STAGE(PG8_SB(0, 0), b2, voffB); PG8_STAGE(PG8_SB(0, 1), b2 + hB, voffB); PG8_STAGE(PG8_SA(0, 0), a2, voffA);
;             PG8_WAIT_V(8); PG8_WAIT_L(0); PG8_BAR; PG8_MMA(1, 0, At, B0); PG8_MMA(1, 1, At, B1); PG8_BAR; PG8_SCHED;
	s_setprio 1
	s_waitcnt lgkmcnt(0)
	v_mfma_f32_16x16x32_bf16 v[124:127], v[140:143], v[178:181], v[124:127]
	v_mfma_f32_16x16x32_bf16 v[120:123], v[152:155], v[178:181], v[120:123]
	v_mfma_f32_16x16x32_bf16 v[116:119], v[140:143], v[186:189], v[116:119]
	v_mfma_f32_16x16x32_bf16 v[108:111], v[152:155], v[186:189], v[108:111]
	v_mfma_f32_16x16x32_bf16 v[92:95], v[140:143], v[198:201], v[92:95]
	v_mfma_f32_16x16x32_bf16 v[88:91], v[152:155], v[198:201], v[88:91]
	v_mfma_f32_16x16x32_bf16 v[84:87], v[140:143], v[206:209], v[84:87]
	v_mfma_f32_16x16x32_bf16 v[76:79], v[152:155], v[206:209], v[76:79]
	v_mfma_f32_16x16x32_bf16 v[124:127], v[148:151], v[182:185], v[124:127]
	v_mfma_f32_16x16x32_bf16 v[120:123], v[156:159], v[182:185], v[120:123]
	v_mfma_f32_16x16x32_bf16 v[116:119], v[148:151], v[194:197], v[116:119]
	v_mfma_f32_16x16x32_bf16 v[108:111], v[156:159], v[194:197], v[108:111]
	v_mfma_f32_16x16x32_bf16 v[92:95], v[148:151], v[202:205], v[92:95]
	v_mfma_f32_16x16x32_bf16 v[88:91], v[156:159], v[202:205], v[88:91]
	v_mfma_f32_16x16x32_bf16 v[84:87], v[148:151], v[210:213], v[84:87]
	v_mfma_f32_16x16x32_bf16 v[76:79], v[156:159], v[210:213], v[76:79]
	v_mfma_f32_16x16x32_bf16 v[112:115], v[160:163], v[178:181], v[112:115]
	v_mfma_f32_16x16x32_bf16 v[104:107], v[168:171], v[178:181], v[104:107]
	v_mfma_f32_16x16x32_bf16 v[100:103], v[160:163], v[186:189], v[100:103]
	v_mfma_f32_16x16x32_bf16 v[96:99], v[168:171], v[186:189], v[96:99]
	v_mfma_f32_16x16x32_bf16 v[80:83], v[160:163], v[198:201], v[80:83]
	v_mfma_f32_16x16x32_bf16 v[72:75], v[168:171], v[198:201], v[72:75]
	v_mfma_f32_16x16x32_bf16 v[68:71], v[160:163], v[206:209], v[68:71]
	v_mfma_f32_16x16x32_bf16 v[64:67], v[168:171], v[206:209], v[64:67]
	v_mfma_f32_16x16x32_bf16 v[112:115], v[164:167], v[182:185], v[112:115]
	v_mfma_f32_16x16x32_bf16 v[104:107], v[172:175], v[182:185], v[104:107]
	v_mfma_f32_16x16x32_bf16 v[100:103], v[164:167], v[194:197], v[100:103]
	v_mfma_f32_16x16x32_bf16 v[96:99], v[172:175], v[194:197], v[96:99]
	v_mfma_f32_16x16x32_bf16 v[80:83], v[164:167], v[202:205], v[80:83]
	v_mfma_f32_16x16x32_bf16 v[72:75], v[172:175], v[202:205], v[72:75]
	v_mfma_f32_16x16x32_bf16 v[68:71], v[164:167], v[210:213], v[68:71]
	v_mfma_f32_16x16x32_bf16 v[64:67], v[172:175], v[210:213], v[64:67]
	s_setprio 0
	s_barrier
	s_add_i32 s37, vcc_lo, s39
	v_lshl_add_u64 v[190:191], s[74:75], 0, v[192:193]
	s_mov_b32 m0, s37
	ds_read_b128 v[178:181], v147 offset:16384
	ds_read_b128 v[182:185], v147 offset:17408
	ds_read_b128 v[186:189], v147 offset:18432
	ds_read_b128 v[194:197], v147 offset:19456
	ds_read_b128 v[198:201], v147 offset:20480
	ds_read_b128 v[202:205], v147 offset:21504
	ds_read_b128 v[206:209], v147 offset:22528
	ds_read_b128 v[210:213], v147 offset:23552
	global_load_lds_dwordx4 v[190:191], off
	s_add_i32 m0, s37, 0x2000
	s_add_u32 vcc_lo, s74, 0x40000
	v_lshl_add_u64 v[214:215], s[74:75], 0, v[132:133]
	s_addc_u32 vcc_hi, s75, 0
	s_add_i32 s35, s35, s39
	global_load_lds_dwordx4 v[214:215], off
	v_lshl_add_u64 v[216:217], vcc, 0, v[192:193]
	s_mov_b32 m0, s35
	v_lshl_add_u64 v[218:219], s[76:77], 0, v[130:131]
	global_load_lds_dwordx4 v[216:217], off
	v_lshl_add_u64 v[216:217], vcc, 0, v[132:133]
	s_add_i32 m0, s35, 0x2000
	s_nop 0
	global_load_lds_dwordx4 v[216:217], off
	v_lshl_add_u64 v[216:217], s[76:77], 0, v[128:129]
	s_mov_b32 m0, s13
	s_nop 0
	global_load_lds_dwordx4 v[216:217], off
	s_mov_b32 m0, s40
	s_nop 0
	global_load_lds_dwordx4 v[218:219], off
	s_waitcnt vmcnt(8)
	s_waitcnt lgkmcnt(0)
	s_barrier
	s_setprio 1
	s_waitcnt lgkmcnt(0)
	v_mfma_f32_16x16x32_bf16 v[60:63], v[140:143], v[178:181], v[60:63]
	v_mfma_f32_16x16x32_bf16 v[56:59], v[152:155], v[178:181], v[56:59]
	v_mfma_f32_16x16x32_bf16 v[52:55], v[140:143], v[186:189], v[52:55]
	v_mfma_f32_16x16x32_bf16 v[44:47], v[152:155], v[186:189], v[44:47]
	v_mfma_f32_16x16x32_bf16 v[28:31], v[140:143], v[198:201], v[28:31]
	v_mfma_f32_16x16x32_bf16 v[24:27], v[152:155], v[198:201], v[24:27]
	v_mfma_f32_16x16x32_bf16 v[20:23], v[140:143], v[206:209], v[20:23]
	v_mfma_f32_16x16x32_bf16 v[12:15], v[152:155], v[206:209], v[12:15]
	v_mfma_f32_16x16x32_bf16 v[60:63], v[148:151], v[182:185], v[60:63]
	v_mfma_f32_16x16x32_bf16 v[56:59], v[156:159], v[182:185], v[56:59]
	v_mfma_f32_16x16x32_bf16 v[52:55], v[148:151], v[194:197], v[52:55]
	v_mfma_f32_16x16x32_bf16 v[44:47], v[156:159], v[194:197], v[44:47]
	v_mfma_f32_16x16x32_bf16 v[28:31], v[148:151], v[202:205], v[28:31]
	v_mfma_f32_16x16x32_bf16 v[24:27], v[156:159], v[202:205], v[24:27]
	v_mfma_f32_16x16x32_bf16 v[20:23], v[148:151], v[210:213], v[20:23]
	v_mfma_f32_16x16x32_bf16 v[12:15], v[156:159], v[210:213], v[12:15]
	v_mfma_f32_16x16x32_bf16 v[48:51], v[160:163], v[178:181], v[48:51]
	v_mfma_f32_16x16x32_bf16 v[40:43], v[168:171], v[178:181], v[40:43]
	v_mfma_f32_16x16x32_bf16 v[36:39], v[160:163], v[186:189], v[36:39]
	v_mfma_f32_16x16x32_bf16 v[32:35], v[168:171], v[186:189], v[32:35]
	v_mfma_f32_16x16x32_bf16 v[16:19], v[160:163], v[198:201], v[16:19]
	v_mfma_f32_16x16x32_bf16 v[8:11], v[168:171], v[198:201], v[8:11]
	v_mfma_f32_16x16x32_bf16 v[4:7], v[160:163], v[206:209], v[4:7]
	v_mfma_f32_16x16x32_bf16 v[0:3], v[168:171], v[206:209], v[0:3]
	v_mfma_f32_16x16x32_bf16 v[48:51], v[164:167], v[182:185], v[48:51]
	v_mfma_f32_16x16x32_bf16 v[40:43], v[172:175], v[182:185], v[40:43]
	v_mfma_f32_16x16x32_bf16 v[36:39], v[164:167], v[194:197], v[36:39]
	v_mfma_f32_16x16x32_bf16 v[32:35], v[172:175], v[194:197], v[32:35]
	v_mfma_f32_16x16x32_bf16 v[16:19], v[164:167], v[202:205], v[16:19]
	v_mfma_f32_16x16x32_bf16 v[8:11], v[172:175], v[202:205], v[8:11]
	v_mfma_f32_16x16x32_bf16 v[4:7], v[164:167], v[210:213], v[4:7]
	v_mfma_f32_16x16x32_bf16 v[0:3], v[172:175], v[210:213], v[0:3]
	s_setprio 0
	s_barrier
; #define PG8_STAGE(bufoff, gbase, voff) do { _Pragma("unroll") for (int _i = 0; _i < 2; ++_i) \
;         __builtin_amdgcn_global_load_lds((const unsigned*)((const char*)(gbase) + (voff)[_i]), (LAS unsigned*)(lds + (bufoff) + ldsw + _i * 8192), 16, 0, 0); } while (0)
; #define PG8_LDA(dst, b, h) do { _Pragma("unroll") for (int m = 0; m < 4; ++m) _Pragma("unroll") for (int k = 0; k < 2; ++k) dst[m][k] = *(const LAS bf16x8*)(lds + PG8_SA(b, h) + aoff + m * 2048 + k * 1024); } while (0)
; #define PG8_LDB(dst, b, h) do { _Pragma("unroll") for (int n = 0; n < 2; ++n) _Pragma("unroll") for (int k = 0; k < 2; ++k) dst[n][k] = *(const LAS bf16x8*)(lds + PG8_SB(b, h) + boff + n * 2048 + k * 1024); } while (0)
; #define PG8_MMA(ai, bj, At, Bt) do { __builtin_amdgcn_s_setprio(1); _Pragma("unroll") for (int m = 0; m < 4; ++m) _Pragma("unroll") for (int n = 0; n < 2; ++n) _Pragma("unroll") for (int k = 0; k < 2; ++k) \
;         acc[ai][bj][m][n] = __builtin_amdgcn_mfma_f32_16x16x32_bf16(Bt[n][k], At[m][k], acc[ai][bj][m][n], 0, 0, 0); __builtin_amdgcn_s_setprio(0); } while (0)
; #define PG8_WAIT_V(n) asm volatile("s_waitcnt vmcnt(" #n ")" ::: "memory")
; #define PG8_WAIT_L(n) asm volatile("s_waitcnt lgkmcnt(" #n ")" ::: "memory")
; #define PG8_BAR __builtin_amdgcn_s_barrier()
; #define PG8_SCHED __builtin_amdgcn_sched_barrier(0)
; template <class Epi>
; __device__ __forceinline__ void gemm_phase(LAS unsigned char* lds, const Gemm g, const Sched& S, const Epi& E, const int tid) {
;     ...
;             PG8_LDB(B0, 1, 0); PG8_LDB(B1, 1, 1); PG8_SCHED; PG8_LDA(At, 1, 0); PG8_STAGE(PG8_SA(0, 1), a2 + hA, voffA);
;             PG8_WAIT_V(8); PG8_WAIT_L(0); PG8_BAR; PG8_MMA(0, 0, At, B0); PG8_MMA(0, 1, At, B1); PG8_BAR; PG8_SCHED;
	s_add_i32 s35, 0, 0x18000
	s_add_i32 s37, 0, 0x1c000
	v_add_u32_e32 v156, s35, v145
	v_add_u32_e32 v172, s37, v145
	ds_read_b128 v[140:143], v156
	ds_read_b128 v[148:151], v156 offset:1024
	ds_read_b128 v[152:155], v156 offset:2048
	ds_read_b128 v[156:159], v156 offset:3072
	ds_read_b128 v[160:163], v172
	ds_read_b128 v[164:167], v172 offset:1024
	ds_read_b128 v[168:171], v172 offset:2048
	ds_read_b128 v[172:175], v172 offset:3072
	s_add_u32 s76, s76, 0x40000
	s_addc_u32 s77, s77, 0
	s_mov_b32 m0, s45
	v_lshl_add_u64 v[224:225], s[76:77], 0, v[128:129]
	ds_read_b128 v[178:181], v147 offset:32768
	ds_read_b128 v[182:185], v147 offset:33792
	ds_read_b128 v[186:189], v147 offset:34816
	ds_read_b128 v[194:197], v147 offset:35840
	ds_read_b128 v[198:201], v147 offset:36864
	ds_read_b128 v[202:205], v147 offset:37888
	ds_read_b128 v[206:209], v147 offset:38912
	ds_read_b128 v[210:213], v147 offset:39936
	global_load_lds_dwordx4 v[224:225], off
	v_lshl_add_u64 v[224:225], s[76:77], 0, v[130:131]
	s_mov_b32 m0, s47
	s_nop 0
	global_load_lds_dwordx4 v[224:225], off
	s_waitcnt vmcnt(8)
	s_waitcnt lgkmcnt(0)
	s_barrier
	s_setprio 1
	s_waitcnt lgkmcnt(0)
	v_mfma_f32_16x16x32_bf16 v[124:127], v[140:143], v[178:181], v[124:127]
	v_mfma_f32_16x16x32_bf16 v[120:123], v[152:155], v[178:181], v[120:123]
	v_mfma_f32_16x16x32_bf16 v[116:119], v[140:143], v[186:189], v[116:119]
	v_mfma_f32_16x16x32_bf16 v[108:111], v[152:155], v[186:189], v[108:111]
	v_mfma_f32_16x16x32_bf16 v[92:95], v[140:143], v[198:201], v[92:95]
	v_mfma_f32_16x16x32_bf16 v[88:91], v[152:155], v[198:201], v[88:91]
	v_mfma_f32_16x16x32_bf16 v[84:87], v[140:143], v[206:209], v[84:87]
	v_mfma_f32_16x16x32_bf16 v[76:79], v[152:155], v[206:209], v[76:79]
	v_mfma_f32_16x16x32_bf16 v[124:127], v[148:151], v[182:185], v[124:127]
	v_mfma_f32_16x16x32_bf16 v[120:123], v[156:159], v[182:185], v[120:123]
	v_mfma_f32_16x16x32_bf16 v[116:119], v[148:151], v[194:197], v[116:119]
	v_mfma_f32_16x16x32_bf16 v[108:111], v[156:159], v[194:197], v[108:111]
	v_mfma_f32_16x16x32_bf16 v[92:95], v[148:151], v[202:205], v[92:95]
	v_mfma_f32_16x16x32_bf16 v[88:91], v[156:159], v[202:205], v[88:91]
	v_mfma_f32_16x16x32_bf16 v[84:87], v[148:151], v[210:213], v[84:87]
	v_mfma_f32_16x16x32_bf16 v[76:79], v[156:159], v[210:213], v[76:79]
	v_mfma_f32_16x16x32_bf16 v[112:115], v[160:163], v[178:181], v[112:115]
	v_mfma_f32_16x16x32_bf16 v[104:107], v[168:171], v[178:181], v[104:107]
	v_mfma_f32_16x16x32_bf16 v[100:103], v[160:163], v[186:189], v[100:103]
	v_mfma_f32_16x16x32_bf16 v[96:99], v[168:171], v[186:189], v[96:99]
	v_mfma_f32_16x16x32_bf16 v[80:83], v[160:163], v[198:201], v[80:83]
	v_mfma_f32_16x16x32_bf16 v[72:75], v[168:171], v[198:201], v[72:75]
	v_mfma_f32_16x16x32_bf16 v[68:71], v[160:163], v[206:209], v[68:71]
	v_mfma_f32_16x16x32_bf16 v[64:67], v[168:171], v[206:209], v[64:67]
	v_mfma_f32_16x16x32_bf16 v[112:115], v[164:167], v[182:185], v[112:115]
	v_mfma_f32_16x16x32_bf16 v[104:107], v[172:175], v[182:185], v[104:107]
	v_mfma_f32_16x16x32_bf16 v[100:103], v[164:167], v[194:197], v[100:103]
	v_mfma_f32_16x16x32_bf16 v[96:99], v[172:175], v[194:197], v[96:99]
	v_mfma_f32_16x16x32_bf16 v[80:83], v[164:167], v[202:205], v[80:83]
	v_mfma_f32_16x16x32_bf16 v[72:75], v[172:175], v[202:205], v[72:75]
	v_mfma_f32_16x16x32_bf16 v[68:71], v[164:167], v[210:213], v[68:71]
	v_mfma_f32_16x16x32_bf16 v[64:67], v[172:175], v[210:213], v[64:67]
	s_setprio 0
	s_barrier
; #define PG8_STAGE(bufoff, gbase, voff) do { _Pragma("unroll") for (int _i = 0; _i < 2; ++_i) \
;         __builtin_amdgcn_global_load_lds((const unsigned*)((const char*)(gbase) + (voff)[_i]), (LAS unsigned*)(lds + (bufoff) + ldsw + _i * 8192), 16, 0, 0); } while (0)
; #define PG8_LDA(dst, b, h) do { _Pragma("unroll") for (int m = 0; m < 4; ++m) _Pragma("unroll") for (int k = 0; k < 2; ++k) dst[m][k] = *(const LAS bf16x8*)(lds + PG8_SA(b, h) + aoff + m * 2048 + k * 1024); } while (0)
; #define PG8_MMA(ai, bj, At, Bt) do { __builtin_amdgcn_s_setprio(1); _Pragma("unroll") for (int m = 0; m < 4; ++m) _Pragma("unroll") for (int n = 0; n < 2; ++n) _Pragma("unroll") for (int k = 0; k < 2; ++k) \
;         acc[ai][bj][m][n] = __builtin_amdgcn_mfma_f32_16x16x32_bf16(Bt[n][k], At[m][k], acc[ai][bj][m][n], 0, 0, 0); __builtin_amdgcn_s_setprio(0); } while (0)
; #define PG8_WAIT_V(n) asm volatile("s_waitcnt vmcnt(" #n ")" ::: "memory")
; #define PG8_WAIT_L(n) asm volatile("s_waitcnt lgkmcnt(" #n ")" ::: "memory")
; #define PG8_BAR __builtin_amdgcn_s_barrier()
; #define PG8_SCHED __builtin_amdgcn_sched_barrier(0)
; template <class Epi>
; __device__ __forceinline__ void gemm_phase(LAS unsigned char* lds, const Gemm g, const Sched& S, const Epi& E, const int tid) {
;     ...
;             PG8_LDA(At, 1, 1); PG8_STAGE(PG8_SB(1, 0), b3, voffB); PG8_STAGE(PG8_SB(1, 1), b3 + hB, voffB); PG8_STAGE(PG8_SA(1, 0), a3, voffA);
;             PG8_WAIT_V(8); PG8_WAIT_L(0); PG8_BAR; PG8_MMA(1, 0, At, B0); PG8_MMA(1, 1, At, B1); PG8_BAR; PG8_SCHED;
;         }
	s_add_i32 s35, s35, s39
	v_lshl_add_u64 v[190:191], v[190:191], 0, s[94:95]
	s_mov_b32 m0, s35
	ds_read_b128 v[178:181], v147 offset:49152
	ds_read_b128 v[182:185], v147 offset:50176
	ds_read_b128 v[186:189], v147 offset:51200
	ds_read_b128 v[194:197], v147 offset:52224
	ds_read_b128 v[198:201], v147 offset:53248
	ds_read_b128 v[202:205], v147 offset:54272
	ds_read_b128 v[206:209], v147 offset:55296
	ds_read_b128 v[210:213], v147 offset:56320
	global_load_lds_dwordx4 v[190:191], off
	s_add_i32 m0, s35, 0x2000
	s_add_u32 s74, s74, 0x40080
	v_lshl_add_u64 v[190:191], v[214:215], 0, s[94:95]
	s_addc_u32 s75, s75, 0
	s_add_i32 s35, s37, s39
	global_load_lds_dwordx4 v[190:191], off
	v_lshl_add_u64 v[190:191], s[74:75], 0, v[192:193]
	s_mov_b32 m0, s35
	s_nop 0
	global_load_lds_dwordx4 v[190:191], off
	v_lshl_add_u64 v[190:191], s[74:75], 0, v[132:133]
	s_add_i32 m0, s35, 0x2000
	s_nop 0
	global_load_lds_dwordx4 v[190:191], off
	v_lshl_add_u64 v[190:191], v[216:217], 0, s[94:95]
	s_mov_b32 m0, s78
	s_nop 0
	global_load_lds_dwordx4 v[190:191], off
	v_lshl_add_u64 v[190:191], v[218:219], 0, s[94:95]
	s_mov_b32 m0, s80
	s_nop 0
	global_load_lds_dwordx4 v[190:191], off
	s_waitcnt vmcnt(8)
	s_waitcnt lgkmcnt(0)
	s_barrier
	s_setprio 1
	s_waitcnt lgkmcnt(0)
	v_mfma_f32_16x16x32_bf16 v[60:63], v[140:143], v[178:181], v[60:63]
	v_mfma_f32_16x16x32_bf16 v[56:59], v[152:155], v[178:181], v[56:59]
	v_mfma_f32_16x16x32_bf16 v[52:55], v[140:143], v[186:189], v[52:55]
	v_mfma_f32_16x16x32_bf16 v[44:47], v[152:155], v[186:189], v[44:47]
	v_mfma_f32_16x16x32_bf16 v[28:31], v[140:143], v[198:201], v[28:31]
	v_mfma_f32_16x16x32_bf16 v[24:27], v[152:155], v[198:201], v[24:27]
	v_mfma_f32_16x16x32_bf16 v[20:23], v[140:143], v[206:209], v[20:23]
	v_mfma_f32_16x16x32_bf16 v[12:15], v[152:155], v[206:209], v[12:15]
	v_mfma_f32_16x16x32_bf16 v[60:63], v[148:151], v[182:185], v[60:63]
	v_mfma_f32_16x16x32_bf16 v[56:59], v[156:159], v[182:185], v[56:59]
	v_mfma_f32_16x16x32_bf16 v[52:55], v[148:151], v[194:197], v[52:55]
	v_mfma_f32_16x16x32_bf16 v[44:47], v[156:159], v[194:197], v[44:47]
	v_mfma_f32_16x16x32_bf16 v[28:31], v[148:151], v[202:205], v[28:31]
	v_mfma_f32_16x16x32_bf16 v[24:27], v[156:159], v[202:205], v[24:27]
	v_mfma_f32_16x16x32_bf16 v[20:23], v[148:151], v[210:213], v[20:23]
	v_mfma_f32_16x16x32_bf16 v[12:15], v[156:159], v[210:213], v[12:15]
	v_mfma_f32_16x16x32_bf16 v[48:51], v[160:163], v[178:181], v[48:51]
	v_mfma_f32_16x16x32_bf16 v[40:43], v[168:171], v[178:181], v[40:43]
	v_mfma_f32_16x16x32_bf16 v[36:39], v[160:163], v[186:189], v[36:39]
	v_mfma_f32_16x16x32_bf16 v[32:35], v[168:171], v[186:189], v[32:35]
	v_mfma_f32_16x16x32_bf16 v[16:19], v[160:163], v[198:201], v[16:19]
	v_mfma_f32_16x16x32_bf16 v[8:11], v[168:171], v[198:201], v[8:11]
	v_mfma_f32_16x16x32_bf16 v[4:7], v[160:163], v[206:209], v[4:7]
	v_mfma_f32_16x16x32_bf16 v[0:3], v[168:171], v[206:209], v[0:3]
	v_mfma_f32_16x16x32_bf16 v[48:51], v[164:167], v[182:185], v[48:51]
	v_mfma_f32_16x16x32_bf16 v[40:43], v[172:175], v[182:185], v[40:43]
	v_mfma_f32_16x16x32_bf16 v[36:39], v[164:167], v[194:197], v[36:39]
	v_mfma_f32_16x16x32_bf16 v[32:35], v[172:175], v[194:197], v[32:35]
	v_mfma_f32_16x16x32_bf16 v[16:19], v[164:167], v[202:205], v[16:19]
	v_mfma_f32_16x16x32_bf16 v[8:11], v[172:175], v[202:205], v[8:11]
	v_mfma_f32_16x16x32_bf16 v[4:7], v[164:167], v[210:213], v[4:7]
	v_mfma_f32_16x16x32_bf16 v[0:3], v[172:175], v[210:213], v[0:3]
	s_setprio 0
	s_barrier
	s_add_i32 s21, s21, 2
	s_add_u32 s10, s10, 0x100
	s_addc_u32 s11, s11, 0
	s_add_u32 s9, s9, 0x100
	s_addc_u32 s19, s19, 0
	s_cmp_gt_u32 s21, 13
	s_cbranch_scc0 .LBB0_333

; #define PG8_STAGE(bufoff, gbase, voff) do { _Pragma("unroll") for (int _i = 0; _i < 2; ++_i) \
;         __builtin_amdgcn_global_load_lds((const unsigned*)((const char*)(gbase) + (voff)[_i]), (LAS unsigned*)(lds + (bufoff) + ldsw + _i * 8192), 16, 0, 0); } while (0)
; #define PG8_LDA(dst, b, h) do { _Pragma("unroll") for (int m = 0; m < 4; ++m) _Pragma("unroll") for (int k = 0; k < 2; ++k) dst[m][k] = *(const LAS bf16x8*)(lds + PG8_SA(b, h) + aoff + m * 2048 + k * 1024); } while (0)
; #define PG8_LDB(dst, b, h) do { _Pragma("unroll") for (int n = 0; n < 2; ++n) _Pragma("unroll") for (int k = 0; k < 2; ++k) dst[n][k] = *(const LAS bf16x8*)(lds + PG8_SB(b, h) + boff + n * 2048 + k * 1024); } while (0)
; #define PG8_MMA(ai, bj, At, Bt) do { __builtin_amdgcn_s_setprio(1); _Pragma("unroll") for (int m = 0; m < 4; ++m) _Pragma("unroll") for (int n = 0; n < 2; ++n) _Pragma("unroll") for (int k = 0; k < 2; ++k) \
;         acc[ai][bj][m][n] = __builtin_amdgcn_mfma_f32_16x16x32_bf16(Bt[n][k], At[m][k], acc[ai][bj][m][n], 0, 0, 0); __builtin_amdgcn_s_setprio(0); } while (0)
; #define PG8_WAIT_V(n) asm volatile("s_waitcnt vmcnt(" #n ")" ::: "memory")
; #define PG8_WAIT_L(n) asm volatile("s_waitcnt lgkmcnt(" #n ")" ::: "memory")
; #define PG8_BAR __builtin_amdgcn_s_barrier()
; #define PG8_SCHED __builtin_amdgcn_sched_barrier(0)
; template <class Epi>
; __device__ __forceinline__ void gemm_phase(LAS unsigned char* lds, const Gemm g, const Sched& S, const Epi& E, const int tid) {
;     ...
;         const bool has_next = S.next(ui + 1, nxt);
;         const char* nA = cA; const char* nB = cB; if (has_next) S.ptrs(nxt, nA, nB);
;         for (int t = 0; t < nt; t += 2) {
;             const bool last = (t == nt - 2);
;             const char* a1 = cA + (size_t)(t + 1) * kstep;
;             const char* a2 = last ? nA : cA + (size_t)(t + 2) * kstep; const char* b2 = last ? nB : cB + (size_t)(t + 2) * kstep;
;             const char* a3 = a2 + kstep; const char* b3 = b2 + kstep;
;             PG8_LDB(B0, 0, 0); PG8_LDB(B1, 0, 1); PG8_SCHED; PG8_LDA(At, 0, 0); PG8_STAGE(PG8_SA(1, 1), a1 + hA, voffA);
;             PG8_WAIT_V(8); PG8_WAIT_L(0); PG8_BAR; PG8_MMA(0, 0, At, B0); PG8_MMA(0, 1, At, B1); PG8_BAR; PG8_SCHED;
;             PG8_LDA(At, 0, 1); PG8_STAGE(PG8_SB(0, 0), b2, voffB); PG8_STAGE(PG8_SB(0, 1), b2 + hB, voffB); PG8_STAGE(PG8_SA(0, 0), a2, voffA);
.LBB0_993:
	s_add_u32 s13, s18, 0x100
	s_addc_u32 s40, s19, 0
	s_mov_b32 s42, -2
	s_add_u32 s18, s16, 0x100
	s_addc_u32 s19, s17, 0
	s_add_i32 s45, 0, 0x10000
	s_cmp_eq_u32 s42, 4
	s_cselect_b32 s23, s7, s19
	s_cselect_b32 s22, s6, s18
	s_cselect_b32 s21, s15, s40
	s_cselect_b32 s20, s14, s13
	s_add_i32 s51, 0, 0x14000
	v_add_u32_e32 v128, s45, v183
	v_add_u32_e32 v156, s51, v183
	ds_read_b128 v[104:107], v128
	ds_read_b128 v[112:115], v128 offset:1024
	ds_read_b128 v[124:127], v128 offset:2048
	ds_read_b128 v[128:131], v128 offset:3072
	ds_read_b128 v[136:139], v156
	ds_read_b128 v[144:147], v156 offset:1024
	ds_read_b128 v[152:155], v156 offset:2048
	ds_read_b128 v[156:159], v156 offset:3072
	v_lshl_add_u64 v[190:191], s[16:17], 0, v[166:167]
	s_add_i32 m0, s73, 0xc000
	ds_read_b128 v[170:173], v185
	ds_read_b128 v[174:177], v185 offset:1024
	ds_read_b128 v[178:181], v185 offset:2048
	ds_read_b128 v[186:189], v185 offset:3072
	ds_read_b128 v[194:197], v185 offset:4096
	ds_read_b128 v[198:201], v185 offset:5120
	ds_read_b128 v[204:207], v185 offset:6144
	ds_read_b128 v[208:211], v185 offset:7168
	global_load_lds_dwordx4 v[190:191], off
	v_lshl_add_u64 v[190:191], s[16:17], 0, v[168:169]
	s_add_i32 m0, s73, 0xe000
	s_nop 0
	global_load_lds_dwordx4 v[190:191], off
	s_waitcnt vmcnt(8)
	s_waitcnt lgkmcnt(0)
	s_barrier
	s_setprio 1
	s_waitcnt lgkmcnt(0)
	v_mfma_f32_16x16x32_bf16 v[148:151], v[104:107], v[170:173], 0
	v_mfma_f32_16x16x32_bf16 v[140:143], v[124:127], v[170:173], 0
	v_mfma_f32_16x16x32_bf16 v[116:119], v[104:107], v[178:181], 0
	v_mfma_f32_16x16x32_bf16 v[108:111], v[124:127], v[178:181], 0
	v_mfma_f32_16x16x32_bf16 v[92:95], v[104:107], v[194:197], 0
	v_mfma_f32_16x16x32_bf16 v[88:91], v[124:127], v[194:197], 0
	v_mfma_f32_16x16x32_bf16 v[76:79], v[104:107], v[204:207], 0
	v_mfma_f32_16x16x32_bf16 v[72:75], v[124:127], v[204:207], 0
	v_mfma_f32_16x16x32_bf16 v[148:151], v[112:115], v[174:177], v[148:151]
	v_mfma_f32_16x16x32_bf16 v[140:143], v[128:131], v[174:177], v[140:143]
	v_mfma_f32_16x16x32_bf16 v[116:119], v[112:115], v[186:189], v[116:119]
	v_mfma_f32_16x16x32_bf16 v[108:111], v[128:131], v[186:189], v[108:111]
	v_mfma_f32_16x16x32_bf16 v[92:95], v[112:115], v[198:201], v[92:95]
	v_mfma_f32_16x16x32_bf16 v[88:91], v[128:131], v[198:201], v[88:91]
	v_mfma_f32_16x16x32_bf16 v[76:79], v[112:115], v[208:211], v[76:79]
	v_mfma_f32_16x16x32_bf16 v[72:75], v[128:131], v[208:211], v[72:75]
	v_mfma_f32_16x16x32_bf16 v[132:135], v[136:139], v[170:173], 0
	v_mfma_f32_16x16x32_bf16 v[120:123], v[152:155], v[170:173], 0
	v_mfma_f32_16x16x32_bf16 v[100:103], v[136:139], v[178:181], 0
	v_mfma_f32_16x16x32_bf16 v[96:99], v[152:155], v[178:181], 0
	v_mfma_f32_16x16x32_bf16 v[84:87], v[136:139], v[194:197], 0
	v_mfma_f32_16x16x32_bf16 v[80:83], v[152:155], v[194:197], 0
	v_mfma_f32_16x16x32_bf16 v[68:71], v[136:139], v[204:207], 0
	v_mfma_f32_16x16x32_bf16 v[64:67], v[152:155], v[204:207], 0
	v_mfma_f32_16x16x32_bf16 v[132:135], v[144:147], v[174:177], v[132:135]
	v_mfma_f32_16x16x32_bf16 v[120:123], v[156:159], v[174:177], v[120:123]
	v_mfma_f32_16x16x32_bf16 v[100:103], v[144:147], v[186:189], v[100:103]
	v_mfma_f32_16x16x32_bf16 v[96:99], v[156:159], v[186:189], v[96:99]
	v_mfma_f32_16x16x32_bf16 v[84:87], v[144:147], v[198:201], v[84:87]
	v_mfma_f32_16x16x32_bf16 v[80:83], v[156:159], v[198:201], v[80:83]
	v_mfma_f32_16x16x32_bf16 v[68:71], v[144:147], v[208:211], v[68:71]
	v_mfma_f32_16x16x32_bf16 v[64:67], v[156:159], v[208:211], v[64:67]
	s_setprio 0
	s_barrier
	s_add_i32 s16, s45, s47
	v_lshl_add_u64 v[190:191], s[20:21], 0, v[192:193]
	s_mov_b32 m0, s16
	ds_read_b128 v[170:173], v185 offset:16384
	ds_read_b128 v[174:177], v185 offset:17408
	ds_read_b128 v[178:181], v185 offset:18432
	ds_read_b128 v[186:189], v185 offset:19456
	ds_read_b128 v[194:197], v185 offset:20480
	ds_read_b128 v[198:201], v185 offset:21504
	ds_read_b128 v[204:207], v185 offset:22528
	ds_read_b128 v[208:211], v185 offset:23552
	global_load_lds_dwordx4 v[190:191], off
	s_add_i32 m0, s16, 0x2000
	s_add_u32 s16, s20, 0x20000
	v_lshl_add_u64 v[212:213], s[20:21], 0, v[164:165]
	s_addc_u32 s17, s21, 0
	s_add_i32 s45, s51, s47
	global_load_lds_dwordx4 v[212:213], off
	v_lshl_add_u64 v[214:215], s[16:17], 0, v[192:193]
	s_mov_b32 m0, s45
	v_lshl_add_u64 v[216:217], s[22:23], 0, v[162:163]
	global_load_lds_dwordx4 v[214:215], off
	v_lshl_add_u64 v[214:215], s[16:17], 0, v[164:165]
	s_add_i32 m0, s45, 0x2000
	s_nop 0
	global_load_lds_dwordx4 v[214:215], off
	v_lshl_add_u64 v[214:215], s[22:23], 0, v[160:161]
	s_mov_b32 m0, s73
	s_nop 0
	global_load_lds_dwordx4 v[214:215], off
	s_mov_b32 m0, s74
	s_nop 0
	global_load_lds_dwordx4 v[216:217], off
	s_waitcnt vmcnt(8)
	s_waitcnt lgkmcnt(0)
	s_barrier
; #define PG8_STAGE(bufoff, gbase, voff) do { _Pragma("unroll") for (int _i = 0; _i < 2; ++_i) \
;         __builtin_amdgcn_global_load_lds((const unsigned*)((const char*)(gbase) + (voff)[_i]), (LAS unsigned*)(lds + (bufoff) + ldsw + _i * 8192), 16, 0, 0); } while (0)
; #define PG8_LDA(dst, b, h) do { _Pragma("unroll") for (int m = 0; m < 4; ++m) _Pragma("unroll") for (int k = 0; k < 2; ++k) dst[m][k] = *(const LAS bf16x8*)(lds + PG8_SA(b, h) + aoff + m * 2048 + k * 1024); } while (0)
; #define PG8_LDB(dst, b, h) do { _Pragma("unroll") for (int n = 0; n < 2; ++n) _Pragma("unroll") for (int k = 0; k < 2; ++k) dst[n][k] = *(const LAS bf16x8*)(lds + PG8_SB(b, h) + boff + n * 2048 + k * 1024); } while (0)
; #define PG8_MMA(ai, bj, At, Bt) do { __builtin_amdgcn_s_setprio(1); _Pragma("unroll") for (int m = 0; m < 4; ++m) _Pragma("unroll") for (int n = 0; n < 2; ++n) _Pragma("unroll") for (int k = 0; k < 2; ++k) \
;         acc[ai][bj][m][n] = __builtin_amdgcn_mfma_f32_16x16x32_bf16(Bt[n][k], At[m][k], acc[ai][bj][m][n], 0, 0, 0); __builtin_amdgcn_s_setprio(0); } while (0)
; #define PG8_WAIT_V(n) asm volatile("s_waitcnt vmcnt(" #n ")" ::: "memory")
; #define PG8_WAIT_L(n) asm volatile("s_waitcnt lgkmcnt(" #n ")" ::: "memory")
; #define PG8_BAR __builtin_amdgcn_s_barrier()
; #define PG8_SCHED __builtin_amdgcn_sched_barrier(0)
; template <class Epi>
; __device__ __forceinline__ void gemm_phase(LAS unsigned char* lds, const Gemm g, const Sched& S, const Epi& E, const int tid) {
;     ...
;             PG8_WAIT_V(8); PG8_WAIT_L(0); PG8_BAR; PG8_MMA(1, 0, At, B0); PG8_MMA(1, 1, At, B1); PG8_BAR; PG8_SCHED;
;             PG8_LDB(B0, 1, 0); PG8_LDB(B1, 1, 1); PG8_SCHED; PG8_LDA(At, 1, 0); PG8_STAGE(PG8_SA(0, 1), a2 + hA, voffA);
;             PG8_WAIT_V(8); PG8_WAIT_L(0); PG8_BAR; PG8_MMA(0, 0, At, B0); PG8_MMA(0, 1, At, B1); PG8_BAR; PG8_SCHED;
	s_setprio 1
	s_waitcnt lgkmcnt(0)
	v_mfma_f32_16x16x32_bf16 v[60:63], v[104:107], v[170:173], 0
	v_mfma_f32_16x16x32_bf16 v[56:59], v[124:127], v[170:173], 0
	v_mfma_f32_16x16x32_bf16 v[44:47], v[104:107], v[178:181], 0
	v_mfma_f32_16x16x32_bf16 v[40:43], v[124:127], v[178:181], 0
	v_mfma_f32_16x16x32_bf16 v[28:31], v[104:107], v[194:197], 0
	v_mfma_f32_16x16x32_bf16 v[24:27], v[124:127], v[194:197], 0
	v_mfma_f32_16x16x32_bf16 v[12:15], v[104:107], v[204:207], 0
	v_mfma_f32_16x16x32_bf16 v[8:11], v[124:127], v[204:207], 0
	v_mfma_f32_16x16x32_bf16 v[60:63], v[112:115], v[174:177], v[60:63]
	v_mfma_f32_16x16x32_bf16 v[56:59], v[128:131], v[174:177], v[56:59]
	v_mfma_f32_16x16x32_bf16 v[44:47], v[112:115], v[186:189], v[44:47]
	v_mfma_f32_16x16x32_bf16 v[40:43], v[128:131], v[186:189], v[40:43]
	v_mfma_f32_16x16x32_bf16 v[28:31], v[112:115], v[198:201], v[28:31]
	v_mfma_f32_16x16x32_bf16 v[24:27], v[128:131], v[198:201], v[24:27]
	v_mfma_f32_16x16x32_bf16 v[12:15], v[112:115], v[208:211], v[12:15]
	v_mfma_f32_16x16x32_bf16 v[8:11], v[128:131], v[208:211], v[8:11]
	v_mfma_f32_16x16x32_bf16 v[52:55], v[136:139], v[170:173], 0
	v_mfma_f32_16x16x32_bf16 v[48:51], v[152:155], v[170:173], 0
	v_mfma_f32_16x16x32_bf16 v[36:39], v[136:139], v[178:181], 0
	v_mfma_f32_16x16x32_bf16 v[32:35], v[152:155], v[178:181], 0
	v_mfma_f32_16x16x32_bf16 v[20:23], v[136:139], v[194:197], 0
	v_mfma_f32_16x16x32_bf16 v[16:19], v[152:155], v[194:197], 0
	v_mfma_f32_16x16x32_bf16 v[4:7], v[136:139], v[204:207], 0
	v_mfma_f32_16x16x32_bf16 v[0:3], v[152:155], v[204:207], 0
	v_mfma_f32_16x16x32_bf16 v[52:55], v[144:147], v[174:177], v[52:55]
	v_mfma_f32_16x16x32_bf16 v[48:51], v[156:159], v[174:177], v[48:51]
	v_mfma_f32_16x16x32_bf16 v[36:39], v[144:147], v[186:189], v[36:39]
	v_mfma_f32_16x16x32_bf16 v[32:35], v[156:159], v[186:189], v[32:35]
	v_mfma_f32_16x16x32_bf16 v[20:23], v[144:147], v[198:201], v[20:23]
	v_mfma_f32_16x16x32_bf16 v[16:19], v[156:159], v[198:201], v[16:19]
	v_mfma_f32_16x16x32_bf16 v[4:7], v[144:147], v[208:211], v[4:7]
	v_mfma_f32_16x16x32_bf16 v[0:3], v[156:159], v[208:211], v[0:3]
	s_setprio 0
	s_barrier
	s_add_i32 s45, 0, 0x18000
	s_add_i32 s51, 0, 0x1c000
	v_add_u32_e32 v128, s45, v183
	v_add_u32_e32 v156, s51, v183
	ds_read_b128 v[104:107], v128
	ds_read_b128 v[112:115], v128 offset:1024
	ds_read_b128 v[124:127], v128 offset:2048
	ds_read_b128 v[128:131], v128 offset:3072
	ds_read_b128 v[136:139], v156
	ds_read_b128 v[144:147], v156 offset:1024
	ds_read_b128 v[152:155], v156 offset:2048
	ds_read_b128 v[156:159], v156 offset:3072
	s_add_u32 s16, s22, 0x120000
	s_addc_u32 s17, s23, 0
	s_mov_b32 m0, s75
	v_lshl_add_u64 v[218:219], s[16:17], 0, v[160:161]
	ds_read_b128 v[170:173], v185 offset:32768
	ds_read_b128 v[174:177], v185 offset:33792
	ds_read_b128 v[178:181], v185 offset:34816
	ds_read_b128 v[186:189], v185 offset:35840
	ds_read_b128 v[194:197], v185 offset:36864
	ds_read_b128 v[198:201], v185 offset:37888
	ds_read_b128 v[204:207], v185 offset:38912
	ds_read_b128 v[208:211], v185 offset:39936
	global_load_lds_dwordx4 v[218:219], off
	v_lshl_add_u64 v[218:219], s[16:17], 0, v[162:163]
	s_mov_b32 m0, s76
	s_nop 0
	global_load_lds_dwordx4 v[218:219], off
	s_waitcnt vmcnt(8)
	s_waitcnt lgkmcnt(0)
	s_barrier
	s_setprio 1
	s_waitcnt lgkmcnt(0)
	v_mfma_f32_16x16x32_bf16 v[148:151], v[104:107], v[170:173], v[148:151]
	v_mfma_f32_16x16x32_bf16 v[140:143], v[124:127], v[170:173], v[140:143]
	v_mfma_f32_16x16x32_bf16 v[116:119], v[104:107], v[178:181], v[116:119]
	v_mfma_f32_16x16x32_bf16 v[108:111], v[124:127], v[178:181], v[108:111]
	v_mfma_f32_16x16x32_bf16 v[92:95], v[104:107], v[194:197], v[92:95]
	v_mfma_f32_16x16x32_bf16 v[88:91], v[124:127], v[194:197], v[88:91]
	v_mfma_f32_16x16x32_bf16 v[76:79], v[104:107], v[204:207], v[76:79]
	v_mfma_f32_16x16x32_bf16 v[72:75], v[124:127], v[204:207], v[72:75]
	v_mfma_f32_16x16x32_bf16 v[148:151], v[112:115], v[174:177], v[148:151]
	v_mfma_f32_16x16x32_bf16 v[140:143], v[128:131], v[174:177], v[140:143]
	v_mfma_f32_16x16x32_bf16 v[116:119], v[112:115], v[186:189], v[116:119]
	v_mfma_f32_16x16x32_bf16 v[108:111], v[128:131], v[186:189], v[108:111]
	v_mfma_f32_16x16x32_bf16 v[92:95], v[112:115], v[198:201], v[92:95]
	v_mfma_f32_16x16x32_bf16 v[88:91], v[128:131], v[198:201], v[88:91]
	v_mfma_f32_16x16x32_bf16 v[76:79], v[112:115], v[208:211], v[76:79]
	v_mfma_f32_16x16x32_bf16 v[72:75], v[128:131], v[208:211], v[72:75]
	v_mfma_f32_16x16x32_bf16 v[132:135], v[136:139], v[170:173], v[132:135]
	v_mfma_f32_16x16x32_bf16 v[120:123], v[152:155], v[170:173], v[120:123]
	v_mfma_f32_16x16x32_bf16 v[100:103], v[136:139], v[178:181], v[100:103]
	v_mfma_f32_16x16x32_bf16 v[96:99], v[152:155], v[178:181], v[96:99]
	v_mfma_f32_16x16x32_bf16 v[84:87], v[136:139], v[194:197], v[84:87]
	v_mfma_f32_16x16x32_bf16 v[80:83], v[152:155], v[194:197], v[80:83]
	v_mfma_f32_16x16x32_bf16 v[68:71], v[136:139], v[204:207], v[68:71]
	v_mfma_f32_16x16x32_bf16 v[64:67], v[152:155], v[204:207], v[64:67]
	v_mfma_f32_16x16x32_bf16 v[132:135], v[144:147], v[174:177], v[132:135]
	v_mfma_f32_16x16x32_bf16 v[120:123], v[156:159], v[174:177], v[120:123]
	v_mfma_f32_16x16x32_bf16 v[100:103], v[144:147], v[186:189], v[100:103]
	v_mfma_f32_16x16x32_bf16 v[96:99], v[156:159], v[186:189], v[96:99]
	v_mfma_f32_16x16x32_bf16 v[84:87], v[144:147], v[198:201], v[84:87]
	v_mfma_f32_16x16x32_bf16 v[80:83], v[156:159], v[198:201], v[80:83]
	v_mfma_f32_16x16x32_bf16 v[68:71], v[144:147], v[208:211], v[68:71]
	v_mfma_f32_16x16x32_bf16 v[64:67], v[156:159], v[208:211], v[64:67]
	s_setprio 0
	s_barrier
; #define PG8_STAGE(bufoff, gbase, voff) do { _Pragma("unroll") for (int _i = 0; _i < 2; ++_i) \
;         __builtin_amdgcn_global_load_lds((const unsigned*)((const char*)(gbase) + (voff)[_i]), (LAS unsigned*)(lds + (bufoff) + ldsw + _i * 8192), 16, 0, 0); } while (0)
; #define PG8_LDA(dst, b, h) do { _Pragma("unroll") for (int m = 0; m < 4; ++m) _Pragma("unroll") for (int k = 0; k < 2; ++k) dst[m][k] = *(const LAS bf16x8*)(lds + PG8_SA(b, h) + aoff + m * 2048 + k * 1024); } while (0)
; #define PG8_LDB(dst, b, h) do { _Pragma("unroll") for (int n = 0; n < 2; ++n) _Pragma("unroll") for (int k = 0; k < 2; ++k) dst[n][k] = *(const LAS bf16x8*)(lds + PG8_SB(b, h) + boff + n * 2048 + k * 1024); } while (0)
; #define PG8_WAIT_V(n) asm volatile("s_waitcnt vmcnt(" #n ")" ::: "memory")
; #define PG8_BAR __builtin_amdgcn_s_barrier()
; template <class Epi>
; __device__ __forceinline__ void gemm_phase(LAS unsigned char* lds, const Gemm g, const Sched& S, const Epi& E, const int tid) {
;     ...
;         for (int t = 0; t < nt; t += 2) {
;             const bool last = (t == nt - 2);
;             const char* a1 = cA + (size_t)(t + 1) * kstep;
;             const char* a2 = last ? nA : cA + (size_t)(t + 2) * kstep; const char* b2 = last ? nB : cB + (size_t)(t + 2) * kstep;
;             const char* a3 = a2 + kstep; const char* b3 = b2 + kstep;
;             PG8_LDB(B0, 0, 0); PG8_LDB(B1, 0, 1); PG8_SCHED; PG8_LDA(At, 0, 0); PG8_STAGE(PG8_SA(1, 1), a1 + hA, voffA);
;             PG8_WAIT_V(8); PG8_WAIT_L(0); PG8_BAR; PG8_MMA(0, 0, At, B0); PG8_MMA(0, 1, At, B1); PG8_BAR; PG8_SCHED;
;             PG8_LDA(At, 0, 1); PG8_STAGE(PG8_SB(0, 0), b2, voffB); PG8_STAGE(PG8_SB(0, 1), b2 + hB, voffB); PG8_STAGE(PG8_SA(0, 0), a2, voffA);
;             PG8_WAIT_V(8); PG8_WAIT_L(0); PG8_BAR; PG8_MMA(1, 0, At, B0); PG8_MMA(1, 1, At, B1); PG8_BAR; PG8_SCHED;
;             PG8_LDB(B0, 1, 0); PG8_LDB(B1, 1, 1); PG8_SCHED; PG8_LDA(At, 1, 0); PG8_STAGE(PG8_SA(0, 1), a2 + hA, voffA);
;             PG8_WAIT_V(8); PG8_WAIT_L(0); PG8_BAR; PG8_MMA(0, 0, At, B0); PG8_MMA(0, 1, At, B1); PG8_BAR; PG8_SCHED;
;             PG8_LDA(At, 1, 1); PG8_STAGE(PG8_SB(1, 0), b3, voffB); PG8_STAGE(PG8_SB(1, 1), b3 + hB, voffB); PG8_STAGE(PG8_SA(1, 0), a3, voffA);
;             PG8_WAIT_V(8); PG8_WAIT_L(0); PG8_BAR; PG8_MMA(1, 0, At, B0); PG8_MMA(1, 1, At, B1); PG8_BAR; PG8_SCHED;
;         }
	s_add_i32 s16, s45, s47
	v_lshl_add_u64 v[190:191], v[190:191], 0, s[94:95]
	s_mov_b32 m0, s16
	ds_read_b128 v[170:173], v185 offset:49152
	ds_read_b128 v[174:177], v185 offset:50176
	ds_read_b128 v[178:181], v185 offset:51200
	ds_read_b128 v[186:189], v185 offset:52224
	ds_read_b128 v[194:197], v185 offset:53248
	ds_read_b128 v[198:201], v185 offset:54272
	ds_read_b128 v[204:207], v185 offset:55296
	ds_read_b128 v[208:211], v185 offset:56320
	global_load_lds_dwordx4 v[190:191], off
	s_add_i32 m0, s16, 0x2000
	s_add_u32 s16, s20, 0x20080
	v_lshl_add_u64 v[190:191], v[212:213], 0, s[94:95]
	s_addc_u32 s17, s21, 0
	s_add_i32 s20, s51, s47
	global_load_lds_dwordx4 v[190:191], off
	v_lshl_add_u64 v[190:191], s[16:17], 0, v[192:193]
	s_mov_b32 m0, s20
	s_nop 0
	global_load_lds_dwordx4 v[190:191], off
	v_lshl_add_u64 v[190:191], s[16:17], 0, v[164:165]
	s_add_i32 m0, s20, 0x2000
	s_nop 0
	global_load_lds_dwordx4 v[190:191], off
	v_lshl_add_u64 v[190:191], v[214:215], 0, s[94:95]
	s_mov_b32 m0, s77
	s_nop 0
	global_load_lds_dwordx4 v[190:191], off
	v_lshl_add_u64 v[190:191], v[216:217], 0, s[94:95]
	s_mov_b32 m0, s78
	s_nop 0
	global_load_lds_dwordx4 v[190:191], off
	s_waitcnt vmcnt(8)
	s_waitcnt lgkmcnt(0)
	s_barrier
	s_setprio 1
	s_waitcnt lgkmcnt(0)
	v_mfma_f32_16x16x32_bf16 v[60:63], v[104:107], v[170:173], v[60:63]
	v_mfma_f32_16x16x32_bf16 v[56:59], v[124:127], v[170:173], v[56:59]
	v_mfma_f32_16x16x32_bf16 v[44:47], v[104:107], v[178:181], v[44:47]
	v_mfma_f32_16x16x32_bf16 v[40:43], v[124:127], v[178:181], v[40:43]
	v_mfma_f32_16x16x32_bf16 v[28:31], v[104:107], v[194:197], v[28:31]
	v_mfma_f32_16x16x32_bf16 v[24:27], v[124:127], v[194:197], v[24:27]
	v_mfma_f32_16x16x32_bf16 v[12:15], v[104:107], v[204:207], v[12:15]
	v_mfma_f32_16x16x32_bf16 v[8:11], v[124:127], v[204:207], v[8:11]
	v_mfma_f32_16x16x32_bf16 v[60:63], v[112:115], v[174:177], v[60:63]
	v_mfma_f32_16x16x32_bf16 v[56:59], v[128:131], v[174:177], v[56:59]
	v_mfma_f32_16x16x32_bf16 v[44:47], v[112:115], v[186:189], v[44:47]
	v_mfma_f32_16x16x32_bf16 v[40:43], v[128:131], v[186:189], v[40:43]
	v_mfma_f32_16x16x32_bf16 v[28:31], v[112:115], v[198:201], v[28:31]
	v_mfma_f32_16x16x32_bf16 v[24:27], v[128:131], v[198:201], v[24:27]
	v_mfma_f32_16x16x32_bf16 v[12:15], v[112:115], v[208:211], v[12:15]
	v_mfma_f32_16x16x32_bf16 v[8:11], v[128:131], v[208:211], v[8:11]
	v_mfma_f32_16x16x32_bf16 v[52:55], v[136:139], v[170:173], v[52:55]
	v_mfma_f32_16x16x32_bf16 v[48:51], v[152:155], v[170:173], v[48:51]
	v_mfma_f32_16x16x32_bf16 v[36:39], v[136:139], v[178:181], v[36:39]
	v_mfma_f32_16x16x32_bf16 v[32:35], v[152:155], v[178:181], v[32:35]
	v_mfma_f32_16x16x32_bf16 v[20:23], v[136:139], v[194:197], v[20:23]
	v_mfma_f32_16x16x32_bf16 v[16:19], v[152:155], v[194:197], v[16:19]
	v_mfma_f32_16x16x32_bf16 v[4:7], v[136:139], v[204:207], v[4:7]
	v_mfma_f32_16x16x32_bf16 v[0:3], v[152:155], v[204:207], v[0:3]
	v_mfma_f32_16x16x32_bf16 v[52:55], v[144:147], v[174:177], v[52:55]
	v_mfma_f32_16x16x32_bf16 v[48:51], v[156:159], v[174:177], v[48:51]
	v_mfma_f32_16x16x32_bf16 v[36:39], v[144:147], v[186:189], v[36:39]
	v_mfma_f32_16x16x32_bf16 v[32:35], v[156:159], v[186:189], v[32:35]
	v_mfma_f32_16x16x32_bf16 v[20:23], v[144:147], v[198:201], v[20:23]
	v_mfma_f32_16x16x32_bf16 v[16:19], v[156:159], v[198:201], v[16:19]
	v_mfma_f32_16x16x32_bf16 v[4:7], v[144:147], v[208:211], v[4:7]
	v_mfma_f32_16x16x32_bf16 v[0:3], v[156:159], v[208:211], v[0:3]
	s_setprio 0
	s_barrier
	s_add_i32 s42, s42, 2
	s_add_u32 s13, s13, 0x100
	s_addc_u32 s40, s40, 0
	s_cmp_gt_u32 s42, 5
	s_mov_b64 s[16:17], s[18:19]
	s_cbranch_scc1 .Lgk_exit_1
.LBB0_994:
	s_add_u32 s18, s16, 0x100
	s_addc_u32 s19, s17, 0
	s_add_i32 s45, 0, 0x10000
	s_cmp_eq_u32 s42, 4
	s_cselect_b32 s23, s7, s19
	s_cselect_b32 s22, s6, s18
	s_cselect_b32 s21, s15, s40
	s_cselect_b32 s20, s14, s13
	s_add_i32 s51, 0, 0x14000
	v_add_u32_e32 v128, s45, v183
	v_add_u32_e32 v156, s51, v183
	ds_read_b128 v[104:107], v128
	ds_read_b128 v[112:115], v128 offset:1024
	ds_read_b128 v[124:127], v128 offset:2048
	ds_read_b128 v[128:131], v128 offset:3072
	ds_read_b128 v[136:139], v156
	ds_read_b128 v[144:147], v156 offset:1024
	ds_read_b128 v[152:155], v156 offset:2048
	ds_read_b128 v[156:159], v156 offset:3072
	v_lshl_add_u64 v[190:191], s[16:17], 0, v[166:167]
	s_add_i32 m0, s73, 0xc000
	ds_read_b128 v[170:173], v185
	ds_read_b128 v[174:177], v185 offset:1024
	ds_read_b128 v[178:181], v185 offset:2048
	ds_read_b128 v[186:189], v185 offset:3072
	ds_read_b128 v[194:197], v185 offset:4096
	ds_read_b128 v[198:201], v185 offset:5120
	ds_read_b128 v[204:207], v185 offset:6144
	ds_read_b128 v[208:211], v185 offset:7168
	global_load_lds_dwordx4 v[190:191], off
	v_lshl_add_u64 v[190:191], s[16:17], 0, v[168:169]
	s_add_i32 m0, s73, 0xe000
	s_nop 0
	global_load_lds_dwordx4 v[190:191], off
	s_waitcnt vmcnt(8)
	s_waitcnt lgkmcnt(0)
	s_barrier
; #define PG8_STAGE(bufoff, gbase, voff) do { _Pragma("unroll") for (int _i = 0; _i < 2; ++_i) \
;         __builtin_amdgcn_global_load_lds((const unsigned*)((const char*)(gbase) + (voff)[_i]), (LAS unsigned*)(lds + (bufoff) + ldsw + _i * 8192), 16, 0, 0); } while (0)
; #define PG8_LDA(dst, b, h) do { _Pragma("unroll") for (int m = 0; m < 4; ++m) _Pragma("unroll") for (int k = 0; k < 2; ++k) dst[m][k] = *(const LAS bf16x8*)(lds + PG8_SA(b, h) + aoff + m * 2048 + k * 1024); } while (0)
; #define PG8_MMA(ai, bj, At, Bt) do { __builtin_amdgcn_s_setprio(1); _Pragma("unroll") for (int m = 0; m < 4; ++m) _Pragma("unroll") for (int n = 0; n < 2; ++n) _Pragma("unroll") for (int k = 0; k < 2; ++k) \
;         acc[ai][bj][m][n] = __builtin_amdgcn_mfma_f32_16x16x32_bf16(Bt[n][k], At[m][k], acc[ai][bj][m][n], 0, 0, 0); __builtin_amdgcn_s_setprio(0); } while (0)
; #define PG8_WAIT_V(n) asm volatile("s_waitcnt vmcnt(" #n ")" ::: "memory")
; #define PG8_WAIT_L(n) asm volatile("s_waitcnt lgkmcnt(" #n ")" ::: "memory")
; #define PG8_BAR __builtin_amdgcn_s_barrier()
; #define PG8_SCHED __builtin_amdgcn_sched_barrier(0)
; template <class Epi>
; __device__ __forceinline__ void gemm_phase(LAS unsigned char* lds, const Gemm g, const Sched& S, const Epi& E, const int tid) {
;     ...
;             PG8_WAIT_V(8); PG8_WAIT_L(0); PG8_BAR; PG8_MMA(0, 0, At, B0); PG8_MMA(0, 1, At, B1); PG8_BAR; PG8_SCHED;
;             PG8_LDA(At, 0, 1); PG8_STAGE(PG8_SB(0, 0), b2, voffB); PG8_STAGE(PG8_SB(0, 1), b2 + hB, voffB); PG8_STAGE(PG8_SA(0, 0), a2, voffA);
;             PG8_WAIT_V(8); PG8_WAIT_L(0); PG8_BAR; PG8_MMA(1, 0, At, B0); PG8_MMA(1, 1, At, B1); PG8_BAR; PG8_SCHED;
	s_setprio 1
	s_waitcnt lgkmcnt(0)
	v_mfma_f32_16x16x32_bf16 v[148:151], v[104:107], v[170:173], v[148:151]
	v_mfma_f32_16x16x32_bf16 v[140:143], v[124:127], v[170:173], v[140:143]
	v_mfma_f32_16x16x32_bf16 v[116:119], v[104:107], v[178:181], v[116:119]
	v_mfma_f32_16x16x32_bf16 v[108:111], v[124:127], v[178:181], v[108:111]
	v_mfma_f32_16x16x32_bf16 v[92:95], v[104:107], v[194:197], v[92:95]
	v_mfma_f32_16x16x32_bf16 v[88:91], v[124:127], v[194:197], v[88:91]
	v_mfma_f32_16x16x32_bf16 v[76:79], v[104:107], v[204:207], v[76:79]
	v_mfma_f32_16x16x32_bf16 v[72:75], v[124:127], v[204:207], v[72:75]
	v_mfma_f32_16x16x32_bf16 v[148:151], v[112:115], v[174:177], v[148:151]
	v_mfma_f32_16x16x32_bf16 v[140:143], v[128:131], v[174:177], v[140:143]
	v_mfma_f32_16x16x32_bf16 v[116:119], v[112:115], v[186:189], v[116:119]
	v_mfma_f32_16x16x32_bf16 v[108:111], v[128:131], v[186:189], v[108:111]
	v_mfma_f32_16x16x32_bf16 v[92:95], v[112:115], v[198:201], v[92:95]
	v_mfma_f32_16x16x32_bf16 v[88:91], v[128:131], v[198:201], v[88:91]
	v_mfma_f32_16x16x32_bf16 v[76:79], v[112:115], v[208:211], v[76:79]
	v_mfma_f32_16x16x32_bf16 v[72:75], v[128:131], v[208:211], v[72:75]
	v_mfma_f32_16x16x32_bf16 v[132:135], v[136:139], v[170:173], v[132:135]
	v_mfma_f32_16x16x32_bf16 v[120:123], v[152:155], v[170:173], v[120:123]
	v_mfma_f32_16x16x32_bf16 v[100:103], v[136:139], v[178:181], v[100:103]
	v_mfma_f32_16x16x32_bf16 v[96:99], v[152:155], v[178:181], v[96:99]
	v_mfma_f32_16x16x32_bf16 v[84:87], v[136:139], v[194:197], v[84:87]
	v_mfma_f32_16x16x32_bf16 v[80:83], v[152:155], v[194:197], v[80:83]
	v_mfma_f32_16x16x32_bf16 v[68:71], v[136:139], v[204:207], v[68:71]
	v_mfma_f32_16x16x32_bf16 v[64:67], v[152:155], v[204:207], v[64:67]
	v_mfma_f32_16x16x32_bf16 v[132:135], v[144:147], v[174:177], v[132:135]
	v_mfma_f32_16x16x32_bf16 v[120:123], v[156:159], v[174:177], v[120:123]
	v_mfma_f32_16x16x32_bf16 v[100:103], v[144:147], v[186:189], v[100:103]
	v_mfma_f32_16x16x32_bf16 v[96:99], v[156:159], v[186:189], v[96:99]
	v_mfma_f32_16x16x32_bf16 v[84:87], v[144:147], v[198:201], v[84:87]
	v_mfma_f32_16x16x32_bf16 v[80:83], v[156:159], v[198:201], v[80:83]
	v_mfma_f32_16x16x32_bf16 v[68:71], v[144:147], v[208:211], v[68:71]
	v_mfma_f32_16x16x32_bf16 v[64:67], v[156:159], v[208:211], v[64:67]
	s_setprio 0
	s_barrier
	s_add_i32 s16, s45, s47
	v_lshl_add_u64 v[190:191], s[20:21], 0, v[192:193]
	s_mov_b32 m0, s16
	ds_read_b128 v[170:173], v185 offset:16384
	ds_read_b128 v[174:177], v185 offset:17408
	ds_read_b128 v[178:181], v185 offset:18432
	ds_read_b128 v[186:189], v185 offset:19456
	ds_read_b128 v[194:197], v185 offset:20480
	ds_read_b128 v[198:201], v185 offset:21504
	ds_read_b128 v[204:207], v185 offset:22528
	ds_read_b128 v[208:211], v185 offset:23552
	global_load_lds_dwordx4 v[190:191], off
	s_add_i32 m0, s16, 0x2000
	s_add_u32 s16, s20, 0x20000
	v_lshl_add_u64 v[212:213], s[20:21], 0, v[164:165]
	s_addc_u32 s17, s21, 0
	s_add_i32 s45, s51, s47
	global_load_lds_dwordx4 v[212:213], off
	v_lshl_add_u64 v[214:215], s[16:17], 0, v[192:193]
	s_mov_b32 m0, s45
	v_lshl_add_u64 v[216:217], s[22:23], 0, v[162:163]
	global_load_lds_dwordx4 v[214:215], off
	v_lshl_add_u64 v[214:215], s[16:17], 0, v[164:165]
	s_add_i32 m0, s45, 0x2000
	s_nop 0
	global_load_lds_dwordx4 v[214:215], off
	v_lshl_add_u64 v[214:215], s[22:23], 0, v[160:161]
	s_mov_b32 m0, s73
	s_nop 0
	global_load_lds_dwordx4 v[214:215], off
	s_mov_b32 m0, s74
	s_nop 0
	global_load_lds_dwordx4 v[216:217], off
	s_waitcnt vmcnt(8)
	s_waitcnt lgkmcnt(0)
	s_barrier
	s_setprio 1
	s_waitcnt lgkmcnt(0)
	v_mfma_f32_16x16x32_bf16 v[60:63], v[104:107], v[170:173], v[60:63]
	v_mfma_f32_16x16x32_bf16 v[56:59], v[124:127], v[170:173], v[56:59]
	v_mfma_f32_16x16x32_bf16 v[44:47], v[104:107], v[178:181], v[44:47]
	v_mfma_f32_16x16x32_bf16 v[40:43], v[124:127], v[178:181], v[40:43]
	v_mfma_f32_16x16x32_bf16 v[28:31], v[104:107], v[194:197], v[28:31]
	v_mfma_f32_16x16x32_bf16 v[24:27], v[124:127], v[194:197], v[24:27]
	v_mfma_f32_16x16x32_bf16 v[12:15], v[104:107], v[204:207], v[12:15]
	v_mfma_f32_16x16x32_bf16 v[8:11], v[124:127], v[204:207], v[8:11]
	v_mfma_f32_16x16x32_bf16 v[60:63], v[112:115], v[174:177], v[60:63]
	v_mfma_f32_16x16x32_bf16 v[56:59], v[128:131], v[174:177], v[56:59]
	v_mfma_f32_16x16x32_bf16 v[44:47], v[112:115], v[186:189], v[44:47]
	v_mfma_f32_16x16x32_bf16 v[40:43], v[128:131], v[186:189], v[40:43]
	v_mfma_f32_16x16x32_bf16 v[28:31], v[112:115], v[198:201], v[28:31]
	v_mfma_f32_16x16x32_bf16 v[24:27], v[128:131], v[198:201], v[24:27]
	v_mfma_f32_16x16x32_bf16 v[12:15], v[112:115], v[208:211], v[12:15]
	v_mfma_f32_16x16x32_bf16 v[8:11], v[128:131], v[208:211], v[8:11]
	v_mfma_f32_16x16x32_bf16 v[52:55], v[136:139], v[170:173], v[52:55]
	v_mfma_f32_16x16x32_bf16 v[48:51], v[152:155], v[170:173], v[48:51]
	v_mfma_f32_16x16x32_bf16 v[36:39], v[136:139], v[178:181], v[36:39]
	v_mfma_f32_16x16x32_bf16 v[32:35], v[152:155], v[178:181], v[32:35]
	v_mfma_f32_16x16x32_bf16 v[20:23], v[136:139], v[194:197], v[20:23]
	v_mfma_f32_16x16x32_bf16 v[16:19], v[152:155], v[194:197], v[16:19]
	v_mfma_f32_16x16x32_bf16 v[4:7], v[136:139], v[204:207], v[4:7]
	v_mfma_f32_16x16x32_bf16 v[0:3], v[152:155], v[204:207], v[0:3]
	v_mfma_f32_16x16x32_bf16 v[52:55], v[144:147], v[174:177], v[52:55]
	v_mfma_f32_16x16x32_bf16 v[48:51], v[156:159], v[174:177], v[48:51]
	v_mfma_f32_16x16x32_bf16 v[36:39], v[144:147], v[186:189], v[36:39]
	v_mfma_f32_16x16x32_bf16 v[32:35], v[156:159], v[186:189], v[32:35]
	v_mfma_f32_16x16x32_bf16 v[20:23], v[144:147], v[198:201], v[20:23]
	v_mfma_f32_16x16x32_bf16 v[16:19], v[156:159], v[198:201], v[16:19]
	v_mfma_f32_16x16x32_bf16 v[4:7], v[144:147], v[208:211], v[4:7]
	v_mfma_f32_16x16x32_bf16 v[0:3], v[156:159], v[208:211], v[0:3]
	s_setprio 0
	s_barrier
; #define PG8_STAGE(bufoff, gbase, voff) do { _Pragma("unroll") for (int _i = 0; _i < 2; ++_i) \
;         __builtin_amdgcn_global_load_lds((const unsigned*)((const char*)(gbase) + (voff)[_i]), (LAS unsigned*)(lds + (bufoff) + ldsw + _i * 8192), 16, 0, 0); } while (0)
; #define PG8_LDA(dst, b, h) do { _Pragma("unroll") for (int m = 0; m < 4; ++m) _Pragma("unroll") for (int k = 0; k < 2; ++k) dst[m][k] = *(const LAS bf16x8*)(lds + PG8_SA(b, h) + aoff + m * 2048 + k * 1024); } while (0)
; #define PG8_LDB(dst, b, h) do { _Pragma("unroll") for (int n = 0; n < 2; ++n) _Pragma("unroll") for (int k = 0; k < 2; ++k) dst[n][k] = *(const LAS bf16x8*)(lds + PG8_SB(b, h) + boff + n * 2048 + k * 1024); } while (0)
; #define PG8_MMA(ai, bj, At, Bt) do { __builtin_amdgcn_s_setprio(1); _Pragma("unroll") for (int m = 0; m < 4; ++m) _Pragma("unroll") for (int n = 0; n < 2; ++n) _Pragma("unroll") for (int k = 0; k < 2; ++k) \
;         acc[ai][bj][m][n] = __builtin_amdgcn_mfma_f32_16x16x32_bf16(Bt[n][k], At[m][k], acc[ai][bj][m][n], 0, 0, 0); __builtin_amdgcn_s_setprio(0); } while (0)
; #define PG8_WAIT_V(n) asm volatile("s_waitcnt vmcnt(" #n ")" ::: "memory")
; #define PG8_WAIT_L(n) asm volatile("s_waitcnt lgkmcnt(" #n ")" ::: "memory")
; #define PG8_BAR __builtin_amdgcn_s_barrier()
; #define PG8_SCHED __builtin_amdgcn_sched_barrier(0)
; template <class Epi>
; __device__ __forceinline__ void gemm_phase(LAS unsigned char* lds, const Gemm g, const Sched& S, const Epi& E, const int tid) {
;     ...
;             PG8_LDB(B0, 1, 0); PG8_LDB(B1, 1, 1); PG8_SCHED; PG8_LDA(At, 1, 0); PG8_STAGE(PG8_SA(0, 1), a2 + hA, voffA);
;             PG8_WAIT_V(8); PG8_WAIT_L(0); PG8_BAR; PG8_MMA(0, 0, At, B0); PG8_MMA(0, 1, At, B1); PG8_BAR; PG8_SCHED;
	s_add_i32 s45, 0, 0x18000
	s_add_i32 s51, 0, 0x1c000
	v_add_u32_e32 v128, s45, v183
	v_add_u32_e32 v156, s51, v183
	ds_read_b128 v[104:107], v128
	ds_read_b128 v[112:115], v128 offset:1024
	ds_read_b128 v[124:127], v128 offset:2048
	ds_read_b128 v[128:131], v128 offset:3072
	ds_read_b128 v[136:139], v156
	ds_read_b128 v[144:147], v156 offset:1024
	ds_read_b128 v[152:155], v156 offset:2048
	ds_read_b128 v[156:159], v156 offset:3072
	s_add_u32 s16, s22, 0x120000
	s_addc_u32 s17, s23, 0
	s_mov_b32 m0, s75
	v_lshl_add_u64 v[218:219], s[16:17], 0, v[160:161]
	ds_read_b128 v[170:173], v185 offset:32768
	ds_read_b128 v[174:177], v185 offset:33792
	ds_read_b128 v[178:181], v185 offset:34816
	ds_read_b128 v[186:189], v185 offset:35840
	ds_read_b128 v[194:197], v185 offset:36864
	ds_read_b128 v[198:201], v185 offset:37888
	ds_read_b128 v[204:207], v185 offset:38912
	ds_read_b128 v[208:211], v185 offset:39936
	global_load_lds_dwordx4 v[218:219], off
	v_lshl_add_u64 v[218:219], s[16:17], 0, v[162:163]
	s_mov_b32 m0, s76
	s_nop 0
	global_load_lds_dwordx4 v[218:219], off
	s_waitcnt vmcnt(8)
	s_waitcnt lgkmcnt(0)
	s_barrier
	s_setprio 1
	s_waitcnt lgkmcnt(0)
	v_mfma_f32_16x16x32_bf16 v[148:151], v[104:107], v[170:173], v[148:151]
	v_mfma_f32_16x16x32_bf16 v[140:143], v[124:127], v[170:173], v[140:143]
	v_mfma_f32_16x16x32_bf16 v[116:119], v[104:107], v[178:181], v[116:119]
	v_mfma_f32_16x16x32_bf16 v[108:111], v[124:127], v[178:181], v[108:111]
	v_mfma_f32_16x16x32_bf16 v[92:95], v[104:107], v[194:197], v[92:95]
	v_mfma_f32_16x16x32_bf16 v[88:91], v[124:127], v[194:197], v[88:91]
	v_mfma_f32_16x16x32_bf16 v[76:79], v[104:107], v[204:207], v[76:79]
	v_mfma_f32_16x16x32_bf16 v[72:75], v[124:127], v[204:207], v[72:75]
	v_mfma_f32_16x16x32_bf16 v[148:151], v[112:115], v[174:177], v[148:151]
	v_mfma_f32_16x16x32_bf16 v[140:143], v[128:131], v[174:177], v[140:143]
	v_mfma_f32_16x16x32_bf16 v[116:119], v[112:115], v[186:189], v[116:119]
	v_mfma_f32_16x16x32_bf16 v[108:111], v[128:131], v[186:189], v[108:111]
	v_mfma_f32_16x16x32_bf16 v[92:95], v[112:115], v[198:201], v[92:95]
	v_mfma_f32_16x16x32_bf16 v[88:91], v[128:131], v[198:201], v[88:91]
	v_mfma_f32_16x16x32_bf16 v[76:79], v[112:115], v[208:211], v[76:79]
	v_mfma_f32_16x16x32_bf16 v[72:75], v[128:131], v[208:211], v[72:75]
	v_mfma_f32_16x16x32_bf16 v[132:135], v[136:139], v[170:173], v[132:135]
	v_mfma_f32_16x16x32_bf16 v[120:123], v[152:155], v[170:173], v[120:123]
	v_mfma_f32_16x16x32_bf16 v[100:103], v[136:139], v[178:181], v[100:103]
	v_mfma_f32_16x16x32_bf16 v[96:99], v[152:155], v[178:181], v[96:99]
	v_mfma_f32_16x16x32_bf16 v[84:87], v[136:139], v[194:197], v[84:87]
	v_mfma_f32_16x16x32_bf16 v[80:83], v[152:155], v[194:197], v[80:83]
	v_mfma_f32_16x16x32_bf16 v[68:71], v[136:139], v[204:207], v[68:71]
	v_mfma_f32_16x16x32_bf16 v[64:67], v[152:155], v[204:207], v[64:67]
	v_mfma_f32_16x16x32_bf16 v[132:135], v[144:147], v[174:177], v[132:135]
	v_mfma_f32_16x16x32_bf16 v[120:123], v[156:159], v[174:177], v[120:123]
	v_mfma_f32_16x16x32_bf16 v[100:103], v[144:147], v[186:189], v[100:103]
	v_mfma_f32_16x16x32_bf16 v[96:99], v[156:159], v[186:189], v[96:99]
	v_mfma_f32_16x16x32_bf16 v[84:87], v[144:147], v[198:201], v[84:87]
	v_mfma_f32_16x16x32_bf16 v[80:83], v[156:159], v[198:201], v[80:83]
	v_mfma_f32_16x16x32_bf16 v[68:71], v[144:147], v[208:211], v[68:71]
	v_mfma_f32_16x16x32_bf16 v[64:67], v[156:159], v[208:211], v[64:67]
	s_setprio 0
	s_barrier
; #define PG8_STAGE(bufoff, gbase, voff) do { _Pragma("unroll") for (int _i = 0; _i < 2; ++_i) \
;         __builtin_amdgcn_global_load_lds((const unsigned*)((const char*)(gbase) + (voff)[_i]), (LAS unsigned*)(lds + (bufoff) + ldsw + _i * 8192), 16, 0, 0); } while (0)
; #define PG8_LDA(dst, b, h) do { _Pragma("unroll") for (int m = 0; m < 4; ++m) _Pragma("unroll") for (int k = 0; k < 2; ++k) dst[m][k] = *(const LAS bf16x8*)(lds + PG8_SA(b, h) + aoff + m * 2048 + k * 1024); } while (0)
; #define PG8_MMA(ai, bj, At, Bt) do { __builtin_amdgcn_s_setprio(1); _Pragma("unroll") for (int m = 0; m < 4; ++m) _Pragma("unroll") for (int n = 0; n < 2; ++n) _Pragma("unroll") for (int k = 0; k < 2; ++k) \
;         acc[ai][bj][m][n] = __builtin_amdgcn_mfma_f32_16x16x32_bf16(Bt[n][k], At[m][k], acc[ai][bj][m][n], 0, 0, 0); __builtin_amdgcn_s_setprio(0); } while (0)
; #define PG8_WAIT_V(n) asm volatile("s_waitcnt vmcnt(" #n ")" ::: "memory")
; #define PG8_WAIT_L(n) asm volatile("s_waitcnt lgkmcnt(" #n ")" ::: "memory")
; #define PG8_BAR __builtin_amdgcn_s_barrier()
; #define PG8_SCHED __builtin_amdgcn_sched_barrier(0)
; template <class Epi>
; __device__ __forceinline__ void gemm_phase(LAS unsigned char* lds, const Gemm g, const Sched& S, const Epi& E, const int tid) {
;     ...
;             PG8_LDA(At, 1, 1); PG8_STAGE(PG8_SB(1, 0), b3, voffB); PG8_STAGE(PG8_SB(1, 1), b3 + hB, voffB); PG8_STAGE(PG8_SA(1, 0), a3, voffA);
;             PG8_WAIT_V(8); PG8_WAIT_L(0); PG8_BAR; PG8_MMA(1, 0, At, B0); PG8_MMA(1, 1, At, B1); PG8_BAR; PG8_SCHED;
;         }
	s_add_i32 s16, s45, s47
	v_lshl_add_u64 v[190:191], v[190:191], 0, s[94:95]
	s_mov_b32 m0, s16
	ds_read_b128 v[170:173], v185 offset:49152
	ds_read_b128 v[174:177], v185 offset:50176
	ds_read_b128 v[178:181], v185 offset:51200
	ds_read_b128 v[186:189], v185 offset:52224
	ds_read_b128 v[194:197], v185 offset:53248
	ds_read_b128 v[198:201], v185 offset:54272
	ds_read_b128 v[204:207], v185 offset:55296
	ds_read_b128 v[208:211], v185 offset:56320
	global_load_lds_dwordx4 v[190:191], off
	s_add_i32 m0, s16, 0x2000
	s_add_u32 s16, s20, 0x20080
	v_lshl_add_u64 v[190:191], v[212:213], 0, s[94:95]
	s_addc_u32 s17, s21, 0
	s_add_i32 s20, s51, s47
	global_load_lds_dwordx4 v[190:191], off
	v_lshl_add_u64 v[190:191], s[16:17], 0, v[192:193]
	s_mov_b32 m0, s20
	s_nop 0
	global_load_lds_dwordx4 v[190:191], off
	v_lshl_add_u64 v[190:191], s[16:17], 0, v[164:165]
	s_add_i32 m0, s20, 0x2000
	s_nop 0
	global_load_lds_dwordx4 v[190:191], off
	v_lshl_add_u64 v[190:191], v[214:215], 0, s[94:95]
	s_mov_b32 m0, s77
	s_nop 0
	global_load_lds_dwordx4 v[190:191], off
	v_lshl_add_u64 v[190:191], v[216:217], 0, s[94:95]
	s_mov_b32 m0, s78
	s_nop 0
	global_load_lds_dwordx4 v[190:191], off
	s_waitcnt vmcnt(8)
	s_waitcnt lgkmcnt(0)
	s_barrier
	s_setprio 1
	s_waitcnt lgkmcnt(0)
	v_mfma_f32_16x16x32_bf16 v[60:63], v[104:107], v[170:173], v[60:63]
	v_mfma_f32_16x16x32_bf16 v[56:59], v[124:127], v[170:173], v[56:59]
	v_mfma_f32_16x16x32_bf16 v[44:47], v[104:107], v[178:181], v[44:47]
	v_mfma_f32_16x16x32_bf16 v[40:43], v[124:127], v[178:181], v[40:43]
	v_mfma_f32_16x16x32_bf16 v[28:31], v[104:107], v[194:197], v[28:31]
	v_mfma_f32_16x16x32_bf16 v[24:27], v[124:127], v[194:197], v[24:27]
	v_mfma_f32_16x16x32_bf16 v[12:15], v[104:107], v[204:207], v[12:15]
	v_mfma_f32_16x16x32_bf16 v[8:11], v[124:127], v[204:207], v[8:11]
	v_mfma_f32_16x16x32_bf16 v[60:63], v[112:115], v[174:177], v[60:63]
	v_mfma_f32_16x16x32_bf16 v[56:59], v[128:131], v[174:177], v[56:59]
	v_mfma_f32_16x16x32_bf16 v[44:47], v[112:115], v[186:189], v[44:47]
	v_mfma_f32_16x16x32_bf16 v[40:43], v[128:131], v[186:189], v[40:43]
	v_mfma_f32_16x16x32_bf16 v[28:31], v[112:115], v[198:201], v[28:31]
	v_mfma_f32_16x16x32_bf16 v[24:27], v[128:131], v[198:201], v[24:27]
	v_mfma_f32_16x16x32_bf16 v[12:15], v[112:115], v[208:211], v[12:15]
	v_mfma_f32_16x16x32_bf16 v[8:11], v[128:131], v[208:211], v[8:11]
	v_mfma_f32_16x16x32_bf16 v[52:55], v[136:139], v[170:173], v[52:55]
	v_mfma_f32_16x16x32_bf16 v[48:51], v[152:155], v[170:173], v[48:51]
	v_mfma_f32_16x16x32_bf16 v[36:39], v[136:139], v[178:181], v[36:39]
	v_mfma_f32_16x16x32_bf16 v[32:35], v[152:155], v[178:181], v[32:35]
	v_mfma_f32_16x16x32_bf16 v[20:23], v[136:139], v[194:197], v[20:23]
	v_mfma_f32_16x16x32_bf16 v[16:19], v[152:155], v[194:197], v[16:19]
	v_mfma_f32_16x16x32_bf16 v[4:7], v[136:139], v[204:207], v[4:7]
	v_mfma_f32_16x16x32_bf16 v[0:3], v[152:155], v[204:207], v[0:3]
	v_mfma_f32_16x16x32_bf16 v[52:55], v[144:147], v[174:177], v[52:55]
	v_mfma_f32_16x16x32_bf16 v[48:51], v[156:159], v[174:177], v[48:51]
	v_mfma_f32_16x16x32_bf16 v[36:39], v[144:147], v[186:189], v[36:39]
	v_mfma_f32_16x16x32_bf16 v[32:35], v[156:159], v[186:189], v[32:35]
	v_mfma_f32_16x16x32_bf16 v[20:23], v[144:147], v[198:201], v[20:23]
	v_mfma_f32_16x16x32_bf16 v[16:19], v[156:159], v[198:201], v[16:19]
	v_mfma_f32_16x16x32_bf16 v[4:7], v[144:147], v[208:211], v[4:7]
	v_mfma_f32_16x16x32_bf16 v[0:3], v[156:159], v[208:211], v[0:3]
	s_setprio 0
	s_barrier
	s_add_i32 s42, s42, 2
	s_add_u32 s13, s13, 0x100
	s_addc_u32 s40, s40, 0
	s_cmp_gt_u32 s42, 5
	s_mov_b64 s[16:17], s[18:19]
	s_cbranch_scc0 .LBB0_994

; #define PG8_STAGE(bufoff, gbase, voff) do { _Pragma("unroll") for (int _i = 0; _i < 2; ++_i) \
;         __builtin_amdgcn_global_load_lds((const unsigned*)((const char*)(gbase) + (voff)[_i]), (LAS unsigned*)(lds + (bufoff) + ldsw + _i * 8192), 16, 0, 0); } while (0)
; #define PG8_LDA(dst, b, h) do { _Pragma("unroll") for (int m = 0; m < 4; ++m) _Pragma("unroll") for (int k = 0; k < 2; ++k) dst[m][k] = *(const LAS bf16x8*)(lds + PG8_SA(b, h) + aoff + m * 2048 + k * 1024); } while (0)
; #define PG8_LDB(dst, b, h) do { _Pragma("unroll") for (int n = 0; n < 2; ++n) _Pragma("unroll") for (int k = 0; k < 2; ++k) dst[n][k] = *(const LAS bf16x8*)(lds + PG8_SB(b, h) + boff + n * 2048 + k * 1024); } while (0)
; #define PG8_MMA(ai, bj, At, Bt) do { __builtin_amdgcn_s_setprio(1); _Pragma("unroll") for (int m = 0; m < 4; ++m) _Pragma("unroll") for (int n = 0; n < 2; ++n) _Pragma("unroll") for (int k = 0; k < 2; ++k) \
;         acc[ai][bj][m][n] = __builtin_amdgcn_mfma_f32_16x16x32_bf16(Bt[n][k], At[m][k], acc[ai][bj][m][n], 0, 0, 0); __builtin_amdgcn_s_setprio(0); } while (0)
; #define PG8_WAIT_V(n) asm volatile("s_waitcnt vmcnt(" #n ")" ::: "memory")
; #define PG8_WAIT_L(n) asm volatile("s_waitcnt lgkmcnt(" #n ")" ::: "memory")
; #define PG8_BAR __builtin_amdgcn_s_barrier()
; #define PG8_SCHED __builtin_amdgcn_sched_barrier(0)
; template <class Epi>
; __device__ __forceinline__ void gemm_phase(LAS unsigned char* lds, const Gemm g, const Sched& S, const Epi& E, const int tid) {
;     ...
;         const bool has_next = S.next(ui + 1, nxt);
;         const char* nA = cA; const char* nB = cB; if (has_next) S.ptrs(nxt, nA, nB);
;         for (int t = 0; t < nt; t += 2) {
;             const bool last = (t == nt - 2);
;             const char* a1 = cA + (size_t)(t + 1) * kstep;
;             const char* a2 = last ? nA : cA + (size_t)(t + 2) * kstep; const char* b2 = last ? nB : cB + (size_t)(t + 2) * kstep;
;             const char* a3 = a2 + kstep; const char* b3 = b2 + kstep;
;             PG8_LDB(B0, 0, 0); PG8_LDB(B1, 0, 1); PG8_SCHED; PG8_LDA(At, 0, 0); PG8_STAGE(PG8_SA(1, 1), a1 + hA, voffA);
;             PG8_WAIT_V(8); PG8_WAIT_L(0); PG8_BAR; PG8_MMA(0, 0, At, B0); PG8_MMA(0, 1, At, B1); PG8_BAR; PG8_SCHED;
;             PG8_LDA(At, 0, 1); PG8_STAGE(PG8_SB(0, 0), b2, voffB); PG8_STAGE(PG8_SB(0, 1), b2 + hB, voffB); PG8_STAGE(PG8_SA(0, 0), a2, voffA);
.LBB0_1028:
	s_add_u32 s13, s22, 0x100
	s_addc_u32 s37, s23, 0
	s_mov_b32 s40, -2
	s_add_u32 s6, s20, 0x100
	s_addc_u32 s7, s21, 0
	s_add_i32 s42, 0, 0x10000
	s_cmp_eq_u32 s40, 4
	s_cselect_b32 s73, s15, s7
	s_cselect_b32 s72, s14, s6
	s_cselect_b32 s23, s17, s37
	s_cselect_b32 s22, s16, s13
	s_add_i32 s45, 0, 0x14000
	v_add_u32_e32 v128, s42, v241
	v_add_u32_e32 v156, s45, v241
	ds_read_b128 v[104:107], v128
	ds_read_b128 v[112:115], v128 offset:1024
	ds_read_b128 v[120:123], v128 offset:2048
	ds_read_b128 v[128:131], v128 offset:3072
	ds_read_b128 v[136:139], v156
	ds_read_b128 v[140:143], v156 offset:1024
	ds_read_b128 v[148:151], v156 offset:2048
	ds_read_b128 v[156:159], v156 offset:3072
	v_lshl_add_u64 v[194:195], s[20:21], 0, v[210:211]
	s_add_i32 m0, s19, 0xc000
	ds_read_b128 v[160:163], v243
	ds_read_b128 v[164:167], v243 offset:1024
	ds_read_b128 v[168:171], v243 offset:2048
	ds_read_b128 v[172:175], v243 offset:3072
	ds_read_b128 v[176:179], v243 offset:4096
	ds_read_b128 v[180:183], v243 offset:5120
	ds_read_b128 v[184:187], v243 offset:6144
	ds_read_b128 v[188:191], v243 offset:7168
	global_load_lds_dwordx4 v[194:195], off
	v_lshl_add_u64 v[194:195], s[20:21], 0, v[212:213]
	s_add_i32 m0, s19, 0xe000
	s_nop 0
	global_load_lds_dwordx4 v[194:195], off
	s_waitcnt vmcnt(8)
	s_waitcnt lgkmcnt(0)
	s_barrier
	s_setprio 1
	s_waitcnt lgkmcnt(0)
	v_mfma_f32_16x16x32_bf16 v[152:155], v[104:107], v[160:163], 0
	v_mfma_f32_16x16x32_bf16 v[144:147], v[120:123], v[160:163], 0
	v_mfma_f32_16x16x32_bf16 v[116:119], v[104:107], v[168:171], 0
	v_mfma_f32_16x16x32_bf16 v[108:111], v[120:123], v[168:171], 0
	v_mfma_f32_16x16x32_bf16 v[92:95], v[104:107], v[176:179], 0
	v_mfma_f32_16x16x32_bf16 v[88:91], v[120:123], v[176:179], 0
	v_mfma_f32_16x16x32_bf16 v[76:79], v[104:107], v[184:187], 0
	v_mfma_f32_16x16x32_bf16 v[72:75], v[120:123], v[184:187], 0
	v_mfma_f32_16x16x32_bf16 v[152:155], v[112:115], v[164:167], v[152:155]
	v_mfma_f32_16x16x32_bf16 v[144:147], v[128:131], v[164:167], v[144:147]
	v_mfma_f32_16x16x32_bf16 v[116:119], v[112:115], v[172:175], v[116:119]
	v_mfma_f32_16x16x32_bf16 v[108:111], v[128:131], v[172:175], v[108:111]
	v_mfma_f32_16x16x32_bf16 v[92:95], v[112:115], v[180:183], v[92:95]
	v_mfma_f32_16x16x32_bf16 v[88:91], v[128:131], v[180:183], v[88:91]
	v_mfma_f32_16x16x32_bf16 v[76:79], v[112:115], v[188:191], v[76:79]
	v_mfma_f32_16x16x32_bf16 v[72:75], v[128:131], v[188:191], v[72:75]
	v_mfma_f32_16x16x32_bf16 v[132:135], v[136:139], v[160:163], 0
	v_mfma_f32_16x16x32_bf16 v[124:127], v[148:151], v[160:163], 0
	v_mfma_f32_16x16x32_bf16 v[100:103], v[136:139], v[168:171], 0
	v_mfma_f32_16x16x32_bf16 v[96:99], v[148:151], v[168:171], 0
	v_mfma_f32_16x16x32_bf16 v[84:87], v[136:139], v[176:179], 0
	v_mfma_f32_16x16x32_bf16 v[80:83], v[148:151], v[176:179], 0
	v_mfma_f32_16x16x32_bf16 v[68:71], v[136:139], v[184:187], 0
	v_mfma_f32_16x16x32_bf16 v[64:67], v[148:151], v[184:187], 0
	v_mfma_f32_16x16x32_bf16 v[132:135], v[140:143], v[164:167], v[132:135]
	v_mfma_f32_16x16x32_bf16 v[124:127], v[156:159], v[164:167], v[124:127]
	v_mfma_f32_16x16x32_bf16 v[100:103], v[140:143], v[172:175], v[100:103]
	v_mfma_f32_16x16x32_bf16 v[96:99], v[156:159], v[172:175], v[96:99]
	v_mfma_f32_16x16x32_bf16 v[84:87], v[140:143], v[180:183], v[84:87]
	v_mfma_f32_16x16x32_bf16 v[80:83], v[156:159], v[180:183], v[80:83]
	v_mfma_f32_16x16x32_bf16 v[68:71], v[140:143], v[188:191], v[68:71]
	v_mfma_f32_16x16x32_bf16 v[64:67], v[156:159], v[188:191], v[64:67]
	s_setprio 0
	s_barrier
	s_add_i32 s20, s42, s35
	v_lshl_add_u64 v[194:195], s[22:23], 0, v[192:193]
	s_mov_b32 m0, s20
	ds_read_b128 v[160:163], v243 offset:16384
	ds_read_b128 v[164:167], v243 offset:17408
	ds_read_b128 v[168:171], v243 offset:18432
	ds_read_b128 v[172:175], v243 offset:19456
	ds_read_b128 v[176:179], v243 offset:20480
	ds_read_b128 v[180:183], v243 offset:21504
	ds_read_b128 v[184:187], v243 offset:22528
	ds_read_b128 v[188:191], v243 offset:23552
	global_load_lds_dwordx4 v[194:195], off
	s_add_i32 m0, s20, 0x2000
	s_add_u32 s20, s22, 0x20000
	v_lshl_add_u64 v[196:197], s[22:23], 0, v[208:209]
	s_addc_u32 s21, s23, 0
	s_add_i32 s42, s45, s35
	global_load_lds_dwordx4 v[196:197], off
	v_lshl_add_u64 v[198:199], s[20:21], 0, v[192:193]
	s_mov_b32 m0, s42
	v_lshl_add_u64 v[200:201], s[72:73], 0, v[206:207]
	global_load_lds_dwordx4 v[198:199], off
	v_lshl_add_u64 v[198:199], s[20:21], 0, v[208:209]
	s_add_i32 m0, s42, 0x2000
	s_nop 0
	global_load_lds_dwordx4 v[198:199], off
	v_lshl_add_u64 v[198:199], s[72:73], 0, v[204:205]
	s_mov_b32 m0, s19
	s_nop 0
	global_load_lds_dwordx4 v[198:199], off
	s_mov_b32 m0, s74
	s_nop 0
	global_load_lds_dwordx4 v[200:201], off
	s_waitcnt vmcnt(8)
	s_waitcnt lgkmcnt(0)
	s_barrier
; #define PG8_STAGE(bufoff, gbase, voff) do { _Pragma("unroll") for (int _i = 0; _i < 2; ++_i) \
;         __builtin_amdgcn_global_load_lds((const unsigned*)((const char*)(gbase) + (voff)[_i]), (LAS unsigned*)(lds + (bufoff) + ldsw + _i * 8192), 16, 0, 0); } while (0)
; #define PG8_LDA(dst, b, h) do { _Pragma("unroll") for (int m = 0; m < 4; ++m) _Pragma("unroll") for (int k = 0; k < 2; ++k) dst[m][k] = *(const LAS bf16x8*)(lds + PG8_SA(b, h) + aoff + m * 2048 + k * 1024); } while (0)
; #define PG8_LDB(dst, b, h) do { _Pragma("unroll") for (int n = 0; n < 2; ++n) _Pragma("unroll") for (int k = 0; k < 2; ++k) dst[n][k] = *(const LAS bf16x8*)(lds + PG8_SB(b, h) + boff + n * 2048 + k * 1024); } while (0)
; #define PG8_MMA(ai, bj, At, Bt) do { __builtin_amdgcn_s_setprio(1); _Pragma("unroll") for (int m = 0; m < 4; ++m) _Pragma("unroll") for (int n = 0; n < 2; ++n) _Pragma("unroll") for (int k = 0; k < 2; ++k) \
;         acc[ai][bj][m][n] = __builtin_amdgcn_mfma_f32_16x16x32_bf16(Bt[n][k], At[m][k], acc[ai][bj][m][n], 0, 0, 0); __builtin_amdgcn_s_setprio(0); } while (0)
; #define PG8_WAIT_V(n) asm volatile("s_waitcnt vmcnt(" #n ")" ::: "memory")
; #define PG8_WAIT_L(n) asm volatile("s_waitcnt lgkmcnt(" #n ")" ::: "memory")
; #define PG8_BAR __builtin_amdgcn_s_barrier()
; #define PG8_SCHED __builtin_amdgcn_sched_barrier(0)
; template <class Epi>
; __device__ __forceinline__ void gemm_phase(LAS unsigned char* lds, const Gemm g, const Sched& S, const Epi& E, const int tid) {
;     ...
;             PG8_WAIT_V(8); PG8_WAIT_L(0); PG8_BAR; PG8_MMA(1, 0, At, B0); PG8_MMA(1, 1, At, B1); PG8_BAR; PG8_SCHED;
;             PG8_LDB(B0, 1, 0); PG8_LDB(B1, 1, 1); PG8_SCHED; PG8_LDA(At, 1, 0); PG8_STAGE(PG8_SA(0, 1), a2 + hA, voffA);
;             PG8_WAIT_V(8); PG8_WAIT_L(0); PG8_BAR; PG8_MMA(0, 0, At, B0); PG8_MMA(0, 1, At, B1); PG8_BAR; PG8_SCHED;
	s_setprio 1
	s_waitcnt lgkmcnt(0)
	v_mfma_f32_16x16x32_bf16 v[60:63], v[104:107], v[160:163], 0
	v_mfma_f32_16x16x32_bf16 v[56:59], v[120:123], v[160:163], 0
	v_mfma_f32_16x16x32_bf16 v[44:47], v[104:107], v[168:171], 0
	v_mfma_f32_16x16x32_bf16 v[40:43], v[120:123], v[168:171], 0
	v_mfma_f32_16x16x32_bf16 v[28:31], v[104:107], v[176:179], 0
	v_mfma_f32_16x16x32_bf16 v[24:27], v[120:123], v[176:179], 0
	v_mfma_f32_16x16x32_bf16 v[12:15], v[104:107], v[184:187], 0
	v_mfma_f32_16x16x32_bf16 v[8:11], v[120:123], v[184:187], 0
	v_mfma_f32_16x16x32_bf16 v[60:63], v[112:115], v[164:167], v[60:63]
	v_mfma_f32_16x16x32_bf16 v[56:59], v[128:131], v[164:167], v[56:59]
	v_mfma_f32_16x16x32_bf16 v[44:47], v[112:115], v[172:175], v[44:47]
	v_mfma_f32_16x16x32_bf16 v[40:43], v[128:131], v[172:175], v[40:43]
	v_mfma_f32_16x16x32_bf16 v[28:31], v[112:115], v[180:183], v[28:31]
	v_mfma_f32_16x16x32_bf16 v[24:27], v[128:131], v[180:183], v[24:27]
	v_mfma_f32_16x16x32_bf16 v[12:15], v[112:115], v[188:191], v[12:15]
	v_mfma_f32_16x16x32_bf16 v[8:11], v[128:131], v[188:191], v[8:11]
	v_mfma_f32_16x16x32_bf16 v[52:55], v[136:139], v[160:163], 0
	v_mfma_f32_16x16x32_bf16 v[48:51], v[148:151], v[160:163], 0
	v_mfma_f32_16x16x32_bf16 v[36:39], v[136:139], v[168:171], 0
	v_mfma_f32_16x16x32_bf16 v[32:35], v[148:151], v[168:171], 0
	v_mfma_f32_16x16x32_bf16 v[20:23], v[136:139], v[176:179], 0
	v_mfma_f32_16x16x32_bf16 v[16:19], v[148:151], v[176:179], 0
	v_mfma_f32_16x16x32_bf16 v[4:7], v[136:139], v[184:187], 0
	v_mfma_f32_16x16x32_bf16 v[0:3], v[148:151], v[184:187], 0
	v_mfma_f32_16x16x32_bf16 v[52:55], v[140:143], v[164:167], v[52:55]
	v_mfma_f32_16x16x32_bf16 v[48:51], v[156:159], v[164:167], v[48:51]
	v_mfma_f32_16x16x32_bf16 v[36:39], v[140:143], v[172:175], v[36:39]
	v_mfma_f32_16x16x32_bf16 v[32:35], v[156:159], v[172:175], v[32:35]
	v_mfma_f32_16x16x32_bf16 v[20:23], v[140:143], v[180:183], v[20:23]
	v_mfma_f32_16x16x32_bf16 v[16:19], v[156:159], v[180:183], v[16:19]
	v_mfma_f32_16x16x32_bf16 v[4:7], v[140:143], v[188:191], v[4:7]
	v_mfma_f32_16x16x32_bf16 v[0:3], v[156:159], v[188:191], v[0:3]
	s_setprio 0
	s_barrier
	s_add_i32 s42, 0, 0x18000
	s_add_i32 s45, 0, 0x1c000
	v_add_u32_e32 v128, s42, v241
	v_add_u32_e32 v156, s45, v241
	ds_read_b128 v[104:107], v128
	ds_read_b128 v[112:115], v128 offset:1024
	ds_read_b128 v[120:123], v128 offset:2048
	ds_read_b128 v[128:131], v128 offset:3072
	ds_read_b128 v[136:139], v156
	ds_read_b128 v[140:143], v156 offset:1024
	ds_read_b128 v[148:151], v156 offset:2048
	ds_read_b128 v[156:159], v156 offset:3072
	s_add_u32 s20, s72, 0x120000
	s_addc_u32 s21, s73, 0
	s_mov_b32 m0, s75
	v_lshl_add_u64 v[214:215], s[20:21], 0, v[204:205]
	ds_read_b128 v[160:163], v243 offset:32768
	ds_read_b128 v[164:167], v243 offset:33792
	ds_read_b128 v[168:171], v243 offset:34816
	ds_read_b128 v[172:175], v243 offset:35840
	ds_read_b128 v[176:179], v243 offset:36864
	ds_read_b128 v[180:183], v243 offset:37888
	ds_read_b128 v[184:187], v243 offset:38912
	ds_read_b128 v[188:191], v243 offset:39936
	global_load_lds_dwordx4 v[214:215], off
	v_lshl_add_u64 v[214:215], s[20:21], 0, v[206:207]
	s_mov_b32 m0, s76
	s_nop 0
	global_load_lds_dwordx4 v[214:215], off
	s_waitcnt vmcnt(8)
	s_waitcnt lgkmcnt(0)
	s_barrier
	s_setprio 1
	s_waitcnt lgkmcnt(0)
	v_mfma_f32_16x16x32_bf16 v[152:155], v[104:107], v[160:163], v[152:155]
	v_mfma_f32_16x16x32_bf16 v[144:147], v[120:123], v[160:163], v[144:147]
	v_mfma_f32_16x16x32_bf16 v[116:119], v[104:107], v[168:171], v[116:119]
	v_mfma_f32_16x16x32_bf16 v[108:111], v[120:123], v[168:171], v[108:111]
	v_mfma_f32_16x16x32_bf16 v[92:95], v[104:107], v[176:179], v[92:95]
	v_mfma_f32_16x16x32_bf16 v[88:91], v[120:123], v[176:179], v[88:91]
	v_mfma_f32_16x16x32_bf16 v[76:79], v[104:107], v[184:187], v[76:79]
	v_mfma_f32_16x16x32_bf16 v[72:75], v[120:123], v[184:187], v[72:75]
	v_mfma_f32_16x16x32_bf16 v[152:155], v[112:115], v[164:167], v[152:155]
	v_mfma_f32_16x16x32_bf16 v[144:147], v[128:131], v[164:167], v[144:147]
	v_mfma_f32_16x16x32_bf16 v[116:119], v[112:115], v[172:175], v[116:119]
	v_mfma_f32_16x16x32_bf16 v[108:111], v[128:131], v[172:175], v[108:111]
	v_mfma_f32_16x16x32_bf16 v[92:95], v[112:115], v[180:183], v[92:95]
	v_mfma_f32_16x16x32_bf16 v[88:91], v[128:131], v[180:183], v[88:91]
	v_mfma_f32_16x16x32_bf16 v[76:79], v[112:115], v[188:191], v[76:79]
	v_mfma_f32_16x16x32_bf16 v[72:75], v[128:131], v[188:191], v[72:75]
	v_mfma_f32_16x16x32_bf16 v[132:135], v[136:139], v[160:163], v[132:135]
	v_mfma_f32_16x16x32_bf16 v[124:127], v[148:151], v[160:163], v[124:127]
	v_mfma_f32_16x16x32_bf16 v[100:103], v[136:139], v[168:171], v[100:103]
	v_mfma_f32_16x16x32_bf16 v[96:99], v[148:151], v[168:171], v[96:99]
	v_mfma_f32_16x16x32_bf16 v[84:87], v[136:139], v[176:179], v[84:87]
	v_mfma_f32_16x16x32_bf16 v[80:83], v[148:151], v[176:179], v[80:83]
	v_mfma_f32_16x16x32_bf16 v[68:71], v[136:139], v[184:187], v[68:71]
	v_mfma_f32_16x16x32_bf16 v[64:67], v[148:151], v[184:187], v[64:67]
	v_mfma_f32_16x16x32_bf16 v[132:135], v[140:143], v[164:167], v[132:135]
	v_mfma_f32_16x16x32_bf16 v[124:127], v[156:159], v[164:167], v[124:127]
	v_mfma_f32_16x16x32_bf16 v[100:103], v[140:143], v[172:175], v[100:103]
	v_mfma_f32_16x16x32_bf16 v[96:99], v[156:159], v[172:175], v[96:99]
	v_mfma_f32_16x16x32_bf16 v[84:87], v[140:143], v[180:183], v[84:87]
	v_mfma_f32_16x16x32_bf16 v[80:83], v[156:159], v[180:183], v[80:83]
	v_mfma_f32_16x16x32_bf16 v[68:71], v[140:143], v[188:191], v[68:71]
	v_mfma_f32_16x16x32_bf16 v[64:67], v[156:159], v[188:191], v[64:67]
	s_setprio 0
	s_barrier
; #define PG8_STAGE(bufoff, gbase, voff) do { _Pragma("unroll") for (int _i = 0; _i < 2; ++_i) \
;         __builtin_amdgcn_global_load_lds((const unsigned*)((const char*)(gbase) + (voff)[_i]), (LAS unsigned*)(lds + (bufoff) + ldsw + _i * 8192), 16, 0, 0); } while (0)
; #define PG8_LDA(dst, b, h) do { _Pragma("unroll") for (int m = 0; m < 4; ++m) _Pragma("unroll") for (int k = 0; k < 2; ++k) dst[m][k] = *(const LAS bf16x8*)(lds + PG8_SA(b, h) + aoff + m * 2048 + k * 1024); } while (0)
; #define PG8_LDB(dst, b, h) do { _Pragma("unroll") for (int n = 0; n < 2; ++n) _Pragma("unroll") for (int k = 0; k < 2; ++k) dst[n][k] = *(const LAS bf16x8*)(lds + PG8_SB(b, h) + boff + n * 2048 + k * 1024); } while (0)
; #define PG8_WAIT_V(n) asm volatile("s_waitcnt vmcnt(" #n ")" ::: "memory")
; #define PG8_BAR __builtin_amdgcn_s_barrier()
; template <class Epi>
; __device__ __forceinline__ void gemm_phase(LAS unsigned char* lds, const Gemm g, const Sched& S, const Epi& E, const int tid) {
;     ...
;         for (int t = 0; t < nt; t += 2) {
;             const bool last = (t == nt - 2);
;             const char* a1 = cA + (size_t)(t + 1) * kstep;
;             const char* a2 = last ? nA : cA + (size_t)(t + 2) * kstep; const char* b2 = last ? nB : cB + (size_t)(t + 2) * kstep;
;             const char* a3 = a2 + kstep; const char* b3 = b2 + kstep;
;             PG8_LDB(B0, 0, 0); PG8_LDB(B1, 0, 1); PG8_SCHED; PG8_LDA(At, 0, 0); PG8_STAGE(PG8_SA(1, 1), a1 + hA, voffA);
;             PG8_WAIT_V(8); PG8_WAIT_L(0); PG8_BAR; PG8_MMA(0, 0, At, B0); PG8_MMA(0, 1, At, B1); PG8_BAR; PG8_SCHED;
;             PG8_LDA(At, 0, 1); PG8_STAGE(PG8_SB(0, 0), b2, voffB); PG8_STAGE(PG8_SB(0, 1), b2 + hB, voffB); PG8_STAGE(PG8_SA(0, 0), a2, voffA);
;             PG8_WAIT_V(8); PG8_WAIT_L(0); PG8_BAR; PG8_MMA(1, 0, At, B0); PG8_MMA(1, 1, At, B1); PG8_BAR; PG8_SCHED;
;             PG8_LDB(B0, 1, 0); PG8_LDB(B1, 1, 1); PG8_SCHED; PG8_LDA(At, 1, 0); PG8_STAGE(PG8_SA(0, 1), a2 + hA, voffA);
;             PG8_WAIT_V(8); PG8_WAIT_L(0); PG8_BAR; PG8_MMA(0, 0, At, B0); PG8_MMA(0, 1, At, B1); PG8_BAR; PG8_SCHED;
;             PG8_LDA(At, 1, 1); PG8_STAGE(PG8_SB(1, 0), b3, voffB); PG8_STAGE(PG8_SB(1, 1), b3 + hB, voffB); PG8_STAGE(PG8_SA(1, 0), a3, voffA);
;             PG8_WAIT_V(8); PG8_WAIT_L(0); PG8_BAR; PG8_MMA(1, 0, At, B0); PG8_MMA(1, 1, At, B1); PG8_BAR; PG8_SCHED;
;         }
	s_add_i32 s20, s42, s35
	v_lshl_add_u64 v[194:195], v[194:195], 0, s[94:95]
	s_mov_b32 m0, s20
	ds_read_b128 v[160:163], v243 offset:49152
	ds_read_b128 v[164:167], v243 offset:50176
	ds_read_b128 v[168:171], v243 offset:51200
	ds_read_b128 v[172:175], v243 offset:52224
	ds_read_b128 v[176:179], v243 offset:53248
	ds_read_b128 v[180:183], v243 offset:54272
	ds_read_b128 v[184:187], v243 offset:55296
	ds_read_b128 v[188:191], v243 offset:56320
	global_load_lds_dwordx4 v[194:195], off
	s_add_i32 m0, s20, 0x2000
	s_add_u32 s20, s22, 0x20080
	v_lshl_add_u64 v[194:195], v[196:197], 0, s[94:95]
	s_addc_u32 s21, s23, 0
	s_add_i32 s22, s45, s35
	global_load_lds_dwordx4 v[194:195], off
	v_lshl_add_u64 v[194:195], s[20:21], 0, v[192:193]
	s_mov_b32 m0, s22
	s_nop 0
	global_load_lds_dwordx4 v[194:195], off
	v_lshl_add_u64 v[194:195], s[20:21], 0, v[208:209]
	s_add_i32 m0, s22, 0x2000
	s_nop 0
	global_load_lds_dwordx4 v[194:195], off
	v_lshl_add_u64 v[194:195], v[198:199], 0, s[94:95]
	s_mov_b32 m0, s77
	s_nop 0
	global_load_lds_dwordx4 v[194:195], off
	v_lshl_add_u64 v[194:195], v[200:201], 0, s[94:95]
	s_mov_b32 m0, s78
	s_nop 0
	global_load_lds_dwordx4 v[194:195], off
	s_waitcnt vmcnt(8)
	s_waitcnt lgkmcnt(0)
	s_barrier
	s_setprio 1
	s_waitcnt lgkmcnt(0)
	v_mfma_f32_16x16x32_bf16 v[60:63], v[104:107], v[160:163], v[60:63]
	v_mfma_f32_16x16x32_bf16 v[56:59], v[120:123], v[160:163], v[56:59]
	v_mfma_f32_16x16x32_bf16 v[44:47], v[104:107], v[168:171], v[44:47]
	v_mfma_f32_16x16x32_bf16 v[40:43], v[120:123], v[168:171], v[40:43]
	v_mfma_f32_16x16x32_bf16 v[28:31], v[104:107], v[176:179], v[28:31]
	v_mfma_f32_16x16x32_bf16 v[24:27], v[120:123], v[176:179], v[24:27]
	v_mfma_f32_16x16x32_bf16 v[12:15], v[104:107], v[184:187], v[12:15]
	v_mfma_f32_16x16x32_bf16 v[8:11], v[120:123], v[184:187], v[8:11]
	v_mfma_f32_16x16x32_bf16 v[60:63], v[112:115], v[164:167], v[60:63]
	v_mfma_f32_16x16x32_bf16 v[56:59], v[128:131], v[164:167], v[56:59]
	v_mfma_f32_16x16x32_bf16 v[44:47], v[112:115], v[172:175], v[44:47]
	v_mfma_f32_16x16x32_bf16 v[40:43], v[128:131], v[172:175], v[40:43]
	v_mfma_f32_16x16x32_bf16 v[28:31], v[112:115], v[180:183], v[28:31]
	v_mfma_f32_16x16x32_bf16 v[24:27], v[128:131], v[180:183], v[24:27]
	v_mfma_f32_16x16x32_bf16 v[12:15], v[112:115], v[188:191], v[12:15]
	v_mfma_f32_16x16x32_bf16 v[8:11], v[128:131], v[188:191], v[8:11]
	v_mfma_f32_16x16x32_bf16 v[52:55], v[136:139], v[160:163], v[52:55]
	v_mfma_f32_16x16x32_bf16 v[48:51], v[148:151], v[160:163], v[48:51]
	v_mfma_f32_16x16x32_bf16 v[36:39], v[136:139], v[168:171], v[36:39]
	v_mfma_f32_16x16x32_bf16 v[32:35], v[148:151], v[168:171], v[32:35]
	v_mfma_f32_16x16x32_bf16 v[20:23], v[136:139], v[176:179], v[20:23]
	v_mfma_f32_16x16x32_bf16 v[16:19], v[148:151], v[176:179], v[16:19]
	v_mfma_f32_16x16x32_bf16 v[4:7], v[136:139], v[184:187], v[4:7]
	v_mfma_f32_16x16x32_bf16 v[0:3], v[148:151], v[184:187], v[0:3]
	v_mfma_f32_16x16x32_bf16 v[52:55], v[140:143], v[164:167], v[52:55]
	v_mfma_f32_16x16x32_bf16 v[48:51], v[156:159], v[164:167], v[48:51]
	v_mfma_f32_16x16x32_bf16 v[36:39], v[140:143], v[172:175], v[36:39]
	v_mfma_f32_16x16x32_bf16 v[32:35], v[156:159], v[172:175], v[32:35]
	v_mfma_f32_16x16x32_bf16 v[20:23], v[140:143], v[180:183], v[20:23]
	v_mfma_f32_16x16x32_bf16 v[16:19], v[156:159], v[180:183], v[16:19]
	v_mfma_f32_16x16x32_bf16 v[4:7], v[140:143], v[188:191], v[4:7]
	v_mfma_f32_16x16x32_bf16 v[0:3], v[156:159], v[188:191], v[0:3]
	s_setprio 0
	s_barrier
	s_add_i32 s40, s40, 2
	s_add_u32 s13, s13, 0x100
	s_addc_u32 s37, s37, 0
	s_cmp_gt_u32 s40, 5
	s_mov_b64 s[20:21], s[6:7]
	s_cbranch_scc1 .Lgk_exit_2
.LBB0_1029:
	s_add_u32 s6, s20, 0x100
	s_addc_u32 s7, s21, 0
	s_add_i32 s42, 0, 0x10000
	s_cmp_eq_u32 s40, 4
	s_cselect_b32 s73, s15, s7
	s_cselect_b32 s72, s14, s6
	s_cselect_b32 s23, s17, s37
	s_cselect_b32 s22, s16, s13
	s_add_i32 s45, 0, 0x14000
	v_add_u32_e32 v128, s42, v241
	v_add_u32_e32 v156, s45, v241
	ds_read_b128 v[104:107], v128
	ds_read_b128 v[112:115], v128 offset:1024
	ds_read_b128 v[120:123], v128 offset:2048
	ds_read_b128 v[128:131], v128 offset:3072
	ds_read_b128 v[136:139], v156
	ds_read_b128 v[140:143], v156 offset:1024
	ds_read_b128 v[148:151], v156 offset:2048
	ds_read_b128 v[156:159], v156 offset:3072
	v_lshl_add_u64 v[194:195], s[20:21], 0, v[210:211]
	s_add_i32 m0, s19, 0xc000
	ds_read_b128 v[160:163], v243
	ds_read_b128 v[164:167], v243 offset:1024
	ds_read_b128 v[168:171], v243 offset:2048
	ds_read_b128 v[172:175], v243 offset:3072
	ds_read_b128 v[176:179], v243 offset:4096
	ds_read_b128 v[180:183], v243 offset:5120
	ds_read_b128 v[184:187], v243 offset:6144
	ds_read_b128 v[188:191], v243 offset:7168
	global_load_lds_dwordx4 v[194:195], off
	v_lshl_add_u64 v[194:195], s[20:21], 0, v[212:213]
	s_add_i32 m0, s19, 0xe000
	s_nop 0
	global_load_lds_dwordx4 v[194:195], off
	s_waitcnt vmcnt(8)
	s_waitcnt lgkmcnt(0)
	s_barrier
; #define PG8_STAGE(bufoff, gbase, voff) do { _Pragma("unroll") for (int _i = 0; _i < 2; ++_i) \
;         __builtin_amdgcn_global_load_lds((const unsigned*)((const char*)(gbase) + (voff)[_i]), (LAS unsigned*)(lds + (bufoff) + ldsw + _i * 8192), 16, 0, 0); } while (0)
; #define PG8_LDA(dst, b, h) do { _Pragma("unroll") for (int m = 0; m < 4; ++m) _Pragma("unroll") for (int k = 0; k < 2; ++k) dst[m][k] = *(const LAS bf16x8*)(lds + PG8_SA(b, h) + aoff + m * 2048 + k * 1024); } while (0)
; #define PG8_MMA(ai, bj, At, Bt) do { __builtin_amdgcn_s_setprio(1); _Pragma("unroll") for (int m = 0; m < 4; ++m) _Pragma("unroll") for (int n = 0; n < 2; ++n) _Pragma("unroll") for (int k = 0; k < 2; ++k) \
;         acc[ai][bj][m][n] = __builtin_amdgcn_mfma_f32_16x16x32_bf16(Bt[n][k], At[m][k], acc[ai][bj][m][n], 0, 0, 0); __builtin_amdgcn_s_setprio(0); } while (0)
; #define PG8_WAIT_V(n) asm volatile("s_waitcnt vmcnt(" #n ")" ::: "memory")
; #define PG8_WAIT_L(n) asm volatile("s_waitcnt lgkmcnt(" #n ")" ::: "memory")
; #define PG8_BAR __builtin_amdgcn_s_barrier()
; #define PG8_SCHED __builtin_amdgcn_sched_barrier(0)
; template <class Epi>
; __device__ __forceinline__ void gemm_phase(LAS unsigned char* lds, const Gemm g, const Sched& S, const Epi& E, const int tid) {
;     ...
;             PG8_WAIT_V(8); PG8_WAIT_L(0); PG8_BAR; PG8_MMA(0, 0, At, B0); PG8_MMA(0, 1, At, B1); PG8_BAR; PG8_SCHED;
;             PG8_LDA(At, 0, 1); PG8_STAGE(PG8_SB(0, 0), b2, voffB); PG8_STAGE(PG8_SB(0, 1), b2 + hB, voffB); PG8_STAGE(PG8_SA(0, 0), a2, voffA);
;             PG8_WAIT_V(8); PG8_WAIT_L(0); PG8_BAR; PG8_MMA(1, 0, At, B0); PG8_MMA(1, 1, At, B1); PG8_BAR; PG8_SCHED;
	s_setprio 1
	s_waitcnt lgkmcnt(0)
	v_mfma_f32_16x16x32_bf16 v[152:155], v[104:107], v[160:163], v[152:155]
	v_mfma_f32_16x16x32_bf16 v[144:147], v[120:123], v[160:163], v[144:147]
	v_mfma_f32_16x16x32_bf16 v[116:119], v[104:107], v[168:171], v[116:119]
	v_mfma_f32_16x16x32_bf16 v[108:111], v[120:123], v[168:171], v[108:111]
	v_mfma_f32_16x16x32_bf16 v[92:95], v[104:107], v[176:179], v[92:95]
	v_mfma_f32_16x16x32_bf16 v[88:91], v[120:123], v[176:179], v[88:91]
	v_mfma_f32_16x16x32_bf16 v[76:79], v[104:107], v[184:187], v[76:79]
	v_mfma_f32_16x16x32_bf16 v[72:75], v[120:123], v[184:187], v[72:75]
	v_mfma_f32_16x16x32_bf16 v[152:155], v[112:115], v[164:167], v[152:155]
	v_mfma_f32_16x16x32_bf16 v[144:147], v[128:131], v[164:167], v[144:147]
	v_mfma_f32_16x16x32_bf16 v[116:119], v[112:115], v[172:175], v[116:119]
	v_mfma_f32_16x16x32_bf16 v[108:111], v[128:131], v[172:175], v[108:111]
	v_mfma_f32_16x16x32_bf16 v[92:95], v[112:115], v[180:183], v[92:95]
	v_mfma_f32_16x16x32_bf16 v[88:91], v[128:131], v[180:183], v[88:91]
	v_mfma_f32_16x16x32_bf16 v[76:79], v[112:115], v[188:191], v[76:79]
	v_mfma_f32_16x16x32_bf16 v[72:75], v[128:131], v[188:191], v[72:75]
	v_mfma_f32_16x16x32_bf16 v[132:135], v[136:139], v[160:163], v[132:135]
	v_mfma_f32_16x16x32_bf16 v[124:127], v[148:151], v[160:163], v[124:127]
	v_mfma_f32_16x16x32_bf16 v[100:103], v[136:139], v[168:171], v[100:103]
	v_mfma_f32_16x16x32_bf16 v[96:99], v[148:151], v[168:171], v[96:99]
	v_mfma_f32_16x16x32_bf16 v[84:87], v[136:139], v[176:179], v[84:87]
	v_mfma_f32_16x16x32_bf16 v[80:83], v[148:151], v[176:179], v[80:83]
	v_mfma_f32_16x16x32_bf16 v[68:71], v[136:139], v[184:187], v[68:71]
	v_mfma_f32_16x16x32_bf16 v[64:67], v[148:151], v[184:187], v[64:67]
	v_mfma_f32_16x16x32_bf16 v[132:135], v[140:143], v[164:167], v[132:135]
	v_mfma_f32_16x16x32_bf16 v[124:127], v[156:159], v[164:167], v[124:127]
	v_mfma_f32_16x16x32_bf16 v[100:103], v[140:143], v[172:175], v[100:103]
	v_mfma_f32_16x16x32_bf16 v[96:99], v[156:159], v[172:175], v[96:99]
	v_mfma_f32_16x16x32_bf16 v[84:87], v[140:143], v[180:183], v[84:87]
	v_mfma_f32_16x16x32_bf16 v[80:83], v[156:159], v[180:183], v[80:83]
	v_mfma_f32_16x16x32_bf16 v[68:71], v[140:143], v[188:191], v[68:71]
	v_mfma_f32_16x16x32_bf16 v[64:67], v[156:159], v[188:191], v[64:67]
	s_setprio 0
	s_barrier
	s_add_i32 s20, s42, s35
	v_lshl_add_u64 v[194:195], s[22:23], 0, v[192:193]
	s_mov_b32 m0, s20
	ds_read_b128 v[160:163], v243 offset:16384
	ds_read_b128 v[164:167], v243 offset:17408
	ds_read_b128 v[168:171], v243 offset:18432
	ds_read_b128 v[172:175], v243 offset:19456
	ds_read_b128 v[176:179], v243 offset:20480
	ds_read_b128 v[180:183], v243 offset:21504
	ds_read_b128 v[184:187], v243 offset:22528
	ds_read_b128 v[188:191], v243 offset:23552
	global_load_lds_dwordx4 v[194:195], off
	s_add_i32 m0, s20, 0x2000
	s_add_u32 s20, s22, 0x20000
	v_lshl_add_u64 v[196:197], s[22:23], 0, v[208:209]
	s_addc_u32 s21, s23, 0
	s_add_i32 s42, s45, s35
	global_load_lds_dwordx4 v[196:197], off
	v_lshl_add_u64 v[198:199], s[20:21], 0, v[192:193]
	s_mov_b32 m0, s42
	v_lshl_add_u64 v[200:201], s[72:73], 0, v[206:207]
	global_load_lds_dwordx4 v[198:199], off
	v_lshl_add_u64 v[198:199], s[20:21], 0, v[208:209]
	s_add_i32 m0, s42, 0x2000
	s_nop 0
	global_load_lds_dwordx4 v[198:199], off
	v_lshl_add_u64 v[198:199], s[72:73], 0, v[204:205]
	s_mov_b32 m0, s19
	s_nop 0
	global_load_lds_dwordx4 v[198:199], off
	s_mov_b32 m0, s74
	s_nop 0
	global_load_lds_dwordx4 v[200:201], off
	s_waitcnt vmcnt(8)
	s_waitcnt lgkmcnt(0)
	s_barrier
	s_setprio 1
	s_waitcnt lgkmcnt(0)
	v_mfma_f32_16x16x32_bf16 v[60:63], v[104:107], v[160:163], v[60:63]
	v_mfma_f32_16x16x32_bf16 v[56:59], v[120:123], v[160:163], v[56:59]
	v_mfma_f32_16x16x32_bf16 v[44:47], v[104:107], v[168:171], v[44:47]
	v_mfma_f32_16x16x32_bf16 v[40:43], v[120:123], v[168:171], v[40:43]
	v_mfma_f32_16x16x32_bf16 v[28:31], v[104:107], v[176:179], v[28:31]
	v_mfma_f32_16x16x32_bf16 v[24:27], v[120:123], v[176:179], v[24:27]
	v_mfma_f32_16x16x32_bf16 v[12:15], v[104:107], v[184:187], v[12:15]
	v_mfma_f32_16x16x32_bf16 v[8:11], v[120:123], v[184:187], v[8:11]
	v_mfma_f32_16x16x32_bf16 v[60:63], v[112:115], v[164:167], v[60:63]
	v_mfma_f32_16x16x32_bf16 v[56:59], v[128:131], v[164:167], v[56:59]
	v_mfma_f32_16x16x32_bf16 v[44:47], v[112:115], v[172:175], v[44:47]
	v_mfma_f32_16x16x32_bf16 v[40:43], v[128:131], v[172:175], v[40:43]
	v_mfma_f32_16x16x32_bf16 v[28:31], v[112:115], v[180:183], v[28:31]
	v_mfma_f32_16x16x32_bf16 v[24:27], v[128:131], v[180:183], v[24:27]
	v_mfma_f32_16x16x32_bf16 v[12:15], v[112:115], v[188:191], v[12:15]
	v_mfma_f32_16x16x32_bf16 v[8:11], v[128:131], v[188:191], v[8:11]
	v_mfma_f32_16x16x32_bf16 v[52:55], v[136:139], v[160:163], v[52:55]
	v_mfma_f32_16x16x32_bf16 v[48:51], v[148:151], v[160:163], v[48:51]
	v_mfma_f32_16x16x32_bf16 v[36:39], v[136:139], v[168:171], v[36:39]
	v_mfma_f32_16x16x32_bf16 v[32:35], v[148:151], v[168:171], v[32:35]
	v_mfma_f32_16x16x32_bf16 v[20:23], v[136:139], v[176:179], v[20:23]
	v_mfma_f32_16x16x32_bf16 v[16:19], v[148:151], v[176:179], v[16:19]
	v_mfma_f32_16x16x32_bf16 v[4:7], v[136:139], v[184:187], v[4:7]
	v_mfma_f32_16x16x32_bf16 v[0:3], v[148:151], v[184:187], v[0:3]
	v_mfma_f32_16x16x32_bf16 v[52:55], v[140:143], v[164:167], v[52:55]
	v_mfma_f32_16x16x32_bf16 v[48:51], v[156:159], v[164:167], v[48:51]
	v_mfma_f32_16x16x32_bf16 v[36:39], v[140:143], v[172:175], v[36:39]
	v_mfma_f32_16x16x32_bf16 v[32:35], v[156:159], v[172:175], v[32:35]
	v_mfma_f32_16x16x32_bf16 v[20:23], v[140:143], v[180:183], v[20:23]
	v_mfma_f32_16x16x32_bf16 v[16:19], v[156:159], v[180:183], v[16:19]
	v_mfma_f32_16x16x32_bf16 v[4:7], v[140:143], v[188:191], v[4:7]
	v_mfma_f32_16x16x32_bf16 v[0:3], v[156:159], v[188:191], v[0:3]
	s_setprio 0
	s_barrier
; #define PG8_STAGE(bufoff, gbase, voff) do { _Pragma("unroll") for (int _i = 0; _i < 2; ++_i) \
;         __builtin_amdgcn_global_load_lds((const unsigned*)((const char*)(gbase) + (voff)[_i]), (LAS unsigned*)(lds + (bufoff) + ldsw + _i * 8192), 16, 0, 0); } while (0)
; #define PG8_LDA(dst, b, h) do { _Pragma("unroll") for (int m = 0; m < 4; ++m) _Pragma("unroll") for (int k = 0; k < 2; ++k) dst[m][k] = *(const LAS bf16x8*)(lds + PG8_SA(b, h) + aoff + m * 2048 + k * 1024); } while (0)
; #define PG8_LDB(dst, b, h) do { _Pragma("unroll") for (int n = 0; n < 2; ++n) _Pragma("unroll") for (int k = 0; k < 2; ++k) dst[n][k] = *(const LAS bf16x8*)(lds + PG8_SB(b, h) + boff + n * 2048 + k * 1024); } while (0)
; #define PG8_MMA(ai, bj, At, Bt) do { __builtin_amdgcn_s_setprio(1); _Pragma("unroll") for (int m = 0; m < 4; ++m) _Pragma("unroll") for (int n = 0; n < 2; ++n) _Pragma("unroll") for (int k = 0; k < 2; ++k) \
;         acc[ai][bj][m][n] = __builtin_amdgcn_mfma_f32_16x16x32_bf16(Bt[n][k], At[m][k], acc[ai][bj][m][n], 0, 0, 0); __builtin_amdgcn_s_setprio(0); } while (0)
; #define PG8_WAIT_V(n) asm volatile("s_waitcnt vmcnt(" #n ")" ::: "memory")
; #define PG8_WAIT_L(n) asm volatile("s_waitcnt lgkmcnt(" #n ")" ::: "memory")
; #define PG8_BAR __builtin_amdgcn_s_barrier()
; #define PG8_SCHED __builtin_amdgcn_sched_barrier(0)
; template <class Epi>
; __device__ __forceinline__ void gemm_phase(LAS unsigned char* lds, const Gemm g, const Sched& S, const Epi& E, const int tid) {
;     ...
;             PG8_LDB(B0, 1, 0); PG8_LDB(B1, 1, 1); PG8_SCHED; PG8_LDA(At, 1, 0); PG8_STAGE(PG8_SA(0, 1), a2 + hA, voffA);
;             PG8_WAIT_V(8); PG8_WAIT_L(0); PG8_BAR; PG8_MMA(0, 0, At, B0); PG8_MMA(0, 1, At, B1); PG8_BAR; PG8_SCHED;
	s_add_i32 s42, 0, 0x18000
	s_add_i32 s45, 0, 0x1c000
	v_add_u32_e32 v128, s42, v241
	v_add_u32_e32 v156, s45, v241
	ds_read_b128 v[104:107], v128
	ds_read_b128 v[112:115], v128 offset:1024
	ds_read_b128 v[120:123], v128 offset:2048
	ds_read_b128 v[128:131], v128 offset:3072
	ds_read_b128 v[136:139], v156
	ds_read_b128 v[140:143], v156 offset:1024
	ds_read_b128 v[148:151], v156 offset:2048
	ds_read_b128 v[156:159], v156 offset:3072
	s_add_u32 s20, s72, 0x120000
	s_addc_u32 s21, s73, 0
	s_mov_b32 m0, s75
	v_lshl_add_u64 v[214:215], s[20:21], 0, v[204:205]
	ds_read_b128 v[160:163], v243 offset:32768
	ds_read_b128 v[164:167], v243 offset:33792
	ds_read_b128 v[168:171], v243 offset:34816
	ds_read_b128 v[172:175], v243 offset:35840
	ds_read_b128 v[176:179], v243 offset:36864
	ds_read_b128 v[180:183], v243 offset:37888
	ds_read_b128 v[184:187], v243 offset:38912
	ds_read_b128 v[188:191], v243 offset:39936
	global_load_lds_dwordx4 v[214:215], off
	v_lshl_add_u64 v[214:215], s[20:21], 0, v[206:207]
	s_mov_b32 m0, s76
	s_nop 0
	global_load_lds_dwordx4 v[214:215], off
	s_waitcnt vmcnt(8)
	s_waitcnt lgkmcnt(0)
	s_barrier
	s_setprio 1
	s_waitcnt lgkmcnt(0)
	v_mfma_f32_16x16x32_bf16 v[152:155], v[104:107], v[160:163], v[152:155]
	v_mfma_f32_16x16x32_bf16 v[144:147], v[120:123], v[160:163], v[144:147]
	v_mfma_f32_16x16x32_bf16 v[116:119], v[104:107], v[168:171], v[116:119]
	v_mfma_f32_16x16x32_bf16 v[108:111], v[120:123], v[168:171], v[108:111]
	v_mfma_f32_16x16x32_bf16 v[92:95], v[104:107], v[176:179], v[92:95]
	v_mfma_f32_16x16x32_bf16 v[88:91], v[120:123], v[176:179], v[88:91]
	v_mfma_f32_16x16x32_bf16 v[76:79], v[104:107], v[184:187], v[76:79]
	v_mfma_f32_16x16x32_bf16 v[72:75], v[120:123], v[184:187], v[72:75]
	v_mfma_f32_16x16x32_bf16 v[152:155], v[112:115], v[164:167], v[152:155]
	v_mfma_f32_16x16x32_bf16 v[144:147], v[128:131], v[164:167], v[144:147]
	v_mfma_f32_16x16x32_bf16 v[116:119], v[112:115], v[172:175], v[116:119]
	v_mfma_f32_16x16x32_bf16 v[108:111], v[128:131], v[172:175], v[108:111]
	v_mfma_f32_16x16x32_bf16 v[92:95], v[112:115], v[180:183], v[92:95]
	v_mfma_f32_16x16x32_bf16 v[88:91], v[128:131], v[180:183], v[88:91]
	v_mfma_f32_16x16x32_bf16 v[76:79], v[112:115], v[188:191], v[76:79]
	v_mfma_f32_16x16x32_bf16 v[72:75], v[128:131], v[188:191], v[72:75]
	v_mfma_f32_16x16x32_bf16 v[132:135], v[136:139], v[160:163], v[132:135]
	v_mfma_f32_16x16x32_bf16 v[124:127], v[148:151], v[160:163], v[124:127]
	v_mfma_f32_16x16x32_bf16 v[100:103], v[136:139], v[168:171], v[100:103]
	v_mfma_f32_16x16x32_bf16 v[96:99], v[148:151], v[168:171], v[96:99]
	v_mfma_f32_16x16x32_bf16 v[84:87], v[136:139], v[176:179], v[84:87]
	v_mfma_f32_16x16x32_bf16 v[80:83], v[148:151], v[176:179], v[80:83]
	v_mfma_f32_16x16x32_bf16 v[68:71], v[136:139], v[184:187], v[68:71]
	v_mfma_f32_16x16x32_bf16 v[64:67], v[148:151], v[184:187], v[64:67]
	v_mfma_f32_16x16x32_bf16 v[132:135], v[140:143], v[164:167], v[132:135]
	v_mfma_f32_16x16x32_bf16 v[124:127], v[156:159], v[164:167], v[124:127]
	v_mfma_f32_16x16x32_bf16 v[100:103], v[140:143], v[172:175], v[100:103]
	v_mfma_f32_16x16x32_bf16 v[96:99], v[156:159], v[172:175], v[96:99]
	v_mfma_f32_16x16x32_bf16 v[84:87], v[140:143], v[180:183], v[84:87]
	v_mfma_f32_16x16x32_bf16 v[80:83], v[156:159], v[180:183], v[80:83]
	v_mfma_f32_16x16x32_bf16 v[68:71], v[140:143], v[188:191], v[68:71]
	v_mfma_f32_16x16x32_bf16 v[64:67], v[156:159], v[188:191], v[64:67]
	s_setprio 0
	s_barrier
; #define PG8_STAGE(bufoff, gbase, voff) do { _Pragma("unroll") for (int _i = 0; _i < 2; ++_i) \
;         __builtin_amdgcn_global_load_lds((const unsigned*)((const char*)(gbase) + (voff)[_i]), (LAS unsigned*)(lds + (bufoff) + ldsw + _i * 8192), 16, 0, 0); } while (0)
; #define PG8_LDA(dst, b, h) do { _Pragma("unroll") for (int m = 0; m < 4; ++m) _Pragma("unroll") for (int k = 0; k < 2; ++k) dst[m][k] = *(const LAS bf16x8*)(lds + PG8_SA(b, h) + aoff + m * 2048 + k * 1024); } while (0)
; #define PG8_MMA(ai, bj, At, Bt) do { __builtin_amdgcn_s_setprio(1); _Pragma("unroll") for (int m = 0; m < 4; ++m) _Pragma("unroll") for (int n = 0; n < 2; ++n) _Pragma("unroll") for (int k = 0; k < 2; ++k) \
;         acc[ai][bj][m][n] = __builtin_amdgcn_mfma_f32_16x16x32_bf16(Bt[n][k], At[m][k], acc[ai][bj][m][n], 0, 0, 0); __builtin_amdgcn_s_setprio(0); } while (0)
; #define PG8_WAIT_V(n) asm volatile("s_waitcnt vmcnt(" #n ")" ::: "memory")
; #define PG8_WAIT_L(n) asm volatile("s_waitcnt lgkmcnt(" #n ")" ::: "memory")
; #define PG8_BAR __builtin_amdgcn_s_barrier()
; #define PG8_SCHED __builtin_amdgcn_sched_barrier(0)
; template <class Epi>
; __device__ __forceinline__ void gemm_phase(LAS unsigned char* lds, const Gemm g, const Sched& S, const Epi& E, const int tid) {
;     ...
;             PG8_LDA(At, 1, 1); PG8_STAGE(PG8_SB(1, 0), b3, voffB); PG8_STAGE(PG8_SB(1, 1), b3 + hB, voffB); PG8_STAGE(PG8_SA(1, 0), a3, voffA);
;             PG8_WAIT_V(8); PG8_WAIT_L(0); PG8_BAR; PG8_MMA(1, 0, At, B0); PG8_MMA(1, 1, At, B1); PG8_BAR; PG8_SCHED;
;         }
	s_add_i32 s20, s42, s35
	v_lshl_add_u64 v[194:195], v[194:195], 0, s[94:95]
	s_mov_b32 m0, s20
	ds_read_b128 v[160:163], v243 offset:49152
	ds_read_b128 v[164:167], v243 offset:50176
	ds_read_b128 v[168:171], v243 offset:51200
	ds_read_b128 v[172:175], v243 offset:52224
	ds_read_b128 v[176:179], v243 offset:53248
	ds_read_b128 v[180:183], v243 offset:54272
	ds_read_b128 v[184:187], v243 offset:55296
	ds_read_b128 v[188:191], v243 offset:56320
	global_load_lds_dwordx4 v[194:195], off
	s_add_i32 m0, s20, 0x2000
	s_add_u32 s20, s22, 0x20080
	v_lshl_add_u64 v[194:195], v[196:197], 0, s[94:95]
	s_addc_u32 s21, s23, 0
	s_add_i32 s22, s45, s35
	global_load_lds_dwordx4 v[194:195], off
	v_lshl_add_u64 v[194:195], s[20:21], 0, v[192:193]
	s_mov_b32 m0, s22
	s_nop 0
	global_load_lds_dwordx4 v[194:195], off
	v_lshl_add_u64 v[194:195], s[20:21], 0, v[208:209]
	s_add_i32 m0, s22, 0x2000
	s_nop 0
	global_load_lds_dwordx4 v[194:195], off
	v_lshl_add_u64 v[194:195], v[198:199], 0, s[94:95]
	s_mov_b32 m0, s77
	s_nop 0
	global_load_lds_dwordx4 v[194:195], off
	v_lshl_add_u64 v[194:195], v[200:201], 0, s[94:95]
	s_mov_b32 m0, s78
	s_nop 0
	global_load_lds_dwordx4 v[194:195], off
	s_waitcnt vmcnt(8)
	s_waitcnt lgkmcnt(0)
	s_barrier
	s_setprio 1
	s_waitcnt lgkmcnt(0)
	v_mfma_f32_16x16x32_bf16 v[60:63], v[104:107], v[160:163], v[60:63]
	v_mfma_f32_16x16x32_bf16 v[56:59], v[120:123], v[160:163], v[56:59]
	v_mfma_f32_16x16x32_bf16 v[44:47], v[104:107], v[168:171], v[44:47]
	v_mfma_f32_16x16x32_bf16 v[40:43], v[120:123], v[168:171], v[40:43]
	v_mfma_f32_16x16x32_bf16 v[28:31], v[104:107], v[176:179], v[28:31]
	v_mfma_f32_16x16x32_bf16 v[24:27], v[120:123], v[176:179], v[24:27]
	v_mfma_f32_16x16x32_bf16 v[12:15], v[104:107], v[184:187], v[12:15]
	v_mfma_f32_16x16x32_bf16 v[8:11], v[120:123], v[184:187], v[8:11]
	v_mfma_f32_16x16x32_bf16 v[60:63], v[112:115], v[164:167], v[60:63]
	v_mfma_f32_16x16x32_bf16 v[56:59], v[128:131], v[164:167], v[56:59]
	v_mfma_f32_16x16x32_bf16 v[44:47], v[112:115], v[172:175], v[44:47]
	v_mfma_f32_16x16x32_bf16 v[40:43], v[128:131], v[172:175], v[40:43]
	v_mfma_f32_16x16x32_bf16 v[28:31], v[112:115], v[180:183], v[28:31]
	v_mfma_f32_16x16x32_bf16 v[24:27], v[128:131], v[180:183], v[24:27]
	v_mfma_f32_16x16x32_bf16 v[12:15], v[112:115], v[188:191], v[12:15]
	v_mfma_f32_16x16x32_bf16 v[8:11], v[128:131], v[188:191], v[8:11]
	v_mfma_f32_16x16x32_bf16 v[52:55], v[136:139], v[160:163], v[52:55]
	v_mfma_f32_16x16x32_bf16 v[48:51], v[148:151], v[160:163], v[48:51]
	v_mfma_f32_16x16x32_bf16 v[36:39], v[136:139], v[168:171], v[36:39]
	v_mfma_f32_16x16x32_bf16 v[32:35], v[148:151], v[168:171], v[32:35]
	v_mfma_f32_16x16x32_bf16 v[20:23], v[136:139], v[176:179], v[20:23]
	v_mfma_f32_16x16x32_bf16 v[16:19], v[148:151], v[176:179], v[16:19]
	v_mfma_f32_16x16x32_bf16 v[4:7], v[136:139], v[184:187], v[4:7]
	v_mfma_f32_16x16x32_bf16 v[0:3], v[148:151], v[184:187], v[0:3]
	v_mfma_f32_16x16x32_bf16 v[52:55], v[140:143], v[164:167], v[52:55]
	v_mfma_f32_16x16x32_bf16 v[48:51], v[156:159], v[164:167], v[48:51]
	v_mfma_f32_16x16x32_bf16 v[36:39], v[140:143], v[172:175], v[36:39]
	v_mfma_f32_16x16x32_bf16 v[32:35], v[156:159], v[172:175], v[32:35]
	v_mfma_f32_16x16x32_bf16 v[20:23], v[140:143], v[180:183], v[20:23]
	v_mfma_f32_16x16x32_bf16 v[16:19], v[156:159], v[180:183], v[16:19]
	v_mfma_f32_16x16x32_bf16 v[4:7], v[140:143], v[188:191], v[4:7]
	v_mfma_f32_16x16x32_bf16 v[0:3], v[156:159], v[188:191], v[0:3]
	s_setprio 0
	s_barrier
	s_add_i32 s40, s40, 2
	s_add_u32 s13, s13, 0x100
	s_addc_u32 s37, s37, 0
	s_cmp_gt_u32 s40, 5
	s_mov_b64 s[20:21], s[6:7]
	s_cbranch_scc0 .LBB0_1029

; #define PG8_STAGE(bufoff, gbase, voff) do { _Pragma("unroll") for (int _i = 0; _i < 2; ++_i) \
;         __builtin_amdgcn_global_load_lds((const unsigned*)((const char*)(gbase) + (voff)[_i]), (LAS unsigned*)(lds + (bufoff) + ldsw + _i * 8192), 16, 0, 0); } while (0)
; #define PG8_LDA(dst, b, h) do { _Pragma("unroll") for (int m = 0; m < 4; ++m) _Pragma("unroll") for (int k = 0; k < 2; ++k) dst[m][k] = *(const LAS bf16x8*)(lds + PG8_SA(b, h) + aoff + m * 2048 + k * 1024); } while (0)
; #define PG8_LDB(dst, b, h) do { _Pragma("unroll") for (int n = 0; n < 2; ++n) _Pragma("unroll") for (int k = 0; k < 2; ++k) dst[n][k] = *(const LAS bf16x8*)(lds + PG8_SB(b, h) + boff + n * 2048 + k * 1024); } while (0)
; #define PG8_MMA(ai, bj, At, Bt) do { __builtin_amdgcn_s_setprio(1); _Pragma("unroll") for (int m = 0; m < 4; ++m) _Pragma("unroll") for (int n = 0; n < 2; ++n) _Pragma("unroll") for (int k = 0; k < 2; ++k) \
;         acc[ai][bj][m][n] = __builtin_amdgcn_mfma_f32_16x16x32_bf16(Bt[n][k], At[m][k], acc[ai][bj][m][n], 0, 0, 0); __builtin_amdgcn_s_setprio(0); } while (0)
; #define PG8_WAIT_V(n) asm volatile("s_waitcnt vmcnt(" #n ")" ::: "memory")
; #define PG8_WAIT_L(n) asm volatile("s_waitcnt lgkmcnt(" #n ")" ::: "memory")
; #define PG8_BAR __builtin_amdgcn_s_barrier()
; #define PG8_SCHED __builtin_amdgcn_sched_barrier(0)
; template <class Epi>
; __device__ __forceinline__ void gemm_phase(LAS unsigned char* lds, const Gemm g, const Sched& S, const Epi& E, const int tid) {
;     ...
;         const bool has_next = S.next(ui + 1, nxt);
;         const char* nA = cA; const char* nB = cB; if (has_next) S.ptrs(nxt, nA, nB);
;         for (int t = 0; t < nt; t += 2) {
;             const bool last = (t == nt - 2);
;             const char* a1 = cA + (size_t)(t + 1) * kstep;
;             const char* a2 = last ? nA : cA + (size_t)(t + 2) * kstep; const char* b2 = last ? nB : cB + (size_t)(t + 2) * kstep;
;             const char* a3 = a2 + kstep; const char* b3 = b2 + kstep;
;             PG8_LDB(B0, 0, 0); PG8_LDB(B1, 0, 1); PG8_SCHED; PG8_LDA(At, 0, 0); PG8_STAGE(PG8_SA(1, 1), a1 + hA, voffA);
;             PG8_WAIT_V(8); PG8_WAIT_L(0); PG8_BAR; PG8_MMA(0, 0, At, B0); PG8_MMA(0, 1, At, B1); PG8_BAR; PG8_SCHED;
;             PG8_LDA(At, 0, 1); PG8_STAGE(PG8_SB(0, 0), b2, voffB); PG8_STAGE(PG8_SB(0, 1), b2 + hB, voffB); PG8_STAGE(PG8_SA(0, 0), a2, voffA);
.LBB0_1142:
	s_add_u32 s17, s22, 0x100
	s_addc_u32 vcc_lo, s23, 0
	s_mov_b32 vcc_hi, -2
	s_add_u32 s22, s20, 0x100
	s_addc_u32 s23, s21, 0
	s_add_i32 s43, 0, 0x10000
	s_cmp_eq_u32 vcc_hi, 12
	s_cselect_b32 s75, s7, s23
	s_cselect_b32 s74, s6, s22
	s_cselect_b32 s73, s19, vcc_lo
	s_cselect_b32 s72, s18, s17
	s_add_i32 s44, 0, 0x14000
	v_add_u32_e32 v100, s43, v159
	v_add_u32_e32 v170, s44, v159
	ds_read_b128 v[64:67], v100
	ds_read_b128 v[68:71], v100 offset:1024
	ds_read_b128 v[72:75], v100 offset:2048
	ds_read_b128 v[100:103], v100 offset:3072
	ds_read_b128 v[154:157], v170
	ds_read_b128 v[162:165], v170 offset:1024
	ds_read_b128 v[166:169], v170 offset:2048
	ds_read_b128 v[170:173], v170 offset:3072
	v_lshl_add_u64 v[190:191], s[20:21], 0, v[150:151]
	s_add_i32 m0, s80, 0xc000
	ds_read_b128 v[174:177], v161
	ds_read_b128 v[178:181], v161 offset:1024
	ds_read_b128 v[182:185], v161 offset:2048
	ds_read_b128 v[186:189], v161 offset:3072
	ds_read_b128 v[194:197], v161 offset:4096
	ds_read_b128 v[198:201], v161 offset:5120
	ds_read_b128 v[204:207], v161 offset:6144
	ds_read_b128 v[208:211], v161 offset:7168
	global_load_lds_dwordx4 v[190:191], off
	v_lshl_add_u64 v[190:191], s[20:21], 0, v[152:153]
	s_add_i32 m0, s80, 0xe000
	s_nop 0
	global_load_lds_dwordx4 v[190:191], off
	s_waitcnt vmcnt(8)
	s_waitcnt lgkmcnt(0)
	s_barrier
	s_setprio 1
	s_waitcnt lgkmcnt(0)
	v_mfma_f32_16x16x32_bf16 v[140:143], v[64:67], v[174:177], 0
	v_mfma_f32_16x16x32_bf16 v[136:139], v[72:75], v[174:177], 0
	v_mfma_f32_16x16x32_bf16 v[132:135], v[64:67], v[182:185], 0
	v_mfma_f32_16x16x32_bf16 v[120:123], v[72:75], v[182:185], 0
	v_mfma_f32_16x16x32_bf16 v[108:111], v[64:67], v[194:197], 0
	v_mfma_f32_16x16x32_bf16 v[104:107], v[72:75], v[194:197], 0
	v_mfma_f32_16x16x32_bf16 v[96:99], v[64:67], v[204:207], 0
	v_mfma_f32_16x16x32_bf16 v[84:87], v[72:75], v[204:207], 0
	v_mfma_f32_16x16x32_bf16 v[140:143], v[68:71], v[178:181], v[140:143]
	v_mfma_f32_16x16x32_bf16 v[136:139], v[100:103], v[178:181], v[136:139]
	v_mfma_f32_16x16x32_bf16 v[132:135], v[68:71], v[186:189], v[132:135]
	v_mfma_f32_16x16x32_bf16 v[120:123], v[100:103], v[186:189], v[120:123]
	v_mfma_f32_16x16x32_bf16 v[108:111], v[68:71], v[198:201], v[108:111]
	v_mfma_f32_16x16x32_bf16 v[104:107], v[100:103], v[198:201], v[104:107]
	v_mfma_f32_16x16x32_bf16 v[96:99], v[68:71], v[208:211], v[96:99]
	v_mfma_f32_16x16x32_bf16 v[84:87], v[100:103], v[208:211], v[84:87]
	v_mfma_f32_16x16x32_bf16 v[128:131], v[154:157], v[174:177], 0
	v_mfma_f32_16x16x32_bf16 v[124:127], v[166:169], v[174:177], 0
	v_mfma_f32_16x16x32_bf16 v[116:119], v[154:157], v[182:185], 0
	v_mfma_f32_16x16x32_bf16 v[112:115], v[166:169], v[182:185], 0
	v_mfma_f32_16x16x32_bf16 v[92:95], v[154:157], v[194:197], 0
	v_mfma_f32_16x16x32_bf16 v[88:91], v[166:169], v[194:197], 0
	v_mfma_f32_16x16x32_bf16 v[80:83], v[154:157], v[204:207], 0
	v_mfma_f32_16x16x32_bf16 v[76:79], v[166:169], v[204:207], 0
	v_mfma_f32_16x16x32_bf16 v[128:131], v[162:165], v[178:181], v[128:131]
	v_mfma_f32_16x16x32_bf16 v[124:127], v[170:173], v[178:181], v[124:127]
	v_mfma_f32_16x16x32_bf16 v[116:119], v[162:165], v[186:189], v[116:119]
	v_mfma_f32_16x16x32_bf16 v[112:115], v[170:173], v[186:189], v[112:115]
	v_mfma_f32_16x16x32_bf16 v[92:95], v[162:165], v[198:201], v[92:95]
	v_mfma_f32_16x16x32_bf16 v[88:91], v[170:173], v[198:201], v[88:91]
	v_mfma_f32_16x16x32_bf16 v[80:83], v[162:165], v[208:211], v[80:83]
	v_mfma_f32_16x16x32_bf16 v[76:79], v[170:173], v[208:211], v[76:79]
	s_setprio 0
	s_barrier
	s_add_i32 s20, s43, s76
	v_lshl_add_u64 v[190:191], s[72:73], 0, v[192:193]
	s_mov_b32 m0, s20
	ds_read_b128 v[174:177], v161 offset:16384
	ds_read_b128 v[178:181], v161 offset:17408
	ds_read_b128 v[182:185], v161 offset:18432
	ds_read_b128 v[186:189], v161 offset:19456
	ds_read_b128 v[194:197], v161 offset:20480
	ds_read_b128 v[198:201], v161 offset:21504
	ds_read_b128 v[204:207], v161 offset:22528
	ds_read_b128 v[208:211], v161 offset:23552
	global_load_lds_dwordx4 v[190:191], off
	s_add_i32 m0, s20, 0x2000
	s_add_u32 s20, s72, 0x40000
	v_lshl_add_u64 v[212:213], s[72:73], 0, v[144:145]
	s_addc_u32 s21, s73, 0
	s_add_i32 s43, s44, s76
	global_load_lds_dwordx4 v[212:213], off
	v_lshl_add_u64 v[214:215], s[20:21], 0, v[192:193]
	s_mov_b32 m0, s43
	v_lshl_add_u64 v[216:217], s[74:75], 0, v[146:147]
	global_load_lds_dwordx4 v[214:215], off
	v_lshl_add_u64 v[214:215], s[20:21], 0, v[144:145]
	s_add_i32 m0, s43, 0x2000
	s_nop 0
	global_load_lds_dwordx4 v[214:215], off
	v_lshl_add_u64 v[214:215], s[74:75], 0, v[148:149]
	s_mov_b32 m0, s80
	s_nop 0
	global_load_lds_dwordx4 v[214:215], off
	s_mov_b32 m0, s81
	s_nop 0
	global_load_lds_dwordx4 v[216:217], off
	s_waitcnt vmcnt(8)
	s_waitcnt lgkmcnt(0)
	s_barrier
; #define PG8_STAGE(bufoff, gbase, voff) do { _Pragma("unroll") for (int _i = 0; _i < 2; ++_i) \
;         __builtin_amdgcn_global_load_lds((const unsigned*)((const char*)(gbase) + (voff)[_i]), (LAS unsigned*)(lds + (bufoff) + ldsw + _i * 8192), 16, 0, 0); } while (0)
; #define PG8_LDA(dst, b, h) do { _Pragma("unroll") for (int m = 0; m < 4; ++m) _Pragma("unroll") for (int k = 0; k < 2; ++k) dst[m][k] = *(const LAS bf16x8*)(lds + PG8_SA(b, h) + aoff + m * 2048 + k * 1024); } while (0)
; #define PG8_LDB(dst, b, h) do { _Pragma("unroll") for (int n = 0; n < 2; ++n) _Pragma("unroll") for (int k = 0; k < 2; ++k) dst[n][k] = *(const LAS bf16x8*)(lds + PG8_SB(b, h) + boff + n * 2048 + k * 1024); } while (0)
; #define PG8_MMA(ai, bj, At, Bt) do { __builtin_amdgcn_s_setprio(1); _Pragma("unroll") for (int m = 0; m < 4; ++m) _Pragma("unroll") for (int n = 0; n < 2; ++n) _Pragma("unroll") for (int k = 0; k < 2; ++k) \
;         acc[ai][bj][m][n] = __builtin_amdgcn_mfma_f32_16x16x32_bf16(Bt[n][k], At[m][k], acc[ai][bj][m][n], 0, 0, 0); __builtin_amdgcn_s_setprio(0); } while (0)
; #define PG8_WAIT_V(n) asm volatile("s_waitcnt vmcnt(" #n ")" ::: "memory")
; #define PG8_WAIT_L(n) asm volatile("s_waitcnt lgkmcnt(" #n ")" ::: "memory")
; #define PG8_BAR __builtin_amdgcn_s_barrier()
; #define PG8_SCHED __builtin_amdgcn_sched_barrier(0)
; template <class Epi>
; __device__ __forceinline__ void gemm_phase(LAS unsigned char* lds, const Gemm g, const Sched& S, const Epi& E, const int tid) {
;     ...
;             PG8_WAIT_V(8); PG8_WAIT_L(0); PG8_BAR; PG8_MMA(1, 0, At, B0); PG8_MMA(1, 1, At, B1); PG8_BAR; PG8_SCHED;
;             PG8_LDB(B0, 1, 0); PG8_LDB(B1, 1, 1); PG8_SCHED; PG8_LDA(At, 1, 0); PG8_STAGE(PG8_SA(0, 1), a2 + hA, voffA);
;             PG8_WAIT_V(8); PG8_WAIT_L(0); PG8_BAR; PG8_MMA(0, 0, At, B0); PG8_MMA(0, 1, At, B1); PG8_BAR; PG8_SCHED;
	s_setprio 1
	s_waitcnt lgkmcnt(0)
	v_mfma_f32_16x16x32_bf16 v[60:63], v[64:67], v[174:177], 0
	v_mfma_f32_16x16x32_bf16 v[56:59], v[72:75], v[174:177], 0
	v_mfma_f32_16x16x32_bf16 v[52:55], v[64:67], v[182:185], 0
	v_mfma_f32_16x16x32_bf16 v[40:43], v[72:75], v[182:185], 0
	v_mfma_f32_16x16x32_bf16 v[28:31], v[64:67], v[194:197], 0
	v_mfma_f32_16x16x32_bf16 v[24:27], v[72:75], v[194:197], 0
	v_mfma_f32_16x16x32_bf16 v[20:23], v[64:67], v[204:207], 0
	v_mfma_f32_16x16x32_bf16 v[8:11], v[72:75], v[204:207], 0
	v_mfma_f32_16x16x32_bf16 v[60:63], v[68:71], v[178:181], v[60:63]
	v_mfma_f32_16x16x32_bf16 v[56:59], v[100:103], v[178:181], v[56:59]
	v_mfma_f32_16x16x32_bf16 v[52:55], v[68:71], v[186:189], v[52:55]
	v_mfma_f32_16x16x32_bf16 v[40:43], v[100:103], v[186:189], v[40:43]
	v_mfma_f32_16x16x32_bf16 v[28:31], v[68:71], v[198:201], v[28:31]
	v_mfma_f32_16x16x32_bf16 v[24:27], v[100:103], v[198:201], v[24:27]
	v_mfma_f32_16x16x32_bf16 v[20:23], v[68:71], v[208:211], v[20:23]
	v_mfma_f32_16x16x32_bf16 v[8:11], v[100:103], v[208:211], v[8:11]
	v_mfma_f32_16x16x32_bf16 v[48:51], v[154:157], v[174:177], 0
	v_mfma_f32_16x16x32_bf16 v[44:47], v[166:169], v[174:177], 0
	v_mfma_f32_16x16x32_bf16 v[36:39], v[154:157], v[182:185], 0
	v_mfma_f32_16x16x32_bf16 v[32:35], v[166:169], v[182:185], 0
	v_mfma_f32_16x16x32_bf16 v[16:19], v[154:157], v[194:197], 0
	v_mfma_f32_16x16x32_bf16 v[12:15], v[166:169], v[194:197], 0
	v_mfma_f32_16x16x32_bf16 v[4:7], v[154:157], v[204:207], 0
	v_mfma_f32_16x16x32_bf16 v[0:3], v[166:169], v[204:207], 0
	v_mfma_f32_16x16x32_bf16 v[48:51], v[162:165], v[178:181], v[48:51]
	v_mfma_f32_16x16x32_bf16 v[44:47], v[170:173], v[178:181], v[44:47]
	v_mfma_f32_16x16x32_bf16 v[36:39], v[162:165], v[186:189], v[36:39]
	v_mfma_f32_16x16x32_bf16 v[32:35], v[170:173], v[186:189], v[32:35]
	v_mfma_f32_16x16x32_bf16 v[16:19], v[162:165], v[198:201], v[16:19]
	v_mfma_f32_16x16x32_bf16 v[12:15], v[170:173], v[198:201], v[12:15]
	v_mfma_f32_16x16x32_bf16 v[4:7], v[162:165], v[208:211], v[4:7]
	v_mfma_f32_16x16x32_bf16 v[0:3], v[170:173], v[208:211], v[0:3]
	s_setprio 0
	s_barrier
	s_add_i32 s43, 0, 0x18000
	s_add_i32 s44, 0, 0x1c000
	v_add_u32_e32 v100, s43, v159
	v_add_u32_e32 v170, s44, v159
	ds_read_b128 v[64:67], v100
	ds_read_b128 v[68:71], v100 offset:1024
	ds_read_b128 v[72:75], v100 offset:2048
	ds_read_b128 v[100:103], v100 offset:3072
	ds_read_b128 v[154:157], v170
	ds_read_b128 v[162:165], v170 offset:1024
	ds_read_b128 v[166:169], v170 offset:2048
	ds_read_b128 v[170:173], v170 offset:3072
	s_add_u32 s20, s74, 0x120000
	s_addc_u32 s21, s75, 0
	s_mov_b32 m0, s3
	v_lshl_add_u64 v[218:219], s[20:21], 0, v[148:149]
	ds_read_b128 v[174:177], v161 offset:32768
	ds_read_b128 v[178:181], v161 offset:33792
	ds_read_b128 v[182:185], v161 offset:34816
	ds_read_b128 v[186:189], v161 offset:35840
	ds_read_b128 v[194:197], v161 offset:36864
	ds_read_b128 v[198:201], v161 offset:37888
	ds_read_b128 v[204:207], v161 offset:38912
	ds_read_b128 v[208:211], v161 offset:39936
	global_load_lds_dwordx4 v[218:219], off
	v_lshl_add_u64 v[218:219], s[20:21], 0, v[146:147]
	s_mov_b32 m0, s34
	s_nop 0
	global_load_lds_dwordx4 v[218:219], off
	s_waitcnt vmcnt(8)
	s_waitcnt lgkmcnt(0)
	s_barrier
	s_setprio 1
	s_waitcnt lgkmcnt(0)
	v_mfma_f32_16x16x32_bf16 v[140:143], v[64:67], v[174:177], v[140:143]
	v_mfma_f32_16x16x32_bf16 v[136:139], v[72:75], v[174:177], v[136:139]
	v_mfma_f32_16x16x32_bf16 v[132:135], v[64:67], v[182:185], v[132:135]
	v_mfma_f32_16x16x32_bf16 v[120:123], v[72:75], v[182:185], v[120:123]
	v_mfma_f32_16x16x32_bf16 v[108:111], v[64:67], v[194:197], v[108:111]
	v_mfma_f32_16x16x32_bf16 v[104:107], v[72:75], v[194:197], v[104:107]
	v_mfma_f32_16x16x32_bf16 v[96:99], v[64:67], v[204:207], v[96:99]
	v_mfma_f32_16x16x32_bf16 v[84:87], v[72:75], v[204:207], v[84:87]
	v_mfma_f32_16x16x32_bf16 v[140:143], v[68:71], v[178:181], v[140:143]
	v_mfma_f32_16x16x32_bf16 v[136:139], v[100:103], v[178:181], v[136:139]
	v_mfma_f32_16x16x32_bf16 v[132:135], v[68:71], v[186:189], v[132:135]
	v_mfma_f32_16x16x32_bf16 v[120:123], v[100:103], v[186:189], v[120:123]
	v_mfma_f32_16x16x32_bf16 v[108:111], v[68:71], v[198:201], v[108:111]
	v_mfma_f32_16x16x32_bf16 v[104:107], v[100:103], v[198:201], v[104:107]
	v_mfma_f32_16x16x32_bf16 v[96:99], v[68:71], v[208:211], v[96:99]
	v_mfma_f32_16x16x32_bf16 v[84:87], v[100:103], v[208:211], v[84:87]
	v_mfma_f32_16x16x32_bf16 v[128:131], v[154:157], v[174:177], v[128:131]
	v_mfma_f32_16x16x32_bf16 v[124:127], v[166:169], v[174:177], v[124:127]
	v_mfma_f32_16x16x32_bf16 v[116:119], v[154:157], v[182:185], v[116:119]
	v_mfma_f32_16x16x32_bf16 v[112:115], v[166:169], v[182:185], v[112:115]
	v_mfma_f32_16x16x32_bf16 v[92:95], v[154:157], v[194:197], v[92:95]
	v_mfma_f32_16x16x32_bf16 v[88:91], v[166:169], v[194:197], v[88:91]
	v_mfma_f32_16x16x32_bf16 v[80:83], v[154:157], v[204:207], v[80:83]
	v_mfma_f32_16x16x32_bf16 v[76:79], v[166:169], v[204:207], v[76:79]
	v_mfma_f32_16x16x32_bf16 v[128:131], v[162:165], v[178:181], v[128:131]
	v_mfma_f32_16x16x32_bf16 v[124:127], v[170:173], v[178:181], v[124:127]
	v_mfma_f32_16x16x32_bf16 v[116:119], v[162:165], v[186:189], v[116:119]
	v_mfma_f32_16x16x32_bf16 v[112:115], v[170:173], v[186:189], v[112:115]
	v_mfma_f32_16x16x32_bf16 v[92:95], v[162:165], v[198:201], v[92:95]
	v_mfma_f32_16x16x32_bf16 v[88:91], v[170:173], v[198:201], v[88:91]
	v_mfma_f32_16x16x32_bf16 v[80:83], v[162:165], v[208:211], v[80:83]
	v_mfma_f32_16x16x32_bf16 v[76:79], v[170:173], v[208:211], v[76:79]
	s_setprio 0
	s_barrier
; #define PG8_STAGE(bufoff, gbase, voff) do { _Pragma("unroll") for (int _i = 0; _i < 2; ++_i) \
;         __builtin_amdgcn_global_load_lds((const unsigned*)((const char*)(gbase) + (voff)[_i]), (LAS unsigned*)(lds + (bufoff) + ldsw + _i * 8192), 16, 0, 0); } while (0)
; #define PG8_LDA(dst, b, h) do { _Pragma("unroll") for (int m = 0; m < 4; ++m) _Pragma("unroll") for (int k = 0; k < 2; ++k) dst[m][k] = *(const LAS bf16x8*)(lds + PG8_SA(b, h) + aoff + m * 2048 + k * 1024); } while (0)
; #define PG8_LDB(dst, b, h) do { _Pragma("unroll") for (int n = 0; n < 2; ++n) _Pragma("unroll") for (int k = 0; k < 2; ++k) dst[n][k] = *(const LAS bf16x8*)(lds + PG8_SB(b, h) + boff + n * 2048 + k * 1024); } while (0)
; #define PG8_WAIT_V(n) asm volatile("s_waitcnt vmcnt(" #n ")" ::: "memory")
; #define PG8_BAR __builtin_amdgcn_s_barrier()
; template <class Epi>
; __device__ __forceinline__ void gemm_phase(LAS unsigned char* lds, const Gemm g, const Sched& S, const Epi& E, const int tid) {
;     ...
;         for (int t = 0; t < nt; t += 2) {
;             const bool last = (t == nt - 2);
;             const char* a1 = cA + (size_t)(t + 1) * kstep;
;             const char* a2 = last ? nA : cA + (size_t)(t + 2) * kstep; const char* b2 = last ? nB : cB + (size_t)(t + 2) * kstep;
;             const char* a3 = a2 + kstep; const char* b3 = b2 + kstep;
;             PG8_LDB(B0, 0, 0); PG8_LDB(B1, 0, 1); PG8_SCHED; PG8_LDA(At, 0, 0); PG8_STAGE(PG8_SA(1, 1), a1 + hA, voffA);
;             PG8_WAIT_V(8); PG8_WAIT_L(0); PG8_BAR; PG8_MMA(0, 0, At, B0); PG8_MMA(0, 1, At, B1); PG8_BAR; PG8_SCHED;
;             PG8_LDA(At, 0, 1); PG8_STAGE(PG8_SB(0, 0), b2, voffB); PG8_STAGE(PG8_SB(0, 1), b2 + hB, voffB); PG8_STAGE(PG8_SA(0, 0), a2, voffA);
;             PG8_WAIT_V(8); PG8_WAIT_L(0); PG8_BAR; PG8_MMA(1, 0, At, B0); PG8_MMA(1, 1, At, B1); PG8_BAR; PG8_SCHED;
;             PG8_LDB(B0, 1, 0); PG8_LDB(B1, 1, 1); PG8_SCHED; PG8_LDA(At, 1, 0); PG8_STAGE(PG8_SA(0, 1), a2 + hA, voffA);
;             PG8_WAIT_V(8); PG8_WAIT_L(0); PG8_BAR; PG8_MMA(0, 0, At, B0); PG8_MMA(0, 1, At, B1); PG8_BAR; PG8_SCHED;
;             PG8_LDA(At, 1, 1); PG8_STAGE(PG8_SB(1, 0), b3, voffB); PG8_STAGE(PG8_SB(1, 1), b3 + hB, voffB); PG8_STAGE(PG8_SA(1, 0), a3, voffA);
;             PG8_WAIT_V(8); PG8_WAIT_L(0); PG8_BAR; PG8_MMA(1, 0, At, B0); PG8_MMA(1, 1, At, B1); PG8_BAR; PG8_SCHED;
;         }
	s_add_i32 s20, s43, s76
	v_lshl_add_u64 v[190:191], v[190:191], 0, s[94:95]
	s_mov_b32 m0, s20
	ds_read_b128 v[174:177], v161 offset:49152
	ds_read_b128 v[178:181], v161 offset:50176
	ds_read_b128 v[182:185], v161 offset:51200
	ds_read_b128 v[186:189], v161 offset:52224
	ds_read_b128 v[194:197], v161 offset:53248
	ds_read_b128 v[198:201], v161 offset:54272
	ds_read_b128 v[204:207], v161 offset:55296
	ds_read_b128 v[208:211], v161 offset:56320
	global_load_lds_dwordx4 v[190:191], off
	s_add_i32 m0, s20, 0x2000
	s_add_u32 s20, s72, 0x40080
	v_lshl_add_u64 v[190:191], v[212:213], 0, s[94:95]
	s_addc_u32 s21, s73, 0
	s_add_i32 s43, s44, s76
	global_load_lds_dwordx4 v[190:191], off
	v_lshl_add_u64 v[190:191], s[20:21], 0, v[192:193]
	s_mov_b32 m0, s43
	s_nop 0
	global_load_lds_dwordx4 v[190:191], off
	v_lshl_add_u64 v[190:191], s[20:21], 0, v[144:145]
	s_add_i32 m0, s43, 0x2000
	s_nop 0
	global_load_lds_dwordx4 v[190:191], off
	v_lshl_add_u64 v[190:191], v[214:215], 0, s[94:95]
	s_mov_b32 m0, s47
	s_nop 0
	global_load_lds_dwordx4 v[190:191], off
	v_lshl_add_u64 v[190:191], v[216:217], 0, s[94:95]
	s_mov_b32 m0, s40
	s_nop 0
	global_load_lds_dwordx4 v[190:191], off
	s_waitcnt vmcnt(8)
	s_waitcnt lgkmcnt(0)
	s_barrier
	s_setprio 1
	s_waitcnt lgkmcnt(0)
	v_mfma_f32_16x16x32_bf16 v[60:63], v[64:67], v[174:177], v[60:63]
	v_mfma_f32_16x16x32_bf16 v[56:59], v[72:75], v[174:177], v[56:59]
	v_mfma_f32_16x16x32_bf16 v[52:55], v[64:67], v[182:185], v[52:55]
	v_mfma_f32_16x16x32_bf16 v[40:43], v[72:75], v[182:185], v[40:43]
	v_mfma_f32_16x16x32_bf16 v[28:31], v[64:67], v[194:197], v[28:31]
	v_mfma_f32_16x16x32_bf16 v[24:27], v[72:75], v[194:197], v[24:27]
	v_mfma_f32_16x16x32_bf16 v[20:23], v[64:67], v[204:207], v[20:23]
	v_mfma_f32_16x16x32_bf16 v[8:11], v[72:75], v[204:207], v[8:11]
	v_mfma_f32_16x16x32_bf16 v[60:63], v[68:71], v[178:181], v[60:63]
	v_mfma_f32_16x16x32_bf16 v[56:59], v[100:103], v[178:181], v[56:59]
	v_mfma_f32_16x16x32_bf16 v[52:55], v[68:71], v[186:189], v[52:55]
	v_mfma_f32_16x16x32_bf16 v[40:43], v[100:103], v[186:189], v[40:43]
	v_mfma_f32_16x16x32_bf16 v[28:31], v[68:71], v[198:201], v[28:31]
	v_mfma_f32_16x16x32_bf16 v[24:27], v[100:103], v[198:201], v[24:27]
	v_mfma_f32_16x16x32_bf16 v[20:23], v[68:71], v[208:211], v[20:23]
	v_mfma_f32_16x16x32_bf16 v[8:11], v[100:103], v[208:211], v[8:11]
	v_mfma_f32_16x16x32_bf16 v[48:51], v[154:157], v[174:177], v[48:51]
	v_mfma_f32_16x16x32_bf16 v[44:47], v[166:169], v[174:177], v[44:47]
	v_mfma_f32_16x16x32_bf16 v[36:39], v[154:157], v[182:185], v[36:39]
	v_mfma_f32_16x16x32_bf16 v[32:35], v[166:169], v[182:185], v[32:35]
	v_mfma_f32_16x16x32_bf16 v[16:19], v[154:157], v[194:197], v[16:19]
	v_mfma_f32_16x16x32_bf16 v[12:15], v[166:169], v[194:197], v[12:15]
	v_mfma_f32_16x16x32_bf16 v[4:7], v[154:157], v[204:207], v[4:7]
	v_mfma_f32_16x16x32_bf16 v[0:3], v[166:169], v[204:207], v[0:3]
	v_mfma_f32_16x16x32_bf16 v[48:51], v[162:165], v[178:181], v[48:51]
	v_mfma_f32_16x16x32_bf16 v[44:47], v[170:173], v[178:181], v[44:47]
	v_mfma_f32_16x16x32_bf16 v[36:39], v[162:165], v[186:189], v[36:39]
	v_mfma_f32_16x16x32_bf16 v[32:35], v[170:173], v[186:189], v[32:35]
	v_mfma_f32_16x16x32_bf16 v[16:19], v[162:165], v[198:201], v[16:19]
	v_mfma_f32_16x16x32_bf16 v[12:15], v[170:173], v[198:201], v[12:15]
	v_mfma_f32_16x16x32_bf16 v[4:7], v[162:165], v[208:211], v[4:7]
	v_mfma_f32_16x16x32_bf16 v[0:3], v[170:173], v[208:211], v[0:3]
	s_setprio 0
	s_barrier
	s_add_i32 vcc_hi, vcc_hi, 2
	s_add_u32 s17, s17, 0x100
	s_addc_u32 vcc_lo, vcc_lo, 0
	s_cmp_gt_u32 vcc_hi, 13
	s_mov_b64 s[20:21], s[22:23]
	s_cbranch_scc1 .Lgk_exit_3
.LBB0_1143:
	s_add_u32 s22, s20, 0x100
	s_addc_u32 s23, s21, 0
	s_add_i32 s43, 0, 0x10000
	s_cmp_eq_u32 vcc_hi, 12
	s_cselect_b32 s75, s7, s23
	s_cselect_b32 s74, s6, s22
	s_cselect_b32 s73, s19, vcc_lo
	s_cselect_b32 s72, s18, s17
	s_add_i32 s44, 0, 0x14000
	v_add_u32_e32 v100, s43, v159
	v_add_u32_e32 v170, s44, v159
	ds_read_b128 v[64:67], v100
	ds_read_b128 v[68:71], v100 offset:1024
	ds_read_b128 v[72:75], v100 offset:2048
	ds_read_b128 v[100:103], v100 offset:3072
	ds_read_b128 v[154:157], v170
	ds_read_b128 v[162:165], v170 offset:1024
	ds_read_b128 v[166:169], v170 offset:2048
	ds_read_b128 v[170:173], v170 offset:3072
	v_lshl_add_u64 v[190:191], s[20:21], 0, v[150:151]
	s_add_i32 m0, s80, 0xc000
	ds_read_b128 v[174:177], v161
	ds_read_b128 v[178:181], v161 offset:1024
	ds_read_b128 v[182:185], v161 offset:2048
	ds_read_b128 v[186:189], v161 offset:3072
	ds_read_b128 v[194:197], v161 offset:4096
	ds_read_b128 v[198:201], v161 offset:5120
	ds_read_b128 v[204:207], v161 offset:6144
	ds_read_b128 v[208:211], v161 offset:7168
	global_load_lds_dwordx4 v[190:191], off
	v_lshl_add_u64 v[190:191], s[20:21], 0, v[152:153]
	s_add_i32 m0, s80, 0xe000
	s_nop 0
	global_load_lds_dwordx4 v[190:191], off
	s_waitcnt vmcnt(8)
	s_waitcnt lgkmcnt(0)
	s_barrier
; #define PG8_STAGE(bufoff, gbase, voff) do { _Pragma("unroll") for (int _i = 0; _i < 2; ++_i) \
;         __builtin_amdgcn_global_load_lds((const unsigned*)((const char*)(gbase) + (voff)[_i]), (LAS unsigned*)(lds + (bufoff) + ldsw + _i * 8192), 16, 0, 0); } while (0)
; #define PG8_LDA(dst, b, h) do { _Pragma("unroll") for (int m = 0; m < 4; ++m) _Pragma("unroll") for (int k = 0; k < 2; ++k) dst[m][k] = *(const LAS bf16x8*)(lds + PG8_SA(b, h) + aoff + m * 2048 + k * 1024); } while (0)
; #define PG8_MMA(ai, bj, At, Bt) do { __builtin_amdgcn_s_setprio(1); _Pragma("unroll") for (int m = 0; m < 4; ++m) _Pragma("unroll") for (int n = 0; n < 2; ++n) _Pragma("unroll") for (int k = 0; k < 2; ++k) \
;         acc[ai][bj][m][n] = __builtin_amdgcn_mfma_f32_16x16x32_bf16(Bt[n][k], At[m][k], acc[ai][bj][m][n], 0, 0, 0); __builtin_amdgcn_s_setprio(0); } while (0)
; #define PG8_WAIT_V(n) asm volatile("s_waitcnt vmcnt(" #n ")" ::: "memory")
; #define PG8_WAIT_L(n) asm volatile("s_waitcnt lgkmcnt(" #n ")" ::: "memory")
; #define PG8_BAR __builtin_amdgcn_s_barrier()
; #define PG8_SCHED __builtin_amdgcn_sched_barrier(0)
; template <class Epi>
; __device__ __forceinline__ void gemm_phase(LAS unsigned char* lds, const Gemm g, const Sched& S, const Epi& E, const int tid) {
;     ...
;             PG8_WAIT_V(8); PG8_WAIT_L(0); PG8_BAR; PG8_MMA(0, 0, At, B0); PG8_MMA(0, 1, At, B1); PG8_BAR; PG8_SCHED;
;             PG8_LDA(At, 0, 1); PG8_STAGE(PG8_SB(0, 0), b2, voffB); PG8_STAGE(PG8_SB(0, 1), b2 + hB, voffB); PG8_STAGE(PG8_SA(0, 0), a2, voffA);
;             PG8_WAIT_V(8); PG8_WAIT_L(0); PG8_BAR; PG8_MMA(1, 0, At, B0); PG8_MMA(1, 1, At, B1); PG8_BAR; PG8_SCHED;
	s_setprio 1
	s_waitcnt lgkmcnt(0)
	v_mfma_f32_16x16x32_bf16 v[140:143], v[64:67], v[174:177], v[140:143]
	v_mfma_f32_16x16x32_bf16 v[136:139], v[72:75], v[174:177], v[136:139]
	v_mfma_f32_16x16x32_bf16 v[132:135], v[64:67], v[182:185], v[132:135]
	v_mfma_f32_16x16x32_bf16 v[120:123], v[72:75], v[182:185], v[120:123]
	v_mfma_f32_16x16x32_bf16 v[108:111], v[64:67], v[194:197], v[108:111]
	v_mfma_f32_16x16x32_bf16 v[104:107], v[72:75], v[194:197], v[104:107]
	v_mfma_f32_16x16x32_bf16 v[96:99], v[64:67], v[204:207], v[96:99]
	v_mfma_f32_16x16x32_bf16 v[84:87], v[72:75], v[204:207], v[84:87]
	v_mfma_f32_16x16x32_bf16 v[140:143], v[68:71], v[178:181], v[140:143]
	v_mfma_f32_16x16x32_bf16 v[136:139], v[100:103], v[178:181], v[136:139]
	v_mfma_f32_16x16x32_bf16 v[132:135], v[68:71], v[186:189], v[132:135]
	v_mfma_f32_16x16x32_bf16 v[120:123], v[100:103], v[186:189], v[120:123]
	v_mfma_f32_16x16x32_bf16 v[108:111], v[68:71], v[198:201], v[108:111]
	v_mfma_f32_16x16x32_bf16 v[104:107], v[100:103], v[198:201], v[104:107]
	v_mfma_f32_16x16x32_bf16 v[96:99], v[68:71], v[208:211], v[96:99]
	v_mfma_f32_16x16x32_bf16 v[84:87], v[100:103], v[208:211], v[84:87]
	v_mfma_f32_16x16x32_bf16 v[128:131], v[154:157], v[174:177], v[128:131]
	v_mfma_f32_16x16x32_bf16 v[124:127], v[166:169], v[174:177], v[124:127]
	v_mfma_f32_16x16x32_bf16 v[116:119], v[154:157], v[182:185], v[116:119]
	v_mfma_f32_16x16x32_bf16 v[112:115], v[166:169], v[182:185], v[112:115]
	v_mfma_f32_16x16x32_bf16 v[92:95], v[154:157], v[194:197], v[92:95]
	v_mfma_f32_16x16x32_bf16 v[88:91], v[166:169], v[194:197], v[88:91]
	v_mfma_f32_16x16x32_bf16 v[80:83], v[154:157], v[204:207], v[80:83]
	v_mfma_f32_16x16x32_bf16 v[76:79], v[166:169], v[204:207], v[76:79]
	v_mfma_f32_16x16x32_bf16 v[128:131], v[162:165], v[178:181], v[128:131]
	v_mfma_f32_16x16x32_bf16 v[124:127], v[170:173], v[178:181], v[124:127]
	v_mfma_f32_16x16x32_bf16 v[116:119], v[162:165], v[186:189], v[116:119]
	v_mfma_f32_16x16x32_bf16 v[112:115], v[170:173], v[186:189], v[112:115]
	v_mfma_f32_16x16x32_bf16 v[92:95], v[162:165], v[198:201], v[92:95]
	v_mfma_f32_16x16x32_bf16 v[88:91], v[170:173], v[198:201], v[88:91]
	v_mfma_f32_16x16x32_bf16 v[80:83], v[162:165], v[208:211], v[80:83]
	v_mfma_f32_16x16x32_bf16 v[76:79], v[170:173], v[208:211], v[76:79]
	s_setprio 0
	s_barrier
	s_add_i32 s20, s43, s76
	v_lshl_add_u64 v[190:191], s[72:73], 0, v[192:193]
	s_mov_b32 m0, s20
	ds_read_b128 v[174:177], v161 offset:16384
	ds_read_b128 v[178:181], v161 offset:17408
	ds_read_b128 v[182:185], v161 offset:18432
	ds_read_b128 v[186:189], v161 offset:19456
	ds_read_b128 v[194:197], v161 offset:20480
	ds_read_b128 v[198:201], v161 offset:21504
	ds_read_b128 v[204:207], v161 offset:22528
	ds_read_b128 v[208:211], v161 offset:23552
	global_load_lds_dwordx4 v[190:191], off
	s_add_i32 m0, s20, 0x2000
	s_add_u32 s20, s72, 0x40000
	v_lshl_add_u64 v[212:213], s[72:73], 0, v[144:145]
	s_addc_u32 s21, s73, 0
	s_add_i32 s43, s44, s76
	global_load_lds_dwordx4 v[212:213], off
	v_lshl_add_u64 v[214:215], s[20:21], 0, v[192:193]
	s_mov_b32 m0, s43
	v_lshl_add_u64 v[216:217], s[74:75], 0, v[146:147]
	global_load_lds_dwordx4 v[214:215], off
	v_lshl_add_u64 v[214:215], s[20:21], 0, v[144:145]
	s_add_i32 m0, s43, 0x2000
	s_nop 0
	global_load_lds_dwordx4 v[214:215], off
	v_lshl_add_u64 v[214:215], s[74:75], 0, v[148:149]
	s_mov_b32 m0, s80
	s_nop 0
	global_load_lds_dwordx4 v[214:215], off
	s_mov_b32 m0, s81
	s_nop 0
	global_load_lds_dwordx4 v[216:217], off
	s_waitcnt vmcnt(8)
	s_waitcnt lgkmcnt(0)
	s_barrier
	s_setprio 1
	s_waitcnt lgkmcnt(0)
	v_mfma_f32_16x16x32_bf16 v[60:63], v[64:67], v[174:177], v[60:63]
	v_mfma_f32_16x16x32_bf16 v[56:59], v[72:75], v[174:177], v[56:59]
	v_mfma_f32_16x16x32_bf16 v[52:55], v[64:67], v[182:185], v[52:55]
	v_mfma_f32_16x16x32_bf16 v[40:43], v[72:75], v[182:185], v[40:43]
	v_mfma_f32_16x16x32_bf16 v[28:31], v[64:67], v[194:197], v[28:31]
	v_mfma_f32_16x16x32_bf16 v[24:27], v[72:75], v[194:197], v[24:27]
	v_mfma_f32_16x16x32_bf16 v[20:23], v[64:67], v[204:207], v[20:23]
	v_mfma_f32_16x16x32_bf16 v[8:11], v[72:75], v[204:207], v[8:11]
	v_mfma_f32_16x16x32_bf16 v[60:63], v[68:71], v[178:181], v[60:63]
	v_mfma_f32_16x16x32_bf16 v[56:59], v[100:103], v[178:181], v[56:59]
	v_mfma_f32_16x16x32_bf16 v[52:55], v[68:71], v[186:189], v[52:55]
	v_mfma_f32_16x16x32_bf16 v[40:43], v[100:103], v[186:189], v[40:43]
	v_mfma_f32_16x16x32_bf16 v[28:31], v[68:71], v[198:201], v[28:31]
	v_mfma_f32_16x16x32_bf16 v[24:27], v[100:103], v[198:201], v[24:27]
	v_mfma_f32_16x16x32_bf16 v[20:23], v[68:71], v[208:211], v[20:23]
	v_mfma_f32_16x16x32_bf16 v[8:11], v[100:103], v[208:211], v[8:11]
	v_mfma_f32_16x16x32_bf16 v[48:51], v[154:157], v[174:177], v[48:51]
	v_mfma_f32_16x16x32_bf16 v[44:47], v[166:169], v[174:177], v[44:47]
	v_mfma_f32_16x16x32_bf16 v[36:39], v[154:157], v[182:185], v[36:39]
	v_mfma_f32_16x16x32_bf16 v[32:35], v[166:169], v[182:185], v[32:35]
	v_mfma_f32_16x16x32_bf16 v[16:19], v[154:157], v[194:197], v[16:19]
	v_mfma_f32_16x16x32_bf16 v[12:15], v[166:169], v[194:197], v[12:15]
	v_mfma_f32_16x16x32_bf16 v[4:7], v[154:157], v[204:207], v[4:7]
	v_mfma_f32_16x16x32_bf16 v[0:3], v[166:169], v[204:207], v[0:3]
	v_mfma_f32_16x16x32_bf16 v[48:51], v[162:165], v[178:181], v[48:51]
	v_mfma_f32_16x16x32_bf16 v[44:47], v[170:173], v[178:181], v[44:47]
	v_mfma_f32_16x16x32_bf16 v[36:39], v[162:165], v[186:189], v[36:39]
	v_mfma_f32_16x16x32_bf16 v[32:35], v[170:173], v[186:189], v[32:35]
	v_mfma_f32_16x16x32_bf16 v[16:19], v[162:165], v[198:201], v[16:19]
	v_mfma_f32_16x16x32_bf16 v[12:15], v[170:173], v[198:201], v[12:15]
	v_mfma_f32_16x16x32_bf16 v[4:7], v[162:165], v[208:211], v[4:7]
	v_mfma_f32_16x16x32_bf16 v[0:3], v[170:173], v[208:211], v[0:3]
	s_setprio 0
	s_barrier
; #define PG8_STAGE(bufoff, gbase, voff) do { _Pragma("unroll") for (int _i = 0; _i < 2; ++_i) \
;         __builtin_amdgcn_global_load_lds((const unsigned*)((const char*)(gbase) + (voff)[_i]), (LAS unsigned*)(lds + (bufoff) + ldsw + _i * 8192), 16, 0, 0); } while (0)
; #define PG8_LDA(dst, b, h) do { _Pragma("unroll") for (int m = 0; m < 4; ++m) _Pragma("unroll") for (int k = 0; k < 2; ++k) dst[m][k] = *(const LAS bf16x8*)(lds + PG8_SA(b, h) + aoff + m * 2048 + k * 1024); } while (0)
; #define PG8_LDB(dst, b, h) do { _Pragma("unroll") for (int n = 0; n < 2; ++n) _Pragma("unroll") for (int k = 0; k < 2; ++k) dst[n][k] = *(const LAS bf16x8*)(lds + PG8_SB(b, h) + boff + n * 2048 + k * 1024); } while (0)
; #define PG8_MMA(ai, bj, At, Bt) do { __builtin_amdgcn_s_setprio(1); _Pragma("unroll") for (int m = 0; m < 4; ++m) _Pragma("unroll") for (int n = 0; n < 2; ++n) _Pragma("unroll") for (int k = 0; k < 2; ++k) \
;         acc[ai][bj][m][n] = __builtin_amdgcn_mfma_f32_16x16x32_bf16(Bt[n][k], At[m][k], acc[ai][bj][m][n], 0, 0, 0); __builtin_amdgcn_s_setprio(0); } while (0)
; #define PG8_WAIT_V(n) asm volatile("s_waitcnt vmcnt(" #n ")" ::: "memory")
; #define PG8_WAIT_L(n) asm volatile("s_waitcnt lgkmcnt(" #n ")" ::: "memory")
; #define PG8_BAR __builtin_amdgcn_s_barrier()
; #define PG8_SCHED __builtin_amdgcn_sched_barrier(0)
; template <class Epi>
; __device__ __forceinline__ void gemm_phase(LAS unsigned char* lds, const Gemm g, const Sched& S, const Epi& E, const int tid) {
;     ...
;             PG8_LDB(B0, 1, 0); PG8_LDB(B1, 1, 1); PG8_SCHED; PG8_LDA(At, 1, 0); PG8_STAGE(PG8_SA(0, 1), a2 + hA, voffA);
;             PG8_WAIT_V(8); PG8_WAIT_L(0); PG8_BAR; PG8_MMA(0, 0, At, B0); PG8_MMA(0, 1, At, B1); PG8_BAR; PG8_SCHED;
	s_add_i32 s43, 0, 0x18000
	s_add_i32 s44, 0, 0x1c000
	v_add_u32_e32 v100, s43, v159
	v_add_u32_e32 v170, s44, v159
	ds_read_b128 v[64:67], v100
	ds_read_b128 v[68:71], v100 offset:1024
	ds_read_b128 v[72:75], v100 offset:2048
	ds_read_b128 v[100:103], v100 offset:3072
	ds_read_b128 v[154:157], v170
	ds_read_b128 v[162:165], v170 offset:1024
	ds_read_b128 v[166:169], v170 offset:2048
	ds_read_b128 v[170:173], v170 offset:3072
	s_add_u32 s20, s74, 0x120000
	s_addc_u32 s21, s75, 0
	s_mov_b32 m0, s3
	v_lshl_add_u64 v[218:219], s[20:21], 0, v[148:149]
	ds_read_b128 v[174:177], v161 offset:32768
	ds_read_b128 v[178:181], v161 offset:33792
	ds_read_b128 v[182:185], v161 offset:34816
	ds_read_b128 v[186:189], v161 offset:35840
	ds_read_b128 v[194:197], v161 offset:36864
	ds_read_b128 v[198:201], v161 offset:37888
	ds_read_b128 v[204:207], v161 offset:38912
	ds_read_b128 v[208:211], v161 offset:39936
	global_load_lds_dwordx4 v[218:219], off
	v_lshl_add_u64 v[218:219], s[20:21], 0, v[146:147]
	s_mov_b32 m0, s34
	s_nop 0
	global_load_lds_dwordx4 v[218:219], off
	s_waitcnt vmcnt(8)
	s_waitcnt lgkmcnt(0)
	s_barrier
	s_setprio 1
	s_waitcnt lgkmcnt(0)
	v_mfma_f32_16x16x32_bf16 v[140:143], v[64:67], v[174:177], v[140:143]
	v_mfma_f32_16x16x32_bf16 v[136:139], v[72:75], v[174:177], v[136:139]
	v_mfma_f32_16x16x32_bf16 v[132:135], v[64:67], v[182:185], v[132:135]
	v_mfma_f32_16x16x32_bf16 v[120:123], v[72:75], v[182:185], v[120:123]
	v_mfma_f32_16x16x32_bf16 v[108:111], v[64:67], v[194:197], v[108:111]
	v_mfma_f32_16x16x32_bf16 v[104:107], v[72:75], v[194:197], v[104:107]
	v_mfma_f32_16x16x32_bf16 v[96:99], v[64:67], v[204:207], v[96:99]
	v_mfma_f32_16x16x32_bf16 v[84:87], v[72:75], v[204:207], v[84:87]
	v_mfma_f32_16x16x32_bf16 v[140:143], v[68:71], v[178:181], v[140:143]
	v_mfma_f32_16x16x32_bf16 v[136:139], v[100:103], v[178:181], v[136:139]
	v_mfma_f32_16x16x32_bf16 v[132:135], v[68:71], v[186:189], v[132:135]
	v_mfma_f32_16x16x32_bf16 v[120:123], v[100:103], v[186:189], v[120:123]
	v_mfma_f32_16x16x32_bf16 v[108:111], v[68:71], v[198:201], v[108:111]
	v_mfma_f32_16x16x32_bf16 v[104:107], v[100:103], v[198:201], v[104:107]
	v_mfma_f32_16x16x32_bf16 v[96:99], v[68:71], v[208:211], v[96:99]
	v_mfma_f32_16x16x32_bf16 v[84:87], v[100:103], v[208:211], v[84:87]
	v_mfma_f32_16x16x32_bf16 v[128:131], v[154:157], v[174:177], v[128:131]
	v_mfma_f32_16x16x32_bf16 v[124:127], v[166:169], v[174:177], v[124:127]
	v_mfma_f32_16x16x32_bf16 v[116:119], v[154:157], v[182:185], v[116:119]
	v_mfma_f32_16x16x32_bf16 v[112:115], v[166:169], v[182:185], v[112:115]
	v_mfma_f32_16x16x32_bf16 v[92:95], v[154:157], v[194:197], v[92:95]
	v_mfma_f32_16x16x32_bf16 v[88:91], v[166:169], v[194:197], v[88:91]
	v_mfma_f32_16x16x32_bf16 v[80:83], v[154:157], v[204:207], v[80:83]
	v_mfma_f32_16x16x32_bf16 v[76:79], v[166:169], v[204:207], v[76:79]
	v_mfma_f32_16x16x32_bf16 v[128:131], v[162:165], v[178:181], v[128:131]
	v_mfma_f32_16x16x32_bf16 v[124:127], v[170:173], v[178:181], v[124:127]
	v_mfma_f32_16x16x32_bf16 v[116:119], v[162:165], v[186:189], v[116:119]
	v_mfma_f32_16x16x32_bf16 v[112:115], v[170:173], v[186:189], v[112:115]
	v_mfma_f32_16x16x32_bf16 v[92:95], v[162:165], v[198:201], v[92:95]
	v_mfma_f32_16x16x32_bf16 v[88:91], v[170:173], v[198:201], v[88:91]
	v_mfma_f32_16x16x32_bf16 v[80:83], v[162:165], v[208:211], v[80:83]
	v_mfma_f32_16x16x32_bf16 v[76:79], v[170:173], v[208:211], v[76:79]
	s_setprio 0
	s_barrier
; #define PG8_STAGE(bufoff, gbase, voff) do { _Pragma("unroll") for (int _i = 0; _i < 2; ++_i) \
;         __builtin_amdgcn_global_load_lds((const unsigned*)((const char*)(gbase) + (voff)[_i]), (LAS unsigned*)(lds + (bufoff) + ldsw + _i * 8192), 16, 0, 0); } while (0)
; #define PG8_LDA(dst, b, h) do { _Pragma("unroll") for (int m = 0; m < 4; ++m) _Pragma("unroll") for (int k = 0; k < 2; ++k) dst[m][k] = *(const LAS bf16x8*)(lds + PG8_SA(b, h) + aoff + m * 2048 + k * 1024); } while (0)
; #define PG8_MMA(ai, bj, At, Bt) do { __builtin_amdgcn_s_setprio(1); _Pragma("unroll") for (int m = 0; m < 4; ++m) _Pragma("unroll") for (int n = 0; n < 2; ++n) _Pragma("unroll") for (int k = 0; k < 2; ++k) \
;         acc[ai][bj][m][n] = __builtin_amdgcn_mfma_f32_16x16x32_bf16(Bt[n][k], At[m][k], acc[ai][bj][m][n], 0, 0, 0); __builtin_amdgcn_s_setprio(0); } while (0)
; #define PG8_WAIT_V(n) asm volatile("s_waitcnt vmcnt(" #n ")" ::: "memory")
; #define PG8_WAIT_L(n) asm volatile("s_waitcnt lgkmcnt(" #n ")" ::: "memory")
; #define PG8_BAR __builtin_amdgcn_s_barrier()
; #define PG8_SCHED __builtin_amdgcn_sched_barrier(0)
; template <class Epi>
; __device__ __forceinline__ void gemm_phase(LAS unsigned char* lds, const Gemm g, const Sched& S, const Epi& E, const int tid) {
;     ...
;             PG8_LDA(At, 1, 1); PG8_STAGE(PG8_SB(1, 0), b3, voffB); PG8_STAGE(PG8_SB(1, 1), b3 + hB, voffB); PG8_STAGE(PG8_SA(1, 0), a3, voffA);
;             PG8_WAIT_V(8); PG8_WAIT_L(0); PG8_BAR; PG8_MMA(1, 0, At, B0); PG8_MMA(1, 1, At, B1); PG8_BAR; PG8_SCHED;
;         }
	s_add_i32 s20, s43, s76
	v_lshl_add_u64 v[190:191], v[190:191], 0, s[94:95]
	s_mov_b32 m0, s20
	ds_read_b128 v[174:177], v161 offset:49152
	ds_read_b128 v[178:181], v161 offset:50176
	ds_read_b128 v[182:185], v161 offset:51200
	ds_read_b128 v[186:189], v161 offset:52224
	ds_read_b128 v[194:197], v161 offset:53248
	ds_read_b128 v[198:201], v161 offset:54272
	ds_read_b128 v[204:207], v161 offset:55296
	ds_read_b128 v[208:211], v161 offset:56320
	global_load_lds_dwordx4 v[190:191], off
	s_add_i32 m0, s20, 0x2000
	s_add_u32 s20, s72, 0x40080
	v_lshl_add_u64 v[190:191], v[212:213], 0, s[94:95]
	s_addc_u32 s21, s73, 0
	s_add_i32 s43, s44, s76
	global_load_lds_dwordx4 v[190:191], off
	v_lshl_add_u64 v[190:191], s[20:21], 0, v[192:193]
	s_mov_b32 m0, s43
	s_nop 0
	global_load_lds_dwordx4 v[190:191], off
	v_lshl_add_u64 v[190:191], s[20:21], 0, v[144:145]
	s_add_i32 m0, s43, 0x2000
	s_nop 0
	global_load_lds_dwordx4 v[190:191], off
	v_lshl_add_u64 v[190:191], v[214:215], 0, s[94:95]
	s_mov_b32 m0, s47
	s_nop 0
	global_load_lds_dwordx4 v[190:191], off
	v_lshl_add_u64 v[190:191], v[216:217], 0, s[94:95]
	s_mov_b32 m0, s40
	s_nop 0
	global_load_lds_dwordx4 v[190:191], off
	s_waitcnt vmcnt(8)
	s_waitcnt lgkmcnt(0)
	s_barrier
	s_setprio 1
	s_waitcnt lgkmcnt(0)
	v_mfma_f32_16x16x32_bf16 v[60:63], v[64:67], v[174:177], v[60:63]
	v_mfma_f32_16x16x32_bf16 v[56:59], v[72:75], v[174:177], v[56:59]
	v_mfma_f32_16x16x32_bf16 v[52:55], v[64:67], v[182:185], v[52:55]
	v_mfma_f32_16x16x32_bf16 v[40:43], v[72:75], v[182:185], v[40:43]
	v_mfma_f32_16x16x32_bf16 v[28:31], v[64:67], v[194:197], v[28:31]
	v_mfma_f32_16x16x32_bf16 v[24:27], v[72:75], v[194:197], v[24:27]
	v_mfma_f32_16x16x32_bf16 v[20:23], v[64:67], v[204:207], v[20:23]
	v_mfma_f32_16x16x32_bf16 v[8:11], v[72:75], v[204:207], v[8:11]
	v_mfma_f32_16x16x32_bf16 v[60:63], v[68:71], v[178:181], v[60:63]
	v_mfma_f32_16x16x32_bf16 v[56:59], v[100:103], v[178:181], v[56:59]
	v_mfma_f32_16x16x32_bf16 v[52:55], v[68:71], v[186:189], v[52:55]
	v_mfma_f32_16x16x32_bf16 v[40:43], v[100:103], v[186:189], v[40:43]
	v_mfma_f32_16x16x32_bf16 v[28:31], v[68:71], v[198:201], v[28:31]
	v_mfma_f32_16x16x32_bf16 v[24:27], v[100:103], v[198:201], v[24:27]
	v_mfma_f32_16x16x32_bf16 v[20:23], v[68:71], v[208:211], v[20:23]
	v_mfma_f32_16x16x32_bf16 v[8:11], v[100:103], v[208:211], v[8:11]
	v_mfma_f32_16x16x32_bf16 v[48:51], v[154:157], v[174:177], v[48:51]
	v_mfma_f32_16x16x32_bf16 v[44:47], v[166:169], v[174:177], v[44:47]
	v_mfma_f32_16x16x32_bf16 v[36:39], v[154:157], v[182:185], v[36:39]
	v_mfma_f32_16x16x32_bf16 v[32:35], v[166:169], v[182:185], v[32:35]
	v_mfma_f32_16x16x32_bf16 v[16:19], v[154:157], v[194:197], v[16:19]
	v_mfma_f32_16x16x32_bf16 v[12:15], v[166:169], v[194:197], v[12:15]
	v_mfma_f32_16x16x32_bf16 v[4:7], v[154:157], v[204:207], v[4:7]
	v_mfma_f32_16x16x32_bf16 v[0:3], v[166:169], v[204:207], v[0:3]
	v_mfma_f32_16x16x32_bf16 v[48:51], v[162:165], v[178:181], v[48:51]
	v_mfma_f32_16x16x32_bf16 v[44:47], v[170:173], v[178:181], v[44:47]
	v_mfma_f32_16x16x32_bf16 v[36:39], v[162:165], v[186:189], v[36:39]
	v_mfma_f32_16x16x32_bf16 v[32:35], v[170:173], v[186:189], v[32:35]
	v_mfma_f32_16x16x32_bf16 v[16:19], v[162:165], v[198:201], v[16:19]
	v_mfma_f32_16x16x32_bf16 v[12:15], v[170:173], v[198:201], v[12:15]
	v_mfma_f32_16x16x32_bf16 v[4:7], v[162:165], v[208:211], v[4:7]
	v_mfma_f32_16x16x32_bf16 v[0:3], v[170:173], v[208:211], v[0:3]
	s_setprio 0
	s_barrier
	s_add_i32 vcc_hi, vcc_hi, 2
	s_add_u32 s17, s17, 0x100
	s_addc_u32 vcc_lo, vcc_lo, 0
	s_cmp_gt_u32 vcc_hi, 13
	s_mov_b64 s[20:21], s[22:23]
	s_cbranch_scc0 .LBB0_1143

; #define PG8_STAGE(bufoff, gbase, voff) do { _Pragma("unroll") for (int _i = 0; _i < 2; ++_i) \
;         __builtin_amdgcn_global_load_lds((const unsigned*)((const char*)(gbase) + (voff)[_i]), (LAS unsigned*)(lds + (bufoff) + ldsw + _i * 8192), 16, 0, 0); } while (0)
; #define PG8_LDA(dst, b, h) do { _Pragma("unroll") for (int m = 0; m < 4; ++m) _Pragma("unroll") for (int k = 0; k < 2; ++k) dst[m][k] = *(const LAS bf16x8*)(lds + PG8_SA(b, h) + aoff + m * 2048 + k * 1024); } while (0)
; #define PG8_LDB(dst, b, h) do { _Pragma("unroll") for (int n = 0; n < 2; ++n) _Pragma("unroll") for (int k = 0; k < 2; ++k) dst[n][k] = *(const LAS bf16x8*)(lds + PG8_SB(b, h) + boff + n * 2048 + k * 1024); } while (0)
; #define PG8_MMA(ai, bj, At, Bt) do { __builtin_amdgcn_s_setprio(1); _Pragma("unroll") for (int m = 0; m < 4; ++m) _Pragma("unroll") for (int n = 0; n < 2; ++n) _Pragma("unroll") for (int k = 0; k < 2; ++k) \
;         acc[ai][bj][m][n] = __builtin_amdgcn_mfma_f32_16x16x32_bf16(Bt[n][k], At[m][k], acc[ai][bj][m][n], 0, 0, 0); __builtin_amdgcn_s_setprio(0); } while (0)
; #define PG8_WAIT_V(n) asm volatile("s_waitcnt vmcnt(" #n ")" ::: "memory")
; #define PG8_WAIT_L(n) asm volatile("s_waitcnt lgkmcnt(" #n ")" ::: "memory")
; #define PG8_BAR __builtin_amdgcn_s_barrier()
; #define PG8_SCHED __builtin_amdgcn_sched_barrier(0)
; template <class Epi>
; __device__ __forceinline__ void gemm_phase(LAS unsigned char* lds, const Gemm g, const Sched& S, const Epi& E, const int tid) {
;     ...
;         const bool has_next = S.next(ui + 1, nxt);
;         const char* nA = cA; const char* nB = cB; if (has_next) S.ptrs(nxt, nA, nB);
;         for (int t = 0; t < nt; t += 2) {
;             const bool last = (t == nt - 2);
;             const char* a1 = cA + (size_t)(t + 1) * kstep;
;             const char* a2 = last ? nA : cA + (size_t)(t + 2) * kstep; const char* b2 = last ? nB : cB + (size_t)(t + 2) * kstep;
;             const char* a3 = a2 + kstep; const char* b3 = b2 + kstep;
;             PG8_LDB(B0, 0, 0); PG8_LDB(B1, 0, 1); PG8_SCHED; PG8_LDA(At, 0, 0); PG8_STAGE(PG8_SA(1, 1), a1 + hA, voffA);
;             PG8_WAIT_V(8); PG8_WAIT_L(0); PG8_BAR; PG8_MMA(0, 0, At, B0); PG8_MMA(0, 1, At, B1); PG8_BAR; PG8_SCHED;
;             PG8_LDA(At, 0, 1); PG8_STAGE(PG8_SB(0, 0), b2, voffB); PG8_STAGE(PG8_SB(0, 1), b2 + hB, voffB); PG8_STAGE(PG8_SA(0, 0), a2, voffA);
.LBB0_1335:
	s_add_u32 s20, s20, 0x40080
	s_addc_u32 s21, s21, 0
	s_add_u32 s13, s22, 0x100
	s_addc_u32 s15, s23, 0
	s_mov_b32 s42, -2
	s_add_u32 s22, s20, 0xfffc0080
	s_addc_u32 s23, s21, -1
	s_add_i32 s43, 0, 0x10000
	s_cmp_eq_u32 s42, 12
	s_cselect_b32 s73, s7, s23
	s_cselect_b32 s72, s6, s22
	v_add_u32_e32 v138, s43, v141
	s_cselect_b32 s23, s17, s15
	s_cselect_b32 s22, s16, s13
	s_add_i32 s44, 0, 0x14000
	ds_read_b128 v[144:147], v138
	ds_read_b128 v[148:151], v138 offset:1024
	ds_read_b128 v[152:155], v138 offset:2048
	ds_read_b128 v[156:159], v138 offset:3072
	v_add_u32_e32 v138, s44, v141
	ds_read_b128 v[160:163], v138
	ds_read_b128 v[164:167], v138 offset:1024
	ds_read_b128 v[168:171], v138 offset:2048
	ds_read_b128 v[172:175], v138 offset:3072
	v_lshl_add_u64 v[138:139], s[20:21], 0, v[134:135]
	s_add_i32 m0, s19, 0xc000
	ds_read_b128 v[176:179], v143
	ds_read_b128 v[180:183], v143 offset:1024
	ds_read_b128 v[184:187], v143 offset:2048
	ds_read_b128 v[188:191], v143 offset:3072
	ds_read_b128 v[194:197], v143 offset:4096
	ds_read_b128 v[198:201], v143 offset:5120
	ds_read_b128 v[204:207], v143 offset:6144
	ds_read_b128 v[208:211], v143 offset:7168
	global_load_lds_dwordx4 v[138:139], off
	v_lshl_add_u64 v[138:139], s[20:21], 0, v[136:137]
	s_add_i32 m0, s19, 0xe000
	s_nop 0
	global_load_lds_dwordx4 v[138:139], off
	s_waitcnt vmcnt(8)
	s_waitcnt lgkmcnt(0)
	s_barrier
	s_setprio 1
	s_waitcnt lgkmcnt(0)
	v_mfma_f32_16x16x32_bf16 v[124:127], v[144:147], v[176:179], 0
	v_mfma_f32_16x16x32_bf16 v[120:123], v[152:155], v[176:179], 0
	v_mfma_f32_16x16x32_bf16 v[108:111], v[144:147], v[184:187], 0
	v_mfma_f32_16x16x32_bf16 v[104:107], v[152:155], v[184:187], 0
	v_mfma_f32_16x16x32_bf16 v[92:95], v[144:147], v[194:197], 0
	v_mfma_f32_16x16x32_bf16 v[88:91], v[152:155], v[194:197], 0
	v_mfma_f32_16x16x32_bf16 v[76:79], v[144:147], v[204:207], 0
	v_mfma_f32_16x16x32_bf16 v[72:75], v[152:155], v[204:207], 0
	v_mfma_f32_16x16x32_bf16 v[124:127], v[148:151], v[180:183], v[124:127]
	v_mfma_f32_16x16x32_bf16 v[120:123], v[156:159], v[180:183], v[120:123]
	v_mfma_f32_16x16x32_bf16 v[108:111], v[148:151], v[188:191], v[108:111]
	v_mfma_f32_16x16x32_bf16 v[104:107], v[156:159], v[188:191], v[104:107]
	v_mfma_f32_16x16x32_bf16 v[92:95], v[148:151], v[198:201], v[92:95]
	v_mfma_f32_16x16x32_bf16 v[88:91], v[156:159], v[198:201], v[88:91]
	v_mfma_f32_16x16x32_bf16 v[76:79], v[148:151], v[208:211], v[76:79]
	v_mfma_f32_16x16x32_bf16 v[72:75], v[156:159], v[208:211], v[72:75]
	v_mfma_f32_16x16x32_bf16 v[116:119], v[160:163], v[176:179], 0
	v_mfma_f32_16x16x32_bf16 v[112:115], v[168:171], v[176:179], 0
	v_mfma_f32_16x16x32_bf16 v[100:103], v[160:163], v[184:187], 0
	v_mfma_f32_16x16x32_bf16 v[96:99], v[168:171], v[184:187], 0
	v_mfma_f32_16x16x32_bf16 v[84:87], v[160:163], v[194:197], 0
	v_mfma_f32_16x16x32_bf16 v[80:83], v[168:171], v[194:197], 0
	v_mfma_f32_16x16x32_bf16 v[68:71], v[160:163], v[204:207], 0
	v_mfma_f32_16x16x32_bf16 v[64:67], v[168:171], v[204:207], 0
	v_mfma_f32_16x16x32_bf16 v[116:119], v[164:167], v[180:183], v[116:119]
	v_mfma_f32_16x16x32_bf16 v[112:115], v[172:175], v[180:183], v[112:115]
	v_mfma_f32_16x16x32_bf16 v[100:103], v[164:167], v[188:191], v[100:103]
	v_mfma_f32_16x16x32_bf16 v[96:99], v[172:175], v[188:191], v[96:99]
	v_mfma_f32_16x16x32_bf16 v[84:87], v[164:167], v[198:201], v[84:87]
	v_mfma_f32_16x16x32_bf16 v[80:83], v[172:175], v[198:201], v[80:83]
	v_mfma_f32_16x16x32_bf16 v[68:71], v[164:167], v[208:211], v[68:71]
	v_mfma_f32_16x16x32_bf16 v[64:67], v[172:175], v[208:211], v[64:67]
	s_setprio 0
	s_barrier
	s_add_i32 s43, s43, s35
	v_lshl_add_u64 v[138:139], s[22:23], 0, v[192:193]
	s_mov_b32 m0, s43
	ds_read_b128 v[176:179], v143 offset:16384
	ds_read_b128 v[180:183], v143 offset:17408
	ds_read_b128 v[184:187], v143 offset:18432
	ds_read_b128 v[188:191], v143 offset:19456
	ds_read_b128 v[194:197], v143 offset:20480
	ds_read_b128 v[198:201], v143 offset:21504
	ds_read_b128 v[204:207], v143 offset:22528
	ds_read_b128 v[208:211], v143 offset:23552
	global_load_lds_dwordx4 v[138:139], off
	s_add_i32 m0, s43, 0x2000
	s_add_u32 s76, s22, 0x40000
	v_lshl_add_u64 v[212:213], s[22:23], 0, v[128:129]
	s_addc_u32 s77, s23, 0
	s_add_i32 s43, s44, s35
	global_load_lds_dwordx4 v[212:213], off
	v_lshl_add_u64 v[214:215], s[76:77], 0, v[192:193]
	s_mov_b32 m0, s43
	v_lshl_add_u64 v[216:217], s[72:73], 0, v[130:131]
	global_load_lds_dwordx4 v[214:215], off
	v_lshl_add_u64 v[214:215], s[76:77], 0, v[128:129]
	s_add_i32 m0, s43, 0x2000
	s_nop 0
	global_load_lds_dwordx4 v[214:215], off
	v_lshl_add_u64 v[214:215], s[72:73], 0, v[132:133]
	s_mov_b32 m0, s19
	s_nop 0
	global_load_lds_dwordx4 v[214:215], off
	s_mov_b32 m0, s39
	s_nop 0
	global_load_lds_dwordx4 v[216:217], off
	s_waitcnt vmcnt(8)
	s_waitcnt lgkmcnt(0)
	s_barrier
; #define PG8_STAGE(bufoff, gbase, voff) do { _Pragma("unroll") for (int _i = 0; _i < 2; ++_i) \
;         __builtin_amdgcn_global_load_lds((const unsigned*)((const char*)(gbase) + (voff)[_i]), (LAS unsigned*)(lds + (bufoff) + ldsw + _i * 8192), 16, 0, 0); } while (0)
; #define PG8_LDA(dst, b, h) do { _Pragma("unroll") for (int m = 0; m < 4; ++m) _Pragma("unroll") for (int k = 0; k < 2; ++k) dst[m][k] = *(const LAS bf16x8*)(lds + PG8_SA(b, h) + aoff + m * 2048 + k * 1024); } while (0)
; #define PG8_LDB(dst, b, h) do { _Pragma("unroll") for (int n = 0; n < 2; ++n) _Pragma("unroll") for (int k = 0; k < 2; ++k) dst[n][k] = *(const LAS bf16x8*)(lds + PG8_SB(b, h) + boff + n * 2048 + k * 1024); } while (0)
; #define PG8_MMA(ai, bj, At, Bt) do { __builtin_amdgcn_s_setprio(1); _Pragma("unroll") for (int m = 0; m < 4; ++m) _Pragma("unroll") for (int n = 0; n < 2; ++n) _Pragma("unroll") for (int k = 0; k < 2; ++k) \
;         acc[ai][bj][m][n] = __builtin_amdgcn_mfma_f32_16x16x32_bf16(Bt[n][k], At[m][k], acc[ai][bj][m][n], 0, 0, 0); __builtin_amdgcn_s_setprio(0); } while (0)
; #define PG8_WAIT_V(n) asm volatile("s_waitcnt vmcnt(" #n ")" ::: "memory")
; #define PG8_WAIT_L(n) asm volatile("s_waitcnt lgkmcnt(" #n ")" ::: "memory")
; #define PG8_BAR __builtin_amdgcn_s_barrier()
; #define PG8_SCHED __builtin_amdgcn_sched_barrier(0)
; template <class Epi>
; __device__ __forceinline__ void gemm_phase(LAS unsigned char* lds, const Gemm g, const Sched& S, const Epi& E, const int tid) {
;     ...
;             PG8_WAIT_V(8); PG8_WAIT_L(0); PG8_BAR; PG8_MMA(1, 0, At, B0); PG8_MMA(1, 1, At, B1); PG8_BAR; PG8_SCHED;
;             PG8_LDB(B0, 1, 0); PG8_LDB(B1, 1, 1); PG8_SCHED; PG8_LDA(At, 1, 0); PG8_STAGE(PG8_SA(0, 1), a2 + hA, voffA);
;             PG8_WAIT_V(8); PG8_WAIT_L(0); PG8_BAR; PG8_MMA(0, 0, At, B0); PG8_MMA(0, 1, At, B1); PG8_BAR; PG8_SCHED;
	s_setprio 1
	s_waitcnt lgkmcnt(0)
	v_mfma_f32_16x16x32_bf16 v[60:63], v[144:147], v[176:179], 0
	v_mfma_f32_16x16x32_bf16 v[56:59], v[152:155], v[176:179], 0
	v_mfma_f32_16x16x32_bf16 v[44:47], v[144:147], v[184:187], 0
	v_mfma_f32_16x16x32_bf16 v[40:43], v[152:155], v[184:187], 0
	v_mfma_f32_16x16x32_bf16 v[28:31], v[144:147], v[194:197], 0
	v_mfma_f32_16x16x32_bf16 v[24:27], v[152:155], v[194:197], 0
	v_mfma_f32_16x16x32_bf16 v[12:15], v[144:147], v[204:207], 0
	v_mfma_f32_16x16x32_bf16 v[8:11], v[152:155], v[204:207], 0
	v_mfma_f32_16x16x32_bf16 v[60:63], v[148:151], v[180:183], v[60:63]
	v_mfma_f32_16x16x32_bf16 v[56:59], v[156:159], v[180:183], v[56:59]
	v_mfma_f32_16x16x32_bf16 v[44:47], v[148:151], v[188:191], v[44:47]
	v_mfma_f32_16x16x32_bf16 v[40:43], v[156:159], v[188:191], v[40:43]
	v_mfma_f32_16x16x32_bf16 v[28:31], v[148:151], v[198:201], v[28:31]
	v_mfma_f32_16x16x32_bf16 v[24:27], v[156:159], v[198:201], v[24:27]
	v_mfma_f32_16x16x32_bf16 v[12:15], v[148:151], v[208:211], v[12:15]
	v_mfma_f32_16x16x32_bf16 v[8:11], v[156:159], v[208:211], v[8:11]
	v_mfma_f32_16x16x32_bf16 v[52:55], v[160:163], v[176:179], 0
	v_mfma_f32_16x16x32_bf16 v[48:51], v[168:171], v[176:179], 0
	v_mfma_f32_16x16x32_bf16 v[36:39], v[160:163], v[184:187], 0
	v_mfma_f32_16x16x32_bf16 v[32:35], v[168:171], v[184:187], 0
	v_mfma_f32_16x16x32_bf16 v[20:23], v[160:163], v[194:197], 0
	v_mfma_f32_16x16x32_bf16 v[16:19], v[168:171], v[194:197], 0
	v_mfma_f32_16x16x32_bf16 v[4:7], v[160:163], v[204:207], 0
	v_mfma_f32_16x16x32_bf16 v[0:3], v[168:171], v[204:207], 0
	v_mfma_f32_16x16x32_bf16 v[52:55], v[164:167], v[180:183], v[52:55]
	v_mfma_f32_16x16x32_bf16 v[48:51], v[172:175], v[180:183], v[48:51]
	v_mfma_f32_16x16x32_bf16 v[36:39], v[164:167], v[188:191], v[36:39]
	v_mfma_f32_16x16x32_bf16 v[32:35], v[172:175], v[188:191], v[32:35]
	v_mfma_f32_16x16x32_bf16 v[20:23], v[164:167], v[198:201], v[20:23]
	v_mfma_f32_16x16x32_bf16 v[16:19], v[172:175], v[198:201], v[16:19]
	v_mfma_f32_16x16x32_bf16 v[4:7], v[164:167], v[208:211], v[4:7]
	v_mfma_f32_16x16x32_bf16 v[0:3], v[172:175], v[208:211], v[0:3]
	s_setprio 0
	s_barrier
	s_add_i32 s43, 0, 0x18000
	s_add_i32 s44, 0, 0x1c000
	v_add_u32_e32 v156, s43, v141
	v_add_u32_e32 v172, s44, v141
	ds_read_b128 v[144:147], v156
	ds_read_b128 v[148:151], v156 offset:1024
	ds_read_b128 v[152:155], v156 offset:2048
	ds_read_b128 v[156:159], v156 offset:3072
	ds_read_b128 v[160:163], v172
	ds_read_b128 v[164:167], v172 offset:1024
	ds_read_b128 v[168:171], v172 offset:2048
	ds_read_b128 v[172:175], v172 offset:3072
	s_add_u32 s72, s72, 0x40000
	s_addc_u32 s73, s73, 0
	s_mov_b32 m0, s40
	v_lshl_add_u64 v[218:219], s[72:73], 0, v[132:133]
	ds_read_b128 v[176:179], v143 offset:32768
	ds_read_b128 v[180:183], v143 offset:33792
	ds_read_b128 v[184:187], v143 offset:34816
	ds_read_b128 v[188:191], v143 offset:35840
	ds_read_b128 v[194:197], v143 offset:36864
	ds_read_b128 v[198:201], v143 offset:37888
	ds_read_b128 v[204:207], v143 offset:38912
	ds_read_b128 v[208:211], v143 offset:39936
	global_load_lds_dwordx4 v[218:219], off
	v_lshl_add_u64 v[218:219], s[72:73], 0, v[130:131]
	s_mov_b32 m0, s45
	s_nop 0
	global_load_lds_dwordx4 v[218:219], off
	s_waitcnt vmcnt(8)
	s_waitcnt lgkmcnt(0)
	s_barrier
	s_setprio 1
	s_waitcnt lgkmcnt(0)
	v_mfma_f32_16x16x32_bf16 v[124:127], v[144:147], v[176:179], v[124:127]
	v_mfma_f32_16x16x32_bf16 v[120:123], v[152:155], v[176:179], v[120:123]
	v_mfma_f32_16x16x32_bf16 v[108:111], v[144:147], v[184:187], v[108:111]
	v_mfma_f32_16x16x32_bf16 v[104:107], v[152:155], v[184:187], v[104:107]
	v_mfma_f32_16x16x32_bf16 v[92:95], v[144:147], v[194:197], v[92:95]
	v_mfma_f32_16x16x32_bf16 v[88:91], v[152:155], v[194:197], v[88:91]
	v_mfma_f32_16x16x32_bf16 v[76:79], v[144:147], v[204:207], v[76:79]
	v_mfma_f32_16x16x32_bf16 v[72:75], v[152:155], v[204:207], v[72:75]
	v_mfma_f32_16x16x32_bf16 v[124:127], v[148:151], v[180:183], v[124:127]
	v_mfma_f32_16x16x32_bf16 v[120:123], v[156:159], v[180:183], v[120:123]
	v_mfma_f32_16x16x32_bf16 v[108:111], v[148:151], v[188:191], v[108:111]
	v_mfma_f32_16x16x32_bf16 v[104:107], v[156:159], v[188:191], v[104:107]
	v_mfma_f32_16x16x32_bf16 v[92:95], v[148:151], v[198:201], v[92:95]
	v_mfma_f32_16x16x32_bf16 v[88:91], v[156:159], v[198:201], v[88:91]
	v_mfma_f32_16x16x32_bf16 v[76:79], v[148:151], v[208:211], v[76:79]
	v_mfma_f32_16x16x32_bf16 v[72:75], v[156:159], v[208:211], v[72:75]
	v_mfma_f32_16x16x32_bf16 v[116:119], v[160:163], v[176:179], v[116:119]
	v_mfma_f32_16x16x32_bf16 v[112:115], v[168:171], v[176:179], v[112:115]
	v_mfma_f32_16x16x32_bf16 v[100:103], v[160:163], v[184:187], v[100:103]
	v_mfma_f32_16x16x32_bf16 v[96:99], v[168:171], v[184:187], v[96:99]
	v_mfma_f32_16x16x32_bf16 v[84:87], v[160:163], v[194:197], v[84:87]
	v_mfma_f32_16x16x32_bf16 v[80:83], v[168:171], v[194:197], v[80:83]
	v_mfma_f32_16x16x32_bf16 v[68:71], v[160:163], v[204:207], v[68:71]
	v_mfma_f32_16x16x32_bf16 v[64:67], v[168:171], v[204:207], v[64:67]
	v_mfma_f32_16x16x32_bf16 v[116:119], v[164:167], v[180:183], v[116:119]
	v_mfma_f32_16x16x32_bf16 v[112:115], v[172:175], v[180:183], v[112:115]
	v_mfma_f32_16x16x32_bf16 v[100:103], v[164:167], v[188:191], v[100:103]
	v_mfma_f32_16x16x32_bf16 v[96:99], v[172:175], v[188:191], v[96:99]
	v_mfma_f32_16x16x32_bf16 v[84:87], v[164:167], v[198:201], v[84:87]
	v_mfma_f32_16x16x32_bf16 v[80:83], v[172:175], v[198:201], v[80:83]
	v_mfma_f32_16x16x32_bf16 v[68:71], v[164:167], v[208:211], v[68:71]
	v_mfma_f32_16x16x32_bf16 v[64:67], v[172:175], v[208:211], v[64:67]
	s_setprio 0
	s_barrier
; #define PG8_STAGE(bufoff, gbase, voff) do { _Pragma("unroll") for (int _i = 0; _i < 2; ++_i) \
;         __builtin_amdgcn_global_load_lds((const unsigned*)((const char*)(gbase) + (voff)[_i]), (LAS unsigned*)(lds + (bufoff) + ldsw + _i * 8192), 16, 0, 0); } while (0)
; #define PG8_LDA(dst, b, h) do { _Pragma("unroll") for (int m = 0; m < 4; ++m) _Pragma("unroll") for (int k = 0; k < 2; ++k) dst[m][k] = *(const LAS bf16x8*)(lds + PG8_SA(b, h) + aoff + m * 2048 + k * 1024); } while (0)
; #define PG8_LDB(dst, b, h) do { _Pragma("unroll") for (int n = 0; n < 2; ++n) _Pragma("unroll") for (int k = 0; k < 2; ++k) dst[n][k] = *(const LAS bf16x8*)(lds + PG8_SB(b, h) + boff + n * 2048 + k * 1024); } while (0)
; #define PG8_WAIT_V(n) asm volatile("s_waitcnt vmcnt(" #n ")" ::: "memory")
; #define PG8_BAR __builtin_amdgcn_s_barrier()
; template <class Epi>
; __device__ __forceinline__ void gemm_phase(LAS unsigned char* lds, const Gemm g, const Sched& S, const Epi& E, const int tid) {
;     ...
;         for (int t = 0; t < nt; t += 2) {
;             const bool last = (t == nt - 2);
;             const char* a1 = cA + (size_t)(t + 1) * kstep;
;             const char* a2 = last ? nA : cA + (size_t)(t + 2) * kstep; const char* b2 = last ? nB : cB + (size_t)(t + 2) * kstep;
;             const char* a3 = a2 + kstep; const char* b3 = b2 + kstep;
;             PG8_LDB(B0, 0, 0); PG8_LDB(B1, 0, 1); PG8_SCHED; PG8_LDA(At, 0, 0); PG8_STAGE(PG8_SA(1, 1), a1 + hA, voffA);
;             PG8_WAIT_V(8); PG8_WAIT_L(0); PG8_BAR; PG8_MMA(0, 0, At, B0); PG8_MMA(0, 1, At, B1); PG8_BAR; PG8_SCHED;
;             PG8_LDA(At, 0, 1); PG8_STAGE(PG8_SB(0, 0), b2, voffB); PG8_STAGE(PG8_SB(0, 1), b2 + hB, voffB); PG8_STAGE(PG8_SA(0, 0), a2, voffA);
;             PG8_WAIT_V(8); PG8_WAIT_L(0); PG8_BAR; PG8_MMA(1, 0, At, B0); PG8_MMA(1, 1, At, B1); PG8_BAR; PG8_SCHED;
;             PG8_LDB(B0, 1, 0); PG8_LDB(B1, 1, 1); PG8_SCHED; PG8_LDA(At, 1, 0); PG8_STAGE(PG8_SA(0, 1), a2 + hA, voffA);
;             PG8_WAIT_V(8); PG8_WAIT_L(0); PG8_BAR; PG8_MMA(0, 0, At, B0); PG8_MMA(0, 1, At, B1); PG8_BAR; PG8_SCHED;
;             PG8_LDA(At, 1, 1); PG8_STAGE(PG8_SB(1, 0), b3, voffB); PG8_STAGE(PG8_SB(1, 1), b3 + hB, voffB); PG8_STAGE(PG8_SA(1, 0), a3, voffA);
;             PG8_WAIT_V(8); PG8_WAIT_L(0); PG8_BAR; PG8_MMA(1, 0, At, B0); PG8_MMA(1, 1, At, B1); PG8_BAR; PG8_SCHED;
;         }
	s_add_i32 s43, s43, s35
	v_lshl_add_u64 v[138:139], v[138:139], 0, s[94:95]
	s_mov_b32 m0, s43
	ds_read_b128 v[176:179], v143 offset:49152
	ds_read_b128 v[180:183], v143 offset:50176
	ds_read_b128 v[184:187], v143 offset:51200
	ds_read_b128 v[188:191], v143 offset:52224
	ds_read_b128 v[194:197], v143 offset:53248
	ds_read_b128 v[198:201], v143 offset:54272
	ds_read_b128 v[204:207], v143 offset:55296
	ds_read_b128 v[208:211], v143 offset:56320
	global_load_lds_dwordx4 v[138:139], off
	s_add_i32 m0, s43, 0x2000
	s_add_u32 s22, s22, 0x40080
	v_lshl_add_u64 v[138:139], v[212:213], 0, s[94:95]
	s_addc_u32 s23, s23, 0
	s_add_i32 s43, s44, s35
	global_load_lds_dwordx4 v[138:139], off
	v_lshl_add_u64 v[138:139], s[22:23], 0, v[192:193]
	s_mov_b32 m0, s43
	s_nop 0
	global_load_lds_dwordx4 v[138:139], off
	v_lshl_add_u64 v[138:139], s[22:23], 0, v[128:129]
	s_add_i32 m0, s43, 0x2000
	s_nop 0
	global_load_lds_dwordx4 v[138:139], off
	v_lshl_add_u64 v[138:139], v[214:215], 0, s[94:95]
	s_mov_b32 m0, s47
	s_nop 0
	global_load_lds_dwordx4 v[138:139], off
	v_lshl_add_u64 v[138:139], v[216:217], 0, s[94:95]
	s_mov_b32 m0, s51
	s_nop 0
	global_load_lds_dwordx4 v[138:139], off
	s_waitcnt vmcnt(8)
	s_waitcnt lgkmcnt(0)
	s_barrier
	s_setprio 1
	s_waitcnt lgkmcnt(0)
	v_mfma_f32_16x16x32_bf16 v[60:63], v[144:147], v[176:179], v[60:63]
	v_mfma_f32_16x16x32_bf16 v[56:59], v[152:155], v[176:179], v[56:59]
	v_mfma_f32_16x16x32_bf16 v[44:47], v[144:147], v[184:187], v[44:47]
	v_mfma_f32_16x16x32_bf16 v[40:43], v[152:155], v[184:187], v[40:43]
	v_mfma_f32_16x16x32_bf16 v[28:31], v[144:147], v[194:197], v[28:31]
	v_mfma_f32_16x16x32_bf16 v[24:27], v[152:155], v[194:197], v[24:27]
	v_mfma_f32_16x16x32_bf16 v[12:15], v[144:147], v[204:207], v[12:15]
	v_mfma_f32_16x16x32_bf16 v[8:11], v[152:155], v[204:207], v[8:11]
	v_mfma_f32_16x16x32_bf16 v[60:63], v[148:151], v[180:183], v[60:63]
	v_mfma_f32_16x16x32_bf16 v[56:59], v[156:159], v[180:183], v[56:59]
	v_mfma_f32_16x16x32_bf16 v[44:47], v[148:151], v[188:191], v[44:47]
	v_mfma_f32_16x16x32_bf16 v[40:43], v[156:159], v[188:191], v[40:43]
	v_mfma_f32_16x16x32_bf16 v[28:31], v[148:151], v[198:201], v[28:31]
	v_mfma_f32_16x16x32_bf16 v[24:27], v[156:159], v[198:201], v[24:27]
	v_mfma_f32_16x16x32_bf16 v[12:15], v[148:151], v[208:211], v[12:15]
	v_mfma_f32_16x16x32_bf16 v[8:11], v[156:159], v[208:211], v[8:11]
	v_mfma_f32_16x16x32_bf16 v[52:55], v[160:163], v[176:179], v[52:55]
	v_mfma_f32_16x16x32_bf16 v[48:51], v[168:171], v[176:179], v[48:51]
	v_mfma_f32_16x16x32_bf16 v[36:39], v[160:163], v[184:187], v[36:39]
	v_mfma_f32_16x16x32_bf16 v[32:35], v[168:171], v[184:187], v[32:35]
	v_mfma_f32_16x16x32_bf16 v[20:23], v[160:163], v[194:197], v[20:23]
	v_mfma_f32_16x16x32_bf16 v[16:19], v[168:171], v[194:197], v[16:19]
	v_mfma_f32_16x16x32_bf16 v[4:7], v[160:163], v[204:207], v[4:7]
	v_mfma_f32_16x16x32_bf16 v[0:3], v[168:171], v[204:207], v[0:3]
	v_mfma_f32_16x16x32_bf16 v[52:55], v[164:167], v[180:183], v[52:55]
	v_mfma_f32_16x16x32_bf16 v[48:51], v[172:175], v[180:183], v[48:51]
	v_mfma_f32_16x16x32_bf16 v[36:39], v[164:167], v[188:191], v[36:39]
	v_mfma_f32_16x16x32_bf16 v[32:35], v[172:175], v[188:191], v[32:35]
	v_mfma_f32_16x16x32_bf16 v[20:23], v[164:167], v[198:201], v[20:23]
	v_mfma_f32_16x16x32_bf16 v[16:19], v[172:175], v[198:201], v[16:19]
	v_mfma_f32_16x16x32_bf16 v[4:7], v[164:167], v[208:211], v[4:7]
	v_mfma_f32_16x16x32_bf16 v[0:3], v[172:175], v[208:211], v[0:3]
	s_setprio 0
	s_barrier
	s_add_i32 s42, s42, 2
	s_add_u32 s20, s20, 0x100
	s_addc_u32 s21, s21, 0
	s_add_u32 s13, s13, 0x100
	s_addc_u32 s15, s15, 0
	s_cmp_gt_u32 s42, 13
	s_cbranch_scc1 .Lgk_exit_4
.LBB0_1336:
	s_add_u32 s22, s20, 0xfffc0080
	s_addc_u32 s23, s21, -1
	s_add_i32 s43, 0, 0x10000
	s_cmp_eq_u32 s42, 12
	s_cselect_b32 s73, s7, s23
	s_cselect_b32 s72, s6, s22
	v_add_u32_e32 v138, s43, v141
	s_cselect_b32 s23, s17, s15
	s_cselect_b32 s22, s16, s13
	s_add_i32 s44, 0, 0x14000
	ds_read_b128 v[144:147], v138
	ds_read_b128 v[148:151], v138 offset:1024
	ds_read_b128 v[152:155], v138 offset:2048
	ds_read_b128 v[156:159], v138 offset:3072
	v_add_u32_e32 v138, s44, v141
	ds_read_b128 v[160:163], v138
	ds_read_b128 v[164:167], v138 offset:1024
	ds_read_b128 v[168:171], v138 offset:2048
	ds_read_b128 v[172:175], v138 offset:3072
	v_lshl_add_u64 v[138:139], s[20:21], 0, v[134:135]
	s_add_i32 m0, s19, 0xc000
	ds_read_b128 v[176:179], v143
	ds_read_b128 v[180:183], v143 offset:1024
	ds_read_b128 v[184:187], v143 offset:2048
	ds_read_b128 v[188:191], v143 offset:3072
	ds_read_b128 v[194:197], v143 offset:4096
	ds_read_b128 v[198:201], v143 offset:5120
	ds_read_b128 v[204:207], v143 offset:6144
	ds_read_b128 v[208:211], v143 offset:7168
	global_load_lds_dwordx4 v[138:139], off
	v_lshl_add_u64 v[138:139], s[20:21], 0, v[136:137]
	s_add_i32 m0, s19, 0xe000
	s_nop 0
	global_load_lds_dwordx4 v[138:139], off
	s_waitcnt vmcnt(8)
	s_waitcnt lgkmcnt(0)
	s_barrier
; #define PG8_STAGE(bufoff, gbase, voff) do { _Pragma("unroll") for (int _i = 0; _i < 2; ++_i) \
;         __builtin_amdgcn_global_load_lds((const unsigned*)((const char*)(gbase) + (voff)[_i]), (LAS unsigned*)(lds + (bufoff) + ldsw + _i * 8192), 16, 0, 0); } while (0)
; #define PG8_LDA(dst, b, h) do { _Pragma("unroll") for (int m = 0; m < 4; ++m) _Pragma("unroll") for (int k = 0; k < 2; ++k) dst[m][k] = *(const LAS bf16x8*)(lds + PG8_SA(b, h) + aoff + m * 2048 + k * 1024); } while (0)
; #define PG8_MMA(ai, bj, At, Bt) do { __builtin_amdgcn_s_setprio(1); _Pragma("unroll") for (int m = 0; m < 4; ++m) _Pragma("unroll") for (int n = 0; n < 2; ++n) _Pragma("unroll") for (int k = 0; k < 2; ++k) \
;         acc[ai][bj][m][n] = __builtin_amdgcn_mfma_f32_16x16x32_bf16(Bt[n][k], At[m][k], acc[ai][bj][m][n], 0, 0, 0); __builtin_amdgcn_s_setprio(0); } while (0)
; #define PG8_WAIT_V(n) asm volatile("s_waitcnt vmcnt(" #n ")" ::: "memory")
; #define PG8_WAIT_L(n) asm volatile("s_waitcnt lgkmcnt(" #n ")" ::: "memory")
; #define PG8_BAR __builtin_amdgcn_s_barrier()
; #define PG8_SCHED __builtin_amdgcn_sched_barrier(0)
; template <class Epi>
; __device__ __forceinline__ void gemm_phase(LAS unsigned char* lds, const Gemm g, const Sched& S, const Epi& E, const int tid) {
;     ...
;             PG8_WAIT_V(8); PG8_WAIT_L(0); PG8_BAR; PG8_MMA(0, 0, At, B0); PG8_MMA(0, 1, At, B1); PG8_BAR; PG8_SCHED;
;             PG8_LDA(At, 0, 1); PG8_STAGE(PG8_SB(0, 0), b2, voffB); PG8_STAGE(PG8_SB(0, 1), b2 + hB, voffB); PG8_STAGE(PG8_SA(0, 0), a2, voffA);
;             PG8_WAIT_V(8); PG8_WAIT_L(0); PG8_BAR; PG8_MMA(1, 0, At, B0); PG8_MMA(1, 1, At, B1); PG8_BAR; PG8_SCHED;
	s_setprio 1
	s_waitcnt lgkmcnt(0)
	v_mfma_f32_16x16x32_bf16 v[124:127], v[144:147], v[176:179], v[124:127]
	v_mfma_f32_16x16x32_bf16 v[120:123], v[152:155], v[176:179], v[120:123]
	v_mfma_f32_16x16x32_bf16 v[108:111], v[144:147], v[184:187], v[108:111]
	v_mfma_f32_16x16x32_bf16 v[104:107], v[152:155], v[184:187], v[104:107]
	v_mfma_f32_16x16x32_bf16 v[92:95], v[144:147], v[194:197], v[92:95]
	v_mfma_f32_16x16x32_bf16 v[88:91], v[152:155], v[194:197], v[88:91]
	v_mfma_f32_16x16x32_bf16 v[76:79], v[144:147], v[204:207], v[76:79]
	v_mfma_f32_16x16x32_bf16 v[72:75], v[152:155], v[204:207], v[72:75]
	v_mfma_f32_16x16x32_bf16 v[124:127], v[148:151], v[180:183], v[124:127]
	v_mfma_f32_16x16x32_bf16 v[120:123], v[156:159], v[180:183], v[120:123]
	v_mfma_f32_16x16x32_bf16 v[108:111], v[148:151], v[188:191], v[108:111]
	v_mfma_f32_16x16x32_bf16 v[104:107], v[156:159], v[188:191], v[104:107]
	v_mfma_f32_16x16x32_bf16 v[92:95], v[148:151], v[198:201], v[92:95]
	v_mfma_f32_16x16x32_bf16 v[88:91], v[156:159], v[198:201], v[88:91]
	v_mfma_f32_16x16x32_bf16 v[76:79], v[148:151], v[208:211], v[76:79]
	v_mfma_f32_16x16x32_bf16 v[72:75], v[156:159], v[208:211], v[72:75]
	v_mfma_f32_16x16x32_bf16 v[116:119], v[160:163], v[176:179], v[116:119]
	v_mfma_f32_16x16x32_bf16 v[112:115], v[168:171], v[176:179], v[112:115]
	v_mfma_f32_16x16x32_bf16 v[100:103], v[160:163], v[184:187], v[100:103]
	v_mfma_f32_16x16x32_bf16 v[96:99], v[168:171], v[184:187], v[96:99]
	v_mfma_f32_16x16x32_bf16 v[84:87], v[160:163], v[194:197], v[84:87]
	v_mfma_f32_16x16x32_bf16 v[80:83], v[168:171], v[194:197], v[80:83]
	v_mfma_f32_16x16x32_bf16 v[68:71], v[160:163], v[204:207], v[68:71]
	v_mfma_f32_16x16x32_bf16 v[64:67], v[168:171], v[204:207], v[64:67]
	v_mfma_f32_16x16x32_bf16 v[116:119], v[164:167], v[180:183], v[116:119]
	v_mfma_f32_16x16x32_bf16 v[112:115], v[172:175], v[180:183], v[112:115]
	v_mfma_f32_16x16x32_bf16 v[100:103], v[164:167], v[188:191], v[100:103]
	v_mfma_f32_16x16x32_bf16 v[96:99], v[172:175], v[188:191], v[96:99]
	v_mfma_f32_16x16x32_bf16 v[84:87], v[164:167], v[198:201], v[84:87]
	v_mfma_f32_16x16x32_bf16 v[80:83], v[172:175], v[198:201], v[80:83]
	v_mfma_f32_16x16x32_bf16 v[68:71], v[164:167], v[208:211], v[68:71]
	v_mfma_f32_16x16x32_bf16 v[64:67], v[172:175], v[208:211], v[64:67]
	s_setprio 0
	s_barrier
	s_add_i32 s43, s43, s35
	v_lshl_add_u64 v[138:139], s[22:23], 0, v[192:193]
	s_mov_b32 m0, s43
	ds_read_b128 v[176:179], v143 offset:16384
	ds_read_b128 v[180:183], v143 offset:17408
	ds_read_b128 v[184:187], v143 offset:18432
	ds_read_b128 v[188:191], v143 offset:19456
	ds_read_b128 v[194:197], v143 offset:20480
	ds_read_b128 v[198:201], v143 offset:21504
	ds_read_b128 v[204:207], v143 offset:22528
	ds_read_b128 v[208:211], v143 offset:23552
	global_load_lds_dwordx4 v[138:139], off
	s_add_i32 m0, s43, 0x2000
	s_add_u32 s76, s22, 0x40000
	v_lshl_add_u64 v[212:213], s[22:23], 0, v[128:129]
	s_addc_u32 s77, s23, 0
	s_add_i32 s43, s44, s35
	global_load_lds_dwordx4 v[212:213], off
	v_lshl_add_u64 v[214:215], s[76:77], 0, v[192:193]
	s_mov_b32 m0, s43
	v_lshl_add_u64 v[216:217], s[72:73], 0, v[130:131]
	global_load_lds_dwordx4 v[214:215], off
	v_lshl_add_u64 v[214:215], s[76:77], 0, v[128:129]
	s_add_i32 m0, s43, 0x2000
	s_nop 0
	global_load_lds_dwordx4 v[214:215], off
	v_lshl_add_u64 v[214:215], s[72:73], 0, v[132:133]
	s_mov_b32 m0, s19
	s_nop 0
	global_load_lds_dwordx4 v[214:215], off
	s_mov_b32 m0, s39
	s_nop 0
	global_load_lds_dwordx4 v[216:217], off
	s_waitcnt vmcnt(8)
	s_waitcnt lgkmcnt(0)
	s_barrier
	s_setprio 1
	s_waitcnt lgkmcnt(0)
	v_mfma_f32_16x16x32_bf16 v[60:63], v[144:147], v[176:179], v[60:63]
	v_mfma_f32_16x16x32_bf16 v[56:59], v[152:155], v[176:179], v[56:59]
	v_mfma_f32_16x16x32_bf16 v[44:47], v[144:147], v[184:187], v[44:47]
	v_mfma_f32_16x16x32_bf16 v[40:43], v[152:155], v[184:187], v[40:43]
	v_mfma_f32_16x16x32_bf16 v[28:31], v[144:147], v[194:197], v[28:31]
	v_mfma_f32_16x16x32_bf16 v[24:27], v[152:155], v[194:197], v[24:27]
	v_mfma_f32_16x16x32_bf16 v[12:15], v[144:147], v[204:207], v[12:15]
	v_mfma_f32_16x16x32_bf16 v[8:11], v[152:155], v[204:207], v[8:11]
	v_mfma_f32_16x16x32_bf16 v[60:63], v[148:151], v[180:183], v[60:63]
	v_mfma_f32_16x16x32_bf16 v[56:59], v[156:159], v[180:183], v[56:59]
	v_mfma_f32_16x16x32_bf16 v[44:47], v[148:151], v[188:191], v[44:47]
	v_mfma_f32_16x16x32_bf16 v[40:43], v[156:159], v[188:191], v[40:43]
	v_mfma_f32_16x16x32_bf16 v[28:31], v[148:151], v[198:201], v[28:31]
	v_mfma_f32_16x16x32_bf16 v[24:27], v[156:159], v[198:201], v[24:27]
	v_mfma_f32_16x16x32_bf16 v[12:15], v[148:151], v[208:211], v[12:15]
	v_mfma_f32_16x16x32_bf16 v[8:11], v[156:159], v[208:211], v[8:11]
	v_mfma_f32_16x16x32_bf16 v[52:55], v[160:163], v[176:179], v[52:55]
	v_mfma_f32_16x16x32_bf16 v[48:51], v[168:171], v[176:179], v[48:51]
	v_mfma_f32_16x16x32_bf16 v[36:39], v[160:163], v[184:187], v[36:39]
	v_mfma_f32_16x16x32_bf16 v[32:35], v[168:171], v[184:187], v[32:35]
	v_mfma_f32_16x16x32_bf16 v[20:23], v[160:163], v[194:197], v[20:23]
	v_mfma_f32_16x16x32_bf16 v[16:19], v[168:171], v[194:197], v[16:19]
	v_mfma_f32_16x16x32_bf16 v[4:7], v[160:163], v[204:207], v[4:7]
	v_mfma_f32_16x16x32_bf16 v[0:3], v[168:171], v[204:207], v[0:3]
	v_mfma_f32_16x16x32_bf16 v[52:55], v[164:167], v[180:183], v[52:55]
	v_mfma_f32_16x16x32_bf16 v[48:51], v[172:175], v[180:183], v[48:51]
	v_mfma_f32_16x16x32_bf16 v[36:39], v[164:167], v[188:191], v[36:39]
	v_mfma_f32_16x16x32_bf16 v[32:35], v[172:175], v[188:191], v[32:35]
	v_mfma_f32_16x16x32_bf16 v[20:23], v[164:167], v[198:201], v[20:23]
	v_mfma_f32_16x16x32_bf16 v[16:19], v[172:175], v[198:201], v[16:19]
	v_mfma_f32_16x16x32_bf16 v[4:7], v[164:167], v[208:211], v[4:7]
	v_mfma_f32_16x16x32_bf16 v[0:3], v[172:175], v[208:211], v[0:3]
	s_setprio 0
	s_barrier
; #define PG8_STAGE(bufoff, gbase, voff) do { _Pragma("unroll") for (int _i = 0; _i < 2; ++_i) \
;         __builtin_amdgcn_global_load_lds((const unsigned*)((const char*)(gbase) + (voff)[_i]), (LAS unsigned*)(lds + (bufoff) + ldsw + _i * 8192), 16, 0, 0); } while (0)
; #define PG8_LDA(dst, b, h) do { _Pragma("unroll") for (int m = 0; m < 4; ++m) _Pragma("unroll") for (int k = 0; k < 2; ++k) dst[m][k] = *(const LAS bf16x8*)(lds + PG8_SA(b, h) + aoff + m * 2048 + k * 1024); } while (0)
; #define PG8_LDB(dst, b, h) do { _Pragma("unroll") for (int n = 0; n < 2; ++n) _Pragma("unroll") for (int k = 0; k < 2; ++k) dst[n][k] = *(const LAS bf16x8*)(lds + PG8_SB(b, h) + boff + n * 2048 + k * 1024); } while (0)
; #define PG8_MMA(ai, bj, At, Bt) do { __builtin_amdgcn_s_setprio(1); _Pragma("unroll") for (int m = 0; m < 4; ++m) _Pragma("unroll") for (int n = 0; n < 2; ++n) _Pragma("unroll") for (int k = 0; k < 2; ++k) \
;         acc[ai][bj][m][n] = __builtin_amdgcn_mfma_f32_16x16x32_bf16(Bt[n][k], At[m][k], acc[ai][bj][m][n], 0, 0, 0); __builtin_amdgcn_s_setprio(0); } while (0)
; #define PG8_WAIT_V(n) asm volatile("s_waitcnt vmcnt(" #n ")" ::: "memory")
; #define PG8_WAIT_L(n) asm volatile("s_waitcnt lgkmcnt(" #n ")" ::: "memory")
; #define PG8_BAR __builtin_amdgcn_s_barrier()
; #define PG8_SCHED __builtin_amdgcn_sched_barrier(0)
; template <class Epi>
; __device__ __forceinline__ void gemm_phase(LAS unsigned char* lds, const Gemm g, const Sched& S, const Epi& E, const int tid) {
;     ...
;             PG8_LDB(B0, 1, 0); PG8_LDB(B1, 1, 1); PG8_SCHED; PG8_LDA(At, 1, 0); PG8_STAGE(PG8_SA(0, 1), a2 + hA, voffA);
;             PG8_WAIT_V(8); PG8_WAIT_L(0); PG8_BAR; PG8_MMA(0, 0, At, B0); PG8_MMA(0, 1, At, B1); PG8_BAR; PG8_SCHED;
	s_add_i32 s43, 0, 0x18000
	s_add_i32 s44, 0, 0x1c000
	v_add_u32_e32 v156, s43, v141
	v_add_u32_e32 v172, s44, v141
	ds_read_b128 v[144:147], v156
	ds_read_b128 v[148:151], v156 offset:1024
	ds_read_b128 v[152:155], v156 offset:2048
	ds_read_b128 v[156:159], v156 offset:3072
	ds_read_b128 v[160:163], v172
	ds_read_b128 v[164:167], v172 offset:1024
	ds_read_b128 v[168:171], v172 offset:2048
	ds_read_b128 v[172:175], v172 offset:3072
	s_add_u32 s72, s72, 0x40000
	s_addc_u32 s73, s73, 0
	s_mov_b32 m0, s40
	v_lshl_add_u64 v[218:219], s[72:73], 0, v[132:133]
	ds_read_b128 v[176:179], v143 offset:32768
	ds_read_b128 v[180:183], v143 offset:33792
	ds_read_b128 v[184:187], v143 offset:34816
	ds_read_b128 v[188:191], v143 offset:35840
	ds_read_b128 v[194:197], v143 offset:36864
	ds_read_b128 v[198:201], v143 offset:37888
	ds_read_b128 v[204:207], v143 offset:38912
	ds_read_b128 v[208:211], v143 offset:39936
	global_load_lds_dwordx4 v[218:219], off
	v_lshl_add_u64 v[218:219], s[72:73], 0, v[130:131]
	s_mov_b32 m0, s45
	s_nop 0
	global_load_lds_dwordx4 v[218:219], off
	s_waitcnt vmcnt(8)
	s_waitcnt lgkmcnt(0)
	s_barrier
	s_setprio 1
	s_waitcnt lgkmcnt(0)
	v_mfma_f32_16x16x32_bf16 v[124:127], v[144:147], v[176:179], v[124:127]
	v_mfma_f32_16x16x32_bf16 v[120:123], v[152:155], v[176:179], v[120:123]
	v_mfma_f32_16x16x32_bf16 v[108:111], v[144:147], v[184:187], v[108:111]
	v_mfma_f32_16x16x32_bf16 v[104:107], v[152:155], v[184:187], v[104:107]
	v_mfma_f32_16x16x32_bf16 v[92:95], v[144:147], v[194:197], v[92:95]
	v_mfma_f32_16x16x32_bf16 v[88:91], v[152:155], v[194:197], v[88:91]
	v_mfma_f32_16x16x32_bf16 v[76:79], v[144:147], v[204:207], v[76:79]
	v_mfma_f32_16x16x32_bf16 v[72:75], v[152:155], v[204:207], v[72:75]
	v_mfma_f32_16x16x32_bf16 v[124:127], v[148:151], v[180:183], v[124:127]
	v_mfma_f32_16x16x32_bf16 v[120:123], v[156:159], v[180:183], v[120:123]
	v_mfma_f32_16x16x32_bf16 v[108:111], v[148:151], v[188:191], v[108:111]
	v_mfma_f32_16x16x32_bf16 v[104:107], v[156:159], v[188:191], v[104:107]
	v_mfma_f32_16x16x32_bf16 v[92:95], v[148:151], v[198:201], v[92:95]
	v_mfma_f32_16x16x32_bf16 v[88:91], v[156:159], v[198:201], v[88:91]
	v_mfma_f32_16x16x32_bf16 v[76:79], v[148:151], v[208:211], v[76:79]
	v_mfma_f32_16x16x32_bf16 v[72:75], v[156:159], v[208:211], v[72:75]
	v_mfma_f32_16x16x32_bf16 v[116:119], v[160:163], v[176:179], v[116:119]
	v_mfma_f32_16x16x32_bf16 v[112:115], v[168:171], v[176:179], v[112:115]
	v_mfma_f32_16x16x32_bf16 v[100:103], v[160:163], v[184:187], v[100:103]
	v_mfma_f32_16x16x32_bf16 v[96:99], v[168:171], v[184:187], v[96:99]
	v_mfma_f32_16x16x32_bf16 v[84:87], v[160:163], v[194:197], v[84:87]
	v_mfma_f32_16x16x32_bf16 v[80:83], v[168:171], v[194:197], v[80:83]
	v_mfma_f32_16x16x32_bf16 v[68:71], v[160:163], v[204:207], v[68:71]
	v_mfma_f32_16x16x32_bf16 v[64:67], v[168:171], v[204:207], v[64:67]
	v_mfma_f32_16x16x32_bf16 v[116:119], v[164:167], v[180:183], v[116:119]
	v_mfma_f32_16x16x32_bf16 v[112:115], v[172:175], v[180:183], v[112:115]
	v_mfma_f32_16x16x32_bf16 v[100:103], v[164:167], v[188:191], v[100:103]
	v_mfma_f32_16x16x32_bf16 v[96:99], v[172:175], v[188:191], v[96:99]
	v_mfma_f32_16x16x32_bf16 v[84:87], v[164:167], v[198:201], v[84:87]
	v_mfma_f32_16x16x32_bf16 v[80:83], v[172:175], v[198:201], v[80:83]
	v_mfma_f32_16x16x32_bf16 v[68:71], v[164:167], v[208:211], v[68:71]
	v_mfma_f32_16x16x32_bf16 v[64:67], v[172:175], v[208:211], v[64:67]
	s_setprio 0
	s_barrier
; #define PG8_STAGE(bufoff, gbase, voff) do { _Pragma("unroll") for (int _i = 0; _i < 2; ++_i) \
;         __builtin_amdgcn_global_load_lds((const unsigned*)((const char*)(gbase) + (voff)[_i]), (LAS unsigned*)(lds + (bufoff) + ldsw + _i * 8192), 16, 0, 0); } while (0)
; #define PG8_LDA(dst, b, h) do { _Pragma("unroll") for (int m = 0; m < 4; ++m) _Pragma("unroll") for (int k = 0; k < 2; ++k) dst[m][k] = *(const LAS bf16x8*)(lds + PG8_SA(b, h) + aoff + m * 2048 + k * 1024); } while (0)
; #define PG8_MMA(ai, bj, At, Bt) do { __builtin_amdgcn_s_setprio(1); _Pragma("unroll") for (int m = 0; m < 4; ++m) _Pragma("unroll") for (int n = 0; n < 2; ++n) _Pragma("unroll") for (int k = 0; k < 2; ++k) \
;         acc[ai][bj][m][n] = __builtin_amdgcn_mfma_f32_16x16x32_bf16(Bt[n][k], At[m][k], acc[ai][bj][m][n], 0, 0, 0); __builtin_amdgcn_s_setprio(0); } while (0)
; #define PG8_WAIT_V(n) asm volatile("s_waitcnt vmcnt(" #n ")" ::: "memory")
; #define PG8_WAIT_L(n) asm volatile("s_waitcnt lgkmcnt(" #n ")" ::: "memory")
; #define PG8_BAR __builtin_amdgcn_s_barrier()
; #define PG8_SCHED __builtin_amdgcn_sched_barrier(0)
; template <class Epi>
; __device__ __forceinline__ void gemm_phase(LAS unsigned char* lds, const Gemm g, const Sched& S, const Epi& E, const int tid) {
;     ...
;             PG8_LDA(At, 1, 1); PG8_STAGE(PG8_SB(1, 0), b3, voffB); PG8_STAGE(PG8_SB(1, 1), b3 + hB, voffB); PG8_STAGE(PG8_SA(1, 0), a3, voffA);
;             PG8_WAIT_V(8); PG8_WAIT_L(0); PG8_BAR; PG8_MMA(1, 0, At, B0); PG8_MMA(1, 1, At, B1); PG8_BAR; PG8_SCHED;
;         }
	s_add_i32 s43, s43, s35
	v_lshl_add_u64 v[138:139], v[138:139], 0, s[94:95]
	s_mov_b32 m0, s43
	ds_read_b128 v[176:179], v143 offset:49152
	ds_read_b128 v[180:183], v143 offset:50176
	ds_read_b128 v[184:187], v143 offset:51200
	ds_read_b128 v[188:191], v143 offset:52224
	ds_read_b128 v[194:197], v143 offset:53248
	ds_read_b128 v[198:201], v143 offset:54272
	ds_read_b128 v[204:207], v143 offset:55296
	ds_read_b128 v[208:211], v143 offset:56320
	global_load_lds_dwordx4 v[138:139], off
	s_add_i32 m0, s43, 0x2000
	s_add_u32 s22, s22, 0x40080
	v_lshl_add_u64 v[138:139], v[212:213], 0, s[94:95]
	s_addc_u32 s23, s23, 0
	s_add_i32 s43, s44, s35
	global_load_lds_dwordx4 v[138:139], off
	v_lshl_add_u64 v[138:139], s[22:23], 0, v[192:193]
	s_mov_b32 m0, s43
	s_nop 0
	global_load_lds_dwordx4 v[138:139], off
	v_lshl_add_u64 v[138:139], s[22:23], 0, v[128:129]
	s_add_i32 m0, s43, 0x2000
	s_nop 0
	global_load_lds_dwordx4 v[138:139], off
	v_lshl_add_u64 v[138:139], v[214:215], 0, s[94:95]
	s_mov_b32 m0, s47
	s_nop 0
	global_load_lds_dwordx4 v[138:139], off
	v_lshl_add_u64 v[138:139], v[216:217], 0, s[94:95]
	s_mov_b32 m0, s51
	s_nop 0
	global_load_lds_dwordx4 v[138:139], off
	s_waitcnt vmcnt(8)
	s_waitcnt lgkmcnt(0)
	s_barrier
	s_setprio 1
	s_waitcnt lgkmcnt(0)
	v_mfma_f32_16x16x32_bf16 v[60:63], v[144:147], v[176:179], v[60:63]
	v_mfma_f32_16x16x32_bf16 v[56:59], v[152:155], v[176:179], v[56:59]
	v_mfma_f32_16x16x32_bf16 v[44:47], v[144:147], v[184:187], v[44:47]
	v_mfma_f32_16x16x32_bf16 v[40:43], v[152:155], v[184:187], v[40:43]
	v_mfma_f32_16x16x32_bf16 v[28:31], v[144:147], v[194:197], v[28:31]
	v_mfma_f32_16x16x32_bf16 v[24:27], v[152:155], v[194:197], v[24:27]
	v_mfma_f32_16x16x32_bf16 v[12:15], v[144:147], v[204:207], v[12:15]
	v_mfma_f32_16x16x32_bf16 v[8:11], v[152:155], v[204:207], v[8:11]
	v_mfma_f32_16x16x32_bf16 v[60:63], v[148:151], v[180:183], v[60:63]
	v_mfma_f32_16x16x32_bf16 v[56:59], v[156:159], v[180:183], v[56:59]
	v_mfma_f32_16x16x32_bf16 v[44:47], v[148:151], v[188:191], v[44:47]
	v_mfma_f32_16x16x32_bf16 v[40:43], v[156:159], v[188:191], v[40:43]
	v_mfma_f32_16x16x32_bf16 v[28:31], v[148:151], v[198:201], v[28:31]
	v_mfma_f32_16x16x32_bf16 v[24:27], v[156:159], v[198:201], v[24:27]
	v_mfma_f32_16x16x32_bf16 v[12:15], v[148:151], v[208:211], v[12:15]
	v_mfma_f32_16x16x32_bf16 v[8:11], v[156:159], v[208:211], v[8:11]
	v_mfma_f32_16x16x32_bf16 v[52:55], v[160:163], v[176:179], v[52:55]
	v_mfma_f32_16x16x32_bf16 v[48:51], v[168:171], v[176:179], v[48:51]
	v_mfma_f32_16x16x32_bf16 v[36:39], v[160:163], v[184:187], v[36:39]
	v_mfma_f32_16x16x32_bf16 v[32:35], v[168:171], v[184:187], v[32:35]
	v_mfma_f32_16x16x32_bf16 v[20:23], v[160:163], v[194:197], v[20:23]
	v_mfma_f32_16x16x32_bf16 v[16:19], v[168:171], v[194:197], v[16:19]
	v_mfma_f32_16x16x32_bf16 v[4:7], v[160:163], v[204:207], v[4:7]
	v_mfma_f32_16x16x32_bf16 v[0:3], v[168:171], v[204:207], v[0:3]
	v_mfma_f32_16x16x32_bf16 v[52:55], v[164:167], v[180:183], v[52:55]
	v_mfma_f32_16x16x32_bf16 v[48:51], v[172:175], v[180:183], v[48:51]
	v_mfma_f32_16x16x32_bf16 v[36:39], v[164:167], v[188:191], v[36:39]
	v_mfma_f32_16x16x32_bf16 v[32:35], v[172:175], v[188:191], v[32:35]
	v_mfma_f32_16x16x32_bf16 v[20:23], v[164:167], v[198:201], v[20:23]
	v_mfma_f32_16x16x32_bf16 v[16:19], v[172:175], v[198:201], v[16:19]
	v_mfma_f32_16x16x32_bf16 v[4:7], v[164:167], v[208:211], v[4:7]
	v_mfma_f32_16x16x32_bf16 v[0:3], v[172:175], v[208:211], v[0:3]
	s_setprio 0
	s_barrier
	s_add_i32 s42, s42, 2
	s_add_u32 s20, s20, 0x100
	s_addc_u32 s21, s21, 0
	s_add_u32 s13, s13, 0x100
	s_addc_u32 s15, s15, 0
	s_cmp_gt_u32 s42, 13
	s_cbranch_scc0 .LBB0_1336

; #define PG8_STAGE(bufoff, gbase, voff) do { _Pragma("unroll") for (int _i = 0; _i < 2; ++_i) \
;         __builtin_amdgcn_global_load_lds((const unsigned*)((const char*)(gbase) + (voff)[_i]), (LAS unsigned*)(lds + (bufoff) + ldsw + _i * 8192), 16, 0, 0); } while (0)
; #define PG8_LDA(dst, b, h) do { _Pragma("unroll") for (int m = 0; m < 4; ++m) _Pragma("unroll") for (int k = 0; k < 2; ++k) dst[m][k] = *(const LAS bf16x8*)(lds + PG8_SA(b, h) + aoff + m * 2048 + k * 1024); } while (0)
; #define PG8_LDB(dst, b, h) do { _Pragma("unroll") for (int n = 0; n < 2; ++n) _Pragma("unroll") for (int k = 0; k < 2; ++k) dst[n][k] = *(const LAS bf16x8*)(lds + PG8_SB(b, h) + boff + n * 2048 + k * 1024); } while (0)
; #define PG8_MMA(ai, bj, At, Bt) do { __builtin_amdgcn_s_setprio(1); _Pragma("unroll") for (int m = 0; m < 4; ++m) _Pragma("unroll") for (int n = 0; n < 2; ++n) _Pragma("unroll") for (int k = 0; k < 2; ++k) \
;         acc[ai][bj][m][n] = __builtin_amdgcn_mfma_f32_16x16x32_bf16(Bt[n][k], At[m][k], acc[ai][bj][m][n], 0, 0, 0); __builtin_amdgcn_s_setprio(0); } while (0)
; #define PG8_WAIT_V(n) asm volatile("s_waitcnt vmcnt(" #n ")" ::: "memory")
; #define PG8_WAIT_L(n) asm volatile("s_waitcnt lgkmcnt(" #n ")" ::: "memory")
; #define PG8_BAR __builtin_amdgcn_s_barrier()
; template <class Epi>
; __device__ __forceinline__ void gemm_phase(LAS unsigned char* lds, const Gemm g, const Sched& S, const Epi& E, const int tid) {
;     ...
;         const char* nA = cA; const char* nB = cB; if (has_next) S.ptrs(nxt, nA, nB);
;         for (int t = 0; t < nt; t += 2) {
;             const bool last = (t == nt - 2);
;             const char* a1 = cA + (size_t)(t + 1) * kstep;
;             const char* a2 = last ? nA : cA + (size_t)(t + 2) * kstep; const char* b2 = last ? nB : cB + (size_t)(t + 2) * kstep;
;             const char* a3 = a2 + kstep; const char* b3 = b2 + kstep;
;             PG8_LDB(B0, 0, 0); PG8_LDB(B1, 0, 1); PG8_SCHED; PG8_LDA(At, 0, 0); PG8_STAGE(PG8_SA(1, 1), a1 + hA, voffA);
;             PG8_WAIT_V(8); PG8_WAIT_L(0); PG8_BAR; PG8_MMA(0, 0, At, B0); PG8_MMA(0, 1, At, B1); PG8_BAR; PG8_SCHED;
;             PG8_LDA(At, 0, 1); PG8_STAGE(PG8_SB(0, 0), b2, voffB); PG8_STAGE(PG8_SB(0, 1), b2 + hB, voffB); PG8_STAGE(PG8_SA(0, 0), a2, voffA);
;             PG8_WAIT_V(8); PG8_WAIT_L(0); PG8_BAR; PG8_MMA(1, 0, At, B0); PG8_MMA(1, 1, At, B1); PG8_BAR; PG8_SCHED;
.LBB0_1410:
	s_add_u32 s80, s18, 0x100
	s_addc_u32 s81, s19, 0
	s_mov_b32 vcc_lo, -2
	s_add_u32 s18, s16, 0x100
	s_addc_u32 s19, s17, 0
	s_add_i32 s43, 0, 0x10000
	s_cmp_eq_u32 vcc_lo, 40
	s_cselect_b32 s23, s7, s19
	s_cselect_b32 s22, s6, s18
	s_cselect_b32 s21, s15, s81
	s_cselect_b32 s20, s14, s80
	s_add_i32 s44, 0, 0x14000
	v_add_u32_e32 v92, s43, v157
	v_add_u32_e32 v154, s44, v157
	ds_read_b128 v[64:67], v92
	ds_read_b128 v[68:71], v92 offset:1024
	ds_read_b128 v[80:83], v92 offset:2048
	ds_read_b128 v[92:95], v92 offset:3072
	ds_read_b128 v[160:163], v154
	ds_read_b128 v[164:167], v154 offset:1024
	ds_read_b128 v[168:171], v154 offset:2048
	ds_read_b128 v[172:175], v154 offset:3072
	v_lshl_add_u64 v[154:155], s[16:17], 0, v[150:151]
	s_add_i32 m0, s40, 0xc000
	ds_read_b128 v[176:179], v159
	ds_read_b128 v[180:183], v159 offset:1024
	ds_read_b128 v[184:187], v159 offset:2048
	ds_read_b128 v[188:191], v159 offset:3072
	ds_read_b128 v[194:197], v159 offset:4096
	ds_read_b128 v[198:201], v159 offset:5120
	ds_read_b128 v[204:207], v159 offset:6144
	ds_read_b128 v[208:211], v159 offset:7168
	global_load_lds_dwordx4 v[154:155], off
	v_lshl_add_u64 v[154:155], s[16:17], 0, v[152:153]
	s_add_i32 m0, s40, 0xe000
	s_nop 0
	global_load_lds_dwordx4 v[154:155], off
	s_waitcnt vmcnt(8)
	s_waitcnt lgkmcnt(0)
	s_barrier
	s_setprio 1
	s_waitcnt lgkmcnt(0)
	v_mfma_f32_16x16x32_bf16 v[140:143], v[64:67], v[176:179], 0
	v_mfma_f32_16x16x32_bf16 v[136:139], v[80:83], v[176:179], 0
	v_mfma_f32_16x16x32_bf16 v[132:135], v[64:67], v[184:187], 0
	v_mfma_f32_16x16x32_bf16 v[128:131], v[80:83], v[184:187], 0
	v_mfma_f32_16x16x32_bf16 v[108:111], v[64:67], v[194:197], 0
	v_mfma_f32_16x16x32_bf16 v[104:107], v[80:83], v[194:197], 0
	v_mfma_f32_16x16x32_bf16 v[100:103], v[64:67], v[204:207], 0
	v_mfma_f32_16x16x32_bf16 v[96:99], v[80:83], v[204:207], 0
	v_mfma_f32_16x16x32_bf16 v[140:143], v[68:71], v[180:183], v[140:143]
	v_mfma_f32_16x16x32_bf16 v[136:139], v[92:95], v[180:183], v[136:139]
	v_mfma_f32_16x16x32_bf16 v[132:135], v[68:71], v[188:191], v[132:135]
	v_mfma_f32_16x16x32_bf16 v[128:131], v[92:95], v[188:191], v[128:131]
	v_mfma_f32_16x16x32_bf16 v[108:111], v[68:71], v[198:201], v[108:111]
	v_mfma_f32_16x16x32_bf16 v[104:107], v[92:95], v[198:201], v[104:107]
	v_mfma_f32_16x16x32_bf16 v[100:103], v[68:71], v[208:211], v[100:103]
	v_mfma_f32_16x16x32_bf16 v[96:99], v[92:95], v[208:211], v[96:99]
	v_mfma_f32_16x16x32_bf16 v[124:127], v[160:163], v[176:179], 0
	v_mfma_f32_16x16x32_bf16 v[120:123], v[168:171], v[176:179], 0
	v_mfma_f32_16x16x32_bf16 v[116:119], v[160:163], v[184:187], 0
	v_mfma_f32_16x16x32_bf16 v[112:115], v[168:171], v[184:187], 0
	v_mfma_f32_16x16x32_bf16 v[88:91], v[160:163], v[194:197], 0
	v_mfma_f32_16x16x32_bf16 v[84:87], v[168:171], v[194:197], 0
	v_mfma_f32_16x16x32_bf16 v[76:79], v[160:163], v[204:207], 0
	v_mfma_f32_16x16x32_bf16 v[72:75], v[168:171], v[204:207], 0
	v_mfma_f32_16x16x32_bf16 v[124:127], v[164:167], v[180:183], v[124:127]
	v_mfma_f32_16x16x32_bf16 v[120:123], v[172:175], v[180:183], v[120:123]
	v_mfma_f32_16x16x32_bf16 v[116:119], v[164:167], v[188:191], v[116:119]
	v_mfma_f32_16x16x32_bf16 v[112:115], v[172:175], v[188:191], v[112:115]
	v_mfma_f32_16x16x32_bf16 v[88:91], v[164:167], v[198:201], v[88:91]
	v_mfma_f32_16x16x32_bf16 v[84:87], v[172:175], v[198:201], v[84:87]
	v_mfma_f32_16x16x32_bf16 v[76:79], v[164:167], v[208:211], v[76:79]
	v_mfma_f32_16x16x32_bf16 v[72:75], v[172:175], v[208:211], v[72:75]
	s_setprio 0
	s_barrier
	s_add_i32 s16, s43, s39
	v_lshl_add_u64 v[154:155], s[20:21], 0, v[192:193]
	s_mov_b32 m0, s16
	ds_read_b128 v[176:179], v159 offset:16384
	ds_read_b128 v[180:183], v159 offset:17408
	ds_read_b128 v[184:187], v159 offset:18432
	ds_read_b128 v[188:191], v159 offset:19456
	ds_read_b128 v[194:197], v159 offset:20480
	ds_read_b128 v[198:201], v159 offset:21504
	ds_read_b128 v[204:207], v159 offset:22528
	ds_read_b128 v[208:211], v159 offset:23552
	global_load_lds_dwordx4 v[154:155], off
	s_add_i32 m0, s16, 0x2000
	s_add_u32 s16, s20, 0xb0000
	v_lshl_add_u64 v[212:213], s[20:21], 0, v[144:145]
	s_addc_u32 s17, s21, 0
	s_add_i32 s43, s44, s39
	global_load_lds_dwordx4 v[212:213], off
	v_lshl_add_u64 v[214:215], s[16:17], 0, v[192:193]
	s_mov_b32 m0, s43
	v_lshl_add_u64 v[216:217], s[22:23], 0, v[146:147]
	global_load_lds_dwordx4 v[214:215], off
	v_lshl_add_u64 v[214:215], s[16:17], 0, v[144:145]
	s_add_i32 m0, s43, 0x2000
	s_nop 0
	global_load_lds_dwordx4 v[214:215], off
	v_lshl_add_u64 v[214:215], s[22:23], 0, v[148:149]
	s_mov_b32 m0, s40
	s_nop 0
	global_load_lds_dwordx4 v[214:215], off
	s_mov_b32 m0, s73
	s_nop 0
	global_load_lds_dwordx4 v[216:217], off
	s_waitcnt vmcnt(8)
	s_waitcnt lgkmcnt(0)
	s_barrier
; #define PG8_STAGE(bufoff, gbase, voff) do { _Pragma("unroll") for (int _i = 0; _i < 2; ++_i) \
;         __builtin_amdgcn_global_load_lds((const unsigned*)((const char*)(gbase) + (voff)[_i]), (LAS unsigned*)(lds + (bufoff) + ldsw + _i * 8192), 16, 0, 0); } while (0)
; #define PG8_LDA(dst, b, h) do { _Pragma("unroll") for (int m = 0; m < 4; ++m) _Pragma("unroll") for (int k = 0; k < 2; ++k) dst[m][k] = *(const LAS bf16x8*)(lds + PG8_SA(b, h) + aoff + m * 2048 + k * 1024); } while (0)
; #define PG8_LDB(dst, b, h) do { _Pragma("unroll") for (int n = 0; n < 2; ++n) _Pragma("unroll") for (int k = 0; k < 2; ++k) dst[n][k] = *(const LAS bf16x8*)(lds + PG8_SB(b, h) + boff + n * 2048 + k * 1024); } while (0)
; #define PG8_MMA(ai, bj, At, Bt) do { __builtin_amdgcn_s_setprio(1); _Pragma("unroll") for (int m = 0; m < 4; ++m) _Pragma("unroll") for (int n = 0; n < 2; ++n) _Pragma("unroll") for (int k = 0; k < 2; ++k) \
;         acc[ai][bj][m][n] = __builtin_amdgcn_mfma_f32_16x16x32_bf16(Bt[n][k], At[m][k], acc[ai][bj][m][n], 0, 0, 0); __builtin_amdgcn_s_setprio(0); } while (0)
; #define PG8_WAIT_V(n) asm volatile("s_waitcnt vmcnt(" #n ")" ::: "memory")
; #define PG8_WAIT_L(n) asm volatile("s_waitcnt lgkmcnt(" #n ")" ::: "memory")
; #define PG8_BAR __builtin_amdgcn_s_barrier()
; #define PG8_SCHED __builtin_amdgcn_sched_barrier(0)
; template <class Epi>
; __device__ __forceinline__ void gemm_phase(LAS unsigned char* lds, const Gemm g, const Sched& S, const Epi& E, const int tid) {
;     ...
;             PG8_WAIT_V(8); PG8_WAIT_L(0); PG8_BAR; PG8_MMA(1, 0, At, B0); PG8_MMA(1, 1, At, B1); PG8_BAR; PG8_SCHED;
;             PG8_LDB(B0, 1, 0); PG8_LDB(B1, 1, 1); PG8_SCHED; PG8_LDA(At, 1, 0); PG8_STAGE(PG8_SA(0, 1), a2 + hA, voffA);
;             PG8_WAIT_V(8); PG8_WAIT_L(0); PG8_BAR; PG8_MMA(0, 0, At, B0); PG8_MMA(0, 1, At, B1); PG8_BAR; PG8_SCHED;
	s_setprio 1
	s_waitcnt lgkmcnt(0)
	v_mfma_f32_16x16x32_bf16 v[60:63], v[64:67], v[176:179], 0
	v_mfma_f32_16x16x32_bf16 v[56:59], v[80:83], v[176:179], 0
	v_mfma_f32_16x16x32_bf16 v[52:55], v[64:67], v[184:187], 0
	v_mfma_f32_16x16x32_bf16 v[48:51], v[80:83], v[184:187], 0
	v_mfma_f32_16x16x32_bf16 v[28:31], v[64:67], v[194:197], 0
	v_mfma_f32_16x16x32_bf16 v[24:27], v[80:83], v[194:197], 0
	v_mfma_f32_16x16x32_bf16 v[16:19], v[64:67], v[204:207], 0
	v_mfma_f32_16x16x32_bf16 v[8:11], v[80:83], v[204:207], 0
	v_mfma_f32_16x16x32_bf16 v[60:63], v[68:71], v[180:183], v[60:63]
	v_mfma_f32_16x16x32_bf16 v[56:59], v[92:95], v[180:183], v[56:59]
	v_mfma_f32_16x16x32_bf16 v[52:55], v[68:71], v[188:191], v[52:55]
	v_mfma_f32_16x16x32_bf16 v[48:51], v[92:95], v[188:191], v[48:51]
	v_mfma_f32_16x16x32_bf16 v[28:31], v[68:71], v[198:201], v[28:31]
	v_mfma_f32_16x16x32_bf16 v[24:27], v[92:95], v[198:201], v[24:27]
	v_mfma_f32_16x16x32_bf16 v[16:19], v[68:71], v[208:211], v[16:19]
	v_mfma_f32_16x16x32_bf16 v[8:11], v[92:95], v[208:211], v[8:11]
	v_mfma_f32_16x16x32_bf16 v[44:47], v[160:163], v[176:179], 0
	v_mfma_f32_16x16x32_bf16 v[40:43], v[168:171], v[176:179], 0
	v_mfma_f32_16x16x32_bf16 v[36:39], v[160:163], v[184:187], 0
	v_mfma_f32_16x16x32_bf16 v[32:35], v[168:171], v[184:187], 0
	v_mfma_f32_16x16x32_bf16 v[20:23], v[160:163], v[194:197], 0
	v_mfma_f32_16x16x32_bf16 v[12:15], v[168:171], v[194:197], 0
	v_mfma_f32_16x16x32_bf16 v[4:7], v[160:163], v[204:207], 0
	v_mfma_f32_16x16x32_bf16 v[0:3], v[168:171], v[204:207], 0
	v_mfma_f32_16x16x32_bf16 v[44:47], v[164:167], v[180:183], v[44:47]
	v_mfma_f32_16x16x32_bf16 v[40:43], v[172:175], v[180:183], v[40:43]
	v_mfma_f32_16x16x32_bf16 v[36:39], v[164:167], v[188:191], v[36:39]
	v_mfma_f32_16x16x32_bf16 v[32:35], v[172:175], v[188:191], v[32:35]
	v_mfma_f32_16x16x32_bf16 v[20:23], v[164:167], v[198:201], v[20:23]
	v_mfma_f32_16x16x32_bf16 v[12:15], v[172:175], v[198:201], v[12:15]
	v_mfma_f32_16x16x32_bf16 v[4:7], v[164:167], v[208:211], v[4:7]
	v_mfma_f32_16x16x32_bf16 v[0:3], v[172:175], v[208:211], v[0:3]
	s_setprio 0
	s_barrier
	s_add_i32 s43, 0, 0x18000
	s_add_i32 s44, 0, 0x1c000
	v_add_u32_e32 v92, s43, v157
	v_add_u32_e32 v172, s44, v157
	ds_read_b128 v[64:67], v92
	ds_read_b128 v[68:71], v92 offset:1024
	ds_read_b128 v[80:83], v92 offset:2048
	ds_read_b128 v[92:95], v92 offset:3072
	ds_read_b128 v[160:163], v172
	ds_read_b128 v[164:167], v172 offset:1024
	ds_read_b128 v[168:171], v172 offset:2048
	ds_read_b128 v[172:175], v172 offset:3072
	s_add_u32 s16, s22, 0xb0000
	s_addc_u32 s17, s23, 0
	s_mov_b32 m0, s74
	v_lshl_add_u64 v[218:219], s[16:17], 0, v[148:149]
	ds_read_b128 v[176:179], v159 offset:32768
	ds_read_b128 v[180:183], v159 offset:33792
	ds_read_b128 v[184:187], v159 offset:34816
	ds_read_b128 v[188:191], v159 offset:35840
	ds_read_b128 v[194:197], v159 offset:36864
	ds_read_b128 v[198:201], v159 offset:37888
	ds_read_b128 v[204:207], v159 offset:38912
	ds_read_b128 v[208:211], v159 offset:39936
	global_load_lds_dwordx4 v[218:219], off
	v_lshl_add_u64 v[218:219], s[16:17], 0, v[146:147]
	s_mov_b32 m0, s75
	s_nop 0
	global_load_lds_dwordx4 v[218:219], off
	s_waitcnt vmcnt(8)
	s_waitcnt lgkmcnt(0)
	s_barrier
	s_setprio 1
	s_waitcnt lgkmcnt(0)
	v_mfma_f32_16x16x32_bf16 v[140:143], v[64:67], v[176:179], v[140:143]
	v_mfma_f32_16x16x32_bf16 v[136:139], v[80:83], v[176:179], v[136:139]
	v_mfma_f32_16x16x32_bf16 v[132:135], v[64:67], v[184:187], v[132:135]
	v_mfma_f32_16x16x32_bf16 v[128:131], v[80:83], v[184:187], v[128:131]
	v_mfma_f32_16x16x32_bf16 v[108:111], v[64:67], v[194:197], v[108:111]
	v_mfma_f32_16x16x32_bf16 v[104:107], v[80:83], v[194:197], v[104:107]
	v_mfma_f32_16x16x32_bf16 v[100:103], v[64:67], v[204:207], v[100:103]
	v_mfma_f32_16x16x32_bf16 v[96:99], v[80:83], v[204:207], v[96:99]
	v_mfma_f32_16x16x32_bf16 v[140:143], v[68:71], v[180:183], v[140:143]
	v_mfma_f32_16x16x32_bf16 v[136:139], v[92:95], v[180:183], v[136:139]
	v_mfma_f32_16x16x32_bf16 v[132:135], v[68:71], v[188:191], v[132:135]
	v_mfma_f32_16x16x32_bf16 v[128:131], v[92:95], v[188:191], v[128:131]
	v_mfma_f32_16x16x32_bf16 v[108:111], v[68:71], v[198:201], v[108:111]
	v_mfma_f32_16x16x32_bf16 v[104:107], v[92:95], v[198:201], v[104:107]
	v_mfma_f32_16x16x32_bf16 v[100:103], v[68:71], v[208:211], v[100:103]
	v_mfma_f32_16x16x32_bf16 v[96:99], v[92:95], v[208:211], v[96:99]
	v_mfma_f32_16x16x32_bf16 v[124:127], v[160:163], v[176:179], v[124:127]
	v_mfma_f32_16x16x32_bf16 v[120:123], v[168:171], v[176:179], v[120:123]
	v_mfma_f32_16x16x32_bf16 v[116:119], v[160:163], v[184:187], v[116:119]
	v_mfma_f32_16x16x32_bf16 v[112:115], v[168:171], v[184:187], v[112:115]
	v_mfma_f32_16x16x32_bf16 v[88:91], v[160:163], v[194:197], v[88:91]
	v_mfma_f32_16x16x32_bf16 v[84:87], v[168:171], v[194:197], v[84:87]
	v_mfma_f32_16x16x32_bf16 v[76:79], v[160:163], v[204:207], v[76:79]
	v_mfma_f32_16x16x32_bf16 v[72:75], v[168:171], v[204:207], v[72:75]
	v_mfma_f32_16x16x32_bf16 v[124:127], v[164:167], v[180:183], v[124:127]
	v_mfma_f32_16x16x32_bf16 v[120:123], v[172:175], v[180:183], v[120:123]
	v_mfma_f32_16x16x32_bf16 v[116:119], v[164:167], v[188:191], v[116:119]
	v_mfma_f32_16x16x32_bf16 v[112:115], v[172:175], v[188:191], v[112:115]
	v_mfma_f32_16x16x32_bf16 v[88:91], v[164:167], v[198:201], v[88:91]
	v_mfma_f32_16x16x32_bf16 v[84:87], v[172:175], v[198:201], v[84:87]
	v_mfma_f32_16x16x32_bf16 v[76:79], v[164:167], v[208:211], v[76:79]
	v_mfma_f32_16x16x32_bf16 v[72:75], v[172:175], v[208:211], v[72:75]
	s_setprio 0
	s_barrier
; #define PG8_STAGE(bufoff, gbase, voff) do { _Pragma("unroll") for (int _i = 0; _i < 2; ++_i) \
;         __builtin_amdgcn_global_load_lds((const unsigned*)((const char*)(gbase) + (voff)[_i]), (LAS unsigned*)(lds + (bufoff) + ldsw + _i * 8192), 16, 0, 0); } while (0)
; #define PG8_LDA(dst, b, h) do { _Pragma("unroll") for (int m = 0; m < 4; ++m) _Pragma("unroll") for (int k = 0; k < 2; ++k) dst[m][k] = *(const LAS bf16x8*)(lds + PG8_SA(b, h) + aoff + m * 2048 + k * 1024); } while (0)
; #define PG8_LDB(dst, b, h) do { _Pragma("unroll") for (int n = 0; n < 2; ++n) _Pragma("unroll") for (int k = 0; k < 2; ++k) dst[n][k] = *(const LAS bf16x8*)(lds + PG8_SB(b, h) + boff + n * 2048 + k * 1024); } while (0)
; #define PG8_WAIT_V(n) asm volatile("s_waitcnt vmcnt(" #n ")" ::: "memory")
; #define PG8_WAIT_L(n) asm volatile("s_waitcnt lgkmcnt(" #n ")" ::: "memory")
; template <class Epi>
; __device__ __forceinline__ void gemm_phase(LAS unsigned char* lds, const Gemm g, const Sched& S, const Epi& E, const int tid) {
;     ...
;         for (int t = 0; t < nt; t += 2) {
;             const bool last = (t == nt - 2);
;             const char* a1 = cA + (size_t)(t + 1) * kstep;
;             const char* a2 = last ? nA : cA + (size_t)(t + 2) * kstep; const char* b2 = last ? nB : cB + (size_t)(t + 2) * kstep;
;             const char* a3 = a2 + kstep; const char* b3 = b2 + kstep;
;             PG8_LDB(B0, 0, 0); PG8_LDB(B1, 0, 1); PG8_SCHED; PG8_LDA(At, 0, 0); PG8_STAGE(PG8_SA(1, 1), a1 + hA, voffA);
;             PG8_WAIT_V(8); PG8_WAIT_L(0); PG8_BAR; PG8_MMA(0, 0, At, B0); PG8_MMA(0, 1, At, B1); PG8_BAR; PG8_SCHED;
;             PG8_LDA(At, 0, 1); PG8_STAGE(PG8_SB(0, 0), b2, voffB); PG8_STAGE(PG8_SB(0, 1), b2 + hB, voffB); PG8_STAGE(PG8_SA(0, 0), a2, voffA);
;             PG8_WAIT_V(8); PG8_WAIT_L(0); PG8_BAR; PG8_MMA(1, 0, At, B0); PG8_MMA(1, 1, At, B1); PG8_BAR; PG8_SCHED;
;             PG8_LDB(B0, 1, 0); PG8_LDB(B1, 1, 1); PG8_SCHED; PG8_LDA(At, 1, 0); PG8_STAGE(PG8_SA(0, 1), a2 + hA, voffA);
;             PG8_WAIT_V(8); PG8_WAIT_L(0); PG8_BAR; PG8_MMA(0, 0, At, B0); PG8_MMA(0, 1, At, B1); PG8_BAR; PG8_SCHED;
;             PG8_LDA(At, 1, 1); PG8_STAGE(PG8_SB(1, 0), b3, voffB); PG8_STAGE(PG8_SB(1, 1), b3 + hB, voffB); PG8_STAGE(PG8_SA(1, 0), a3, voffA);
;             PG8_WAIT_V(8); PG8_WAIT_L(0); PG8_BAR; PG8_MMA(1, 0, At, B0); PG8_MMA(1, 1, At, B1); PG8_BAR; PG8_SCHED;
	s_add_i32 s16, s43, s39
	v_lshl_add_u64 v[154:155], v[154:155], 0, s[94:95]
	s_mov_b32 m0, s16
	ds_read_b128 v[176:179], v159 offset:49152
	ds_read_b128 v[180:183], v159 offset:50176
	ds_read_b128 v[184:187], v159 offset:51200
	ds_read_b128 v[188:191], v159 offset:52224
	ds_read_b128 v[194:197], v159 offset:53248
	ds_read_b128 v[198:201], v159 offset:54272
	ds_read_b128 v[204:207], v159 offset:55296
	ds_read_b128 v[208:211], v159 offset:56320
	global_load_lds_dwordx4 v[154:155], off
	s_add_i32 m0, s16, 0x2000
	s_add_u32 s16, s20, 0xb0080
	v_lshl_add_u64 v[154:155], v[212:213], 0, s[94:95]
	s_addc_u32 s17, s21, 0
	s_add_i32 s20, s44, s39
	global_load_lds_dwordx4 v[154:155], off
	v_lshl_add_u64 v[154:155], s[16:17], 0, v[192:193]
	s_mov_b32 m0, s20
	s_nop 0
	global_load_lds_dwordx4 v[154:155], off
	v_lshl_add_u64 v[154:155], s[16:17], 0, v[144:145]
	s_add_i32 m0, s20, 0x2000
	s_nop 0
	global_load_lds_dwordx4 v[154:155], off
	v_lshl_add_u64 v[154:155], v[214:215], 0, s[94:95]
	s_mov_b32 m0, s51
	s_nop 0
	global_load_lds_dwordx4 v[154:155], off
	v_lshl_add_u64 v[154:155], v[216:217], 0, s[94:95]
	s_mov_b32 m0, s76
	s_nop 0
	global_load_lds_dwordx4 v[154:155], off
	s_waitcnt vmcnt(8)
	s_waitcnt lgkmcnt(0)
	s_barrier
	s_setprio 1
	s_waitcnt lgkmcnt(0)
	v_mfma_f32_16x16x32_bf16 v[60:63], v[64:67], v[176:179], v[60:63]
	v_mfma_f32_16x16x32_bf16 v[56:59], v[80:83], v[176:179], v[56:59]
	v_mfma_f32_16x16x32_bf16 v[52:55], v[64:67], v[184:187], v[52:55]
	v_mfma_f32_16x16x32_bf16 v[48:51], v[80:83], v[184:187], v[48:51]
	v_mfma_f32_16x16x32_bf16 v[28:31], v[64:67], v[194:197], v[28:31]
	v_mfma_f32_16x16x32_bf16 v[24:27], v[80:83], v[194:197], v[24:27]
	v_mfma_f32_16x16x32_bf16 v[16:19], v[64:67], v[204:207], v[16:19]
	v_mfma_f32_16x16x32_bf16 v[8:11], v[80:83], v[204:207], v[8:11]
	v_mfma_f32_16x16x32_bf16 v[60:63], v[68:71], v[180:183], v[60:63]
	v_mfma_f32_16x16x32_bf16 v[56:59], v[92:95], v[180:183], v[56:59]
	v_mfma_f32_16x16x32_bf16 v[52:55], v[68:71], v[188:191], v[52:55]
	v_mfma_f32_16x16x32_bf16 v[48:51], v[92:95], v[188:191], v[48:51]
	v_mfma_f32_16x16x32_bf16 v[28:31], v[68:71], v[198:201], v[28:31]
	v_mfma_f32_16x16x32_bf16 v[24:27], v[92:95], v[198:201], v[24:27]
	v_mfma_f32_16x16x32_bf16 v[16:19], v[68:71], v[208:211], v[16:19]
	v_mfma_f32_16x16x32_bf16 v[8:11], v[92:95], v[208:211], v[8:11]
	v_mfma_f32_16x16x32_bf16 v[44:47], v[160:163], v[176:179], v[44:47]
	v_mfma_f32_16x16x32_bf16 v[40:43], v[168:171], v[176:179], v[40:43]
	v_mfma_f32_16x16x32_bf16 v[36:39], v[160:163], v[184:187], v[36:39]
	v_mfma_f32_16x16x32_bf16 v[32:35], v[168:171], v[184:187], v[32:35]
	v_mfma_f32_16x16x32_bf16 v[20:23], v[160:163], v[194:197], v[20:23]
	v_mfma_f32_16x16x32_bf16 v[12:15], v[168:171], v[194:197], v[12:15]
	v_mfma_f32_16x16x32_bf16 v[4:7], v[160:163], v[204:207], v[4:7]
	v_mfma_f32_16x16x32_bf16 v[0:3], v[168:171], v[204:207], v[0:3]
	v_mfma_f32_16x16x32_bf16 v[44:47], v[164:167], v[180:183], v[44:47]
	v_mfma_f32_16x16x32_bf16 v[40:43], v[172:175], v[180:183], v[40:43]
	v_mfma_f32_16x16x32_bf16 v[36:39], v[164:167], v[188:191], v[36:39]
	v_mfma_f32_16x16x32_bf16 v[32:35], v[172:175], v[188:191], v[32:35]
	v_mfma_f32_16x16x32_bf16 v[20:23], v[164:167], v[198:201], v[20:23]
	v_mfma_f32_16x16x32_bf16 v[12:15], v[172:175], v[198:201], v[12:15]
	v_mfma_f32_16x16x32_bf16 v[4:7], v[164:167], v[208:211], v[4:7]
	v_mfma_f32_16x16x32_bf16 v[0:3], v[172:175], v[208:211], v[0:3]
	s_setprio 0
	s_barrier
	s_add_i32 vcc_lo, vcc_lo, 2
	s_add_u32 s80, s80, 0x100
	s_addc_u32 s81, s81, 0
	s_cmp_gt_u32 vcc_lo, 41
	s_mov_b64 s[16:17], s[18:19]
	s_cbranch_scc1 .Lgk_exit_5
.LBB0_1411:
	s_add_u32 s18, s16, 0x100
	s_addc_u32 s19, s17, 0
	s_add_i32 s43, 0, 0x10000
	s_cmp_eq_u32 vcc_lo, 40
	s_cselect_b32 s23, s7, s19
	s_cselect_b32 s22, s6, s18
	s_cselect_b32 s21, s15, s81
	s_cselect_b32 s20, s14, s80
	s_add_i32 s44, 0, 0x14000
	v_add_u32_e32 v92, s43, v157
	v_add_u32_e32 v154, s44, v157
	ds_read_b128 v[64:67], v92
	ds_read_b128 v[68:71], v92 offset:1024
	ds_read_b128 v[80:83], v92 offset:2048
	ds_read_b128 v[92:95], v92 offset:3072
	ds_read_b128 v[160:163], v154
	ds_read_b128 v[164:167], v154 offset:1024
	ds_read_b128 v[168:171], v154 offset:2048
	ds_read_b128 v[172:175], v154 offset:3072
	v_lshl_add_u64 v[154:155], s[16:17], 0, v[150:151]
	s_add_i32 m0, s40, 0xc000
	ds_read_b128 v[176:179], v159
	ds_read_b128 v[180:183], v159 offset:1024
	ds_read_b128 v[184:187], v159 offset:2048
	ds_read_b128 v[188:191], v159 offset:3072
	ds_read_b128 v[194:197], v159 offset:4096
	ds_read_b128 v[198:201], v159 offset:5120
	ds_read_b128 v[204:207], v159 offset:6144
	ds_read_b128 v[208:211], v159 offset:7168
	global_load_lds_dwordx4 v[154:155], off
	v_lshl_add_u64 v[154:155], s[16:17], 0, v[152:153]
	s_add_i32 m0, s40, 0xe000
	s_nop 0
	global_load_lds_dwordx4 v[154:155], off
	s_waitcnt vmcnt(8)
	s_waitcnt lgkmcnt(0)
	s_barrier
; #define PG8_STAGE(bufoff, gbase, voff) do { _Pragma("unroll") for (int _i = 0; _i < 2; ++_i) \
;         __builtin_amdgcn_global_load_lds((const unsigned*)((const char*)(gbase) + (voff)[_i]), (LAS unsigned*)(lds + (bufoff) + ldsw + _i * 8192), 16, 0, 0); } while (0)
; #define PG8_LDA(dst, b, h) do { _Pragma("unroll") for (int m = 0; m < 4; ++m) _Pragma("unroll") for (int k = 0; k < 2; ++k) dst[m][k] = *(const LAS bf16x8*)(lds + PG8_SA(b, h) + aoff + m * 2048 + k * 1024); } while (0)
; #define PG8_MMA(ai, bj, At, Bt) do { __builtin_amdgcn_s_setprio(1); _Pragma("unroll") for (int m = 0; m < 4; ++m) _Pragma("unroll") for (int n = 0; n < 2; ++n) _Pragma("unroll") for (int k = 0; k < 2; ++k) \
;         acc[ai][bj][m][n] = __builtin_amdgcn_mfma_f32_16x16x32_bf16(Bt[n][k], At[m][k], acc[ai][bj][m][n], 0, 0, 0); __builtin_amdgcn_s_setprio(0); } while (0)
; #define PG8_WAIT_V(n) asm volatile("s_waitcnt vmcnt(" #n ")" ::: "memory")
; #define PG8_WAIT_L(n) asm volatile("s_waitcnt lgkmcnt(" #n ")" ::: "memory")
; #define PG8_BAR __builtin_amdgcn_s_barrier()
; #define PG8_SCHED __builtin_amdgcn_sched_barrier(0)
; template <class Epi>
; __device__ __forceinline__ void gemm_phase(LAS unsigned char* lds, const Gemm g, const Sched& S, const Epi& E, const int tid) {
;     ...
;             PG8_WAIT_V(8); PG8_WAIT_L(0); PG8_BAR; PG8_MMA(0, 0, At, B0); PG8_MMA(0, 1, At, B1); PG8_BAR; PG8_SCHED;
;             PG8_LDA(At, 0, 1); PG8_STAGE(PG8_SB(0, 0), b2, voffB); PG8_STAGE(PG8_SB(0, 1), b2 + hB, voffB); PG8_STAGE(PG8_SA(0, 0), a2, voffA);
;             PG8_WAIT_V(8); PG8_WAIT_L(0); PG8_BAR; PG8_MMA(1, 0, At, B0); PG8_MMA(1, 1, At, B1); PG8_BAR; PG8_SCHED;
	s_setprio 1
	s_waitcnt lgkmcnt(0)
	v_mfma_f32_16x16x32_bf16 v[140:143], v[64:67], v[176:179], v[140:143]
	v_mfma_f32_16x16x32_bf16 v[136:139], v[80:83], v[176:179], v[136:139]
	v_mfma_f32_16x16x32_bf16 v[132:135], v[64:67], v[184:187], v[132:135]
	v_mfma_f32_16x16x32_bf16 v[128:131], v[80:83], v[184:187], v[128:131]
	v_mfma_f32_16x16x32_bf16 v[108:111], v[64:67], v[194:197], v[108:111]
	v_mfma_f32_16x16x32_bf16 v[104:107], v[80:83], v[194:197], v[104:107]
	v_mfma_f32_16x16x32_bf16 v[100:103], v[64:67], v[204:207], v[100:103]
	v_mfma_f32_16x16x32_bf16 v[96:99], v[80:83], v[204:207], v[96:99]
	v_mfma_f32_16x16x32_bf16 v[140:143], v[68:71], v[180:183], v[140:143]
	v_mfma_f32_16x16x32_bf16 v[136:139], v[92:95], v[180:183], v[136:139]
	v_mfma_f32_16x16x32_bf16 v[132:135], v[68:71], v[188:191], v[132:135]
	v_mfma_f32_16x16x32_bf16 v[128:131], v[92:95], v[188:191], v[128:131]
	v_mfma_f32_16x16x32_bf16 v[108:111], v[68:71], v[198:201], v[108:111]
	v_mfma_f32_16x16x32_bf16 v[104:107], v[92:95], v[198:201], v[104:107]
	v_mfma_f32_16x16x32_bf16 v[100:103], v[68:71], v[208:211], v[100:103]
	v_mfma_f32_16x16x32_bf16 v[96:99], v[92:95], v[208:211], v[96:99]
	v_mfma_f32_16x16x32_bf16 v[124:127], v[160:163], v[176:179], v[124:127]
	v_mfma_f32_16x16x32_bf16 v[120:123], v[168:171], v[176:179], v[120:123]
	v_mfma_f32_16x16x32_bf16 v[116:119], v[160:163], v[184:187], v[116:119]
	v_mfma_f32_16x16x32_bf16 v[112:115], v[168:171], v[184:187], v[112:115]
	v_mfma_f32_16x16x32_bf16 v[88:91], v[160:163], v[194:197], v[88:91]
	v_mfma_f32_16x16x32_bf16 v[84:87], v[168:171], v[194:197], v[84:87]
	v_mfma_f32_16x16x32_bf16 v[76:79], v[160:163], v[204:207], v[76:79]
	v_mfma_f32_16x16x32_bf16 v[72:75], v[168:171], v[204:207], v[72:75]
	v_mfma_f32_16x16x32_bf16 v[124:127], v[164:167], v[180:183], v[124:127]
	v_mfma_f32_16x16x32_bf16 v[120:123], v[172:175], v[180:183], v[120:123]
	v_mfma_f32_16x16x32_bf16 v[116:119], v[164:167], v[188:191], v[116:119]
	v_mfma_f32_16x16x32_bf16 v[112:115], v[172:175], v[188:191], v[112:115]
	v_mfma_f32_16x16x32_bf16 v[88:91], v[164:167], v[198:201], v[88:91]
	v_mfma_f32_16x16x32_bf16 v[84:87], v[172:175], v[198:201], v[84:87]
	v_mfma_f32_16x16x32_bf16 v[76:79], v[164:167], v[208:211], v[76:79]
	v_mfma_f32_16x16x32_bf16 v[72:75], v[172:175], v[208:211], v[72:75]
	s_setprio 0
	s_barrier
	s_add_i32 s16, s43, s39
	v_lshl_add_u64 v[154:155], s[20:21], 0, v[192:193]
	s_mov_b32 m0, s16
	ds_read_b128 v[176:179], v159 offset:16384
	ds_read_b128 v[180:183], v159 offset:17408
	ds_read_b128 v[184:187], v159 offset:18432
	ds_read_b128 v[188:191], v159 offset:19456
	ds_read_b128 v[194:197], v159 offset:20480
	ds_read_b128 v[198:201], v159 offset:21504
	ds_read_b128 v[204:207], v159 offset:22528
	ds_read_b128 v[208:211], v159 offset:23552
	global_load_lds_dwordx4 v[154:155], off
	s_add_i32 m0, s16, 0x2000
	s_add_u32 s16, s20, 0xb0000
	v_lshl_add_u64 v[212:213], s[20:21], 0, v[144:145]
	s_addc_u32 s17, s21, 0
	s_add_i32 s43, s44, s39
	global_load_lds_dwordx4 v[212:213], off
	v_lshl_add_u64 v[214:215], s[16:17], 0, v[192:193]
	s_mov_b32 m0, s43
	v_lshl_add_u64 v[216:217], s[22:23], 0, v[146:147]
	global_load_lds_dwordx4 v[214:215], off
	v_lshl_add_u64 v[214:215], s[16:17], 0, v[144:145]
	s_add_i32 m0, s43, 0x2000
	s_nop 0
	global_load_lds_dwordx4 v[214:215], off
	v_lshl_add_u64 v[214:215], s[22:23], 0, v[148:149]
	s_mov_b32 m0, s40
	s_nop 0
	global_load_lds_dwordx4 v[214:215], off
	s_mov_b32 m0, s73
	s_nop 0
	global_load_lds_dwordx4 v[216:217], off
	s_waitcnt vmcnt(8)
	s_waitcnt lgkmcnt(0)
	s_barrier
	s_setprio 1
	s_waitcnt lgkmcnt(0)
	v_mfma_f32_16x16x32_bf16 v[60:63], v[64:67], v[176:179], v[60:63]
	v_mfma_f32_16x16x32_bf16 v[56:59], v[80:83], v[176:179], v[56:59]
	v_mfma_f32_16x16x32_bf16 v[52:55], v[64:67], v[184:187], v[52:55]
	v_mfma_f32_16x16x32_bf16 v[48:51], v[80:83], v[184:187], v[48:51]
	v_mfma_f32_16x16x32_bf16 v[28:31], v[64:67], v[194:197], v[28:31]
	v_mfma_f32_16x16x32_bf16 v[24:27], v[80:83], v[194:197], v[24:27]
	v_mfma_f32_16x16x32_bf16 v[16:19], v[64:67], v[204:207], v[16:19]
	v_mfma_f32_16x16x32_bf16 v[8:11], v[80:83], v[204:207], v[8:11]
	v_mfma_f32_16x16x32_bf16 v[60:63], v[68:71], v[180:183], v[60:63]
	v_mfma_f32_16x16x32_bf16 v[56:59], v[92:95], v[180:183], v[56:59]
	v_mfma_f32_16x16x32_bf16 v[52:55], v[68:71], v[188:191], v[52:55]
	v_mfma_f32_16x16x32_bf16 v[48:51], v[92:95], v[188:191], v[48:51]
	v_mfma_f32_16x16x32_bf16 v[28:31], v[68:71], v[198:201], v[28:31]
	v_mfma_f32_16x16x32_bf16 v[24:27], v[92:95], v[198:201], v[24:27]
	v_mfma_f32_16x16x32_bf16 v[16:19], v[68:71], v[208:211], v[16:19]
	v_mfma_f32_16x16x32_bf16 v[8:11], v[92:95], v[208:211], v[8:11]
	v_mfma_f32_16x16x32_bf16 v[44:47], v[160:163], v[176:179], v[44:47]
	v_mfma_f32_16x16x32_bf16 v[40:43], v[168:171], v[176:179], v[40:43]
	v_mfma_f32_16x16x32_bf16 v[36:39], v[160:163], v[184:187], v[36:39]
	v_mfma_f32_16x16x32_bf16 v[32:35], v[168:171], v[184:187], v[32:35]
	v_mfma_f32_16x16x32_bf16 v[20:23], v[160:163], v[194:197], v[20:23]
	v_mfma_f32_16x16x32_bf16 v[12:15], v[168:171], v[194:197], v[12:15]
	v_mfma_f32_16x16x32_bf16 v[4:7], v[160:163], v[204:207], v[4:7]
	v_mfma_f32_16x16x32_bf16 v[0:3], v[168:171], v[204:207], v[0:3]
	v_mfma_f32_16x16x32_bf16 v[44:47], v[164:167], v[180:183], v[44:47]
	v_mfma_f32_16x16x32_bf16 v[40:43], v[172:175], v[180:183], v[40:43]
	v_mfma_f32_16x16x32_bf16 v[36:39], v[164:167], v[188:191], v[36:39]
	v_mfma_f32_16x16x32_bf16 v[32:35], v[172:175], v[188:191], v[32:35]
	v_mfma_f32_16x16x32_bf16 v[20:23], v[164:167], v[198:201], v[20:23]
	v_mfma_f32_16x16x32_bf16 v[12:15], v[172:175], v[198:201], v[12:15]
	v_mfma_f32_16x16x32_bf16 v[4:7], v[164:167], v[208:211], v[4:7]
	v_mfma_f32_16x16x32_bf16 v[0:3], v[172:175], v[208:211], v[0:3]
	s_setprio 0
	s_barrier
; #define PG8_STAGE(bufoff, gbase, voff) do { _Pragma("unroll") for (int _i = 0; _i < 2; ++_i) \
;         __builtin_amdgcn_global_load_lds((const unsigned*)((const char*)(gbase) + (voff)[_i]), (LAS unsigned*)(lds + (bufoff) + ldsw + _i * 8192), 16, 0, 0); } while (0)
; #define PG8_LDA(dst, b, h) do { _Pragma("unroll") for (int m = 0; m < 4; ++m) _Pragma("unroll") for (int k = 0; k < 2; ++k) dst[m][k] = *(const LAS bf16x8*)(lds + PG8_SA(b, h) + aoff + m * 2048 + k * 1024); } while (0)
; #define PG8_LDB(dst, b, h) do { _Pragma("unroll") for (int n = 0; n < 2; ++n) _Pragma("unroll") for (int k = 0; k < 2; ++k) dst[n][k] = *(const LAS bf16x8*)(lds + PG8_SB(b, h) + boff + n * 2048 + k * 1024); } while (0)
; #define PG8_MMA(ai, bj, At, Bt) do { __builtin_amdgcn_s_setprio(1); _Pragma("unroll") for (int m = 0; m < 4; ++m) _Pragma("unroll") for (int n = 0; n < 2; ++n) _Pragma("unroll") for (int k = 0; k < 2; ++k) \
;         acc[ai][bj][m][n] = __builtin_amdgcn_mfma_f32_16x16x32_bf16(Bt[n][k], At[m][k], acc[ai][bj][m][n], 0, 0, 0); __builtin_amdgcn_s_setprio(0); } while (0)
; #define PG8_WAIT_V(n) asm volatile("s_waitcnt vmcnt(" #n ")" ::: "memory")
; #define PG8_WAIT_L(n) asm volatile("s_waitcnt lgkmcnt(" #n ")" ::: "memory")
; #define PG8_BAR __builtin_amdgcn_s_barrier()
; #define PG8_SCHED __builtin_amdgcn_sched_barrier(0)
; template <class Epi>
; __device__ __forceinline__ void gemm_phase(LAS unsigned char* lds, const Gemm g, const Sched& S, const Epi& E, const int tid) {
;     ...
;             PG8_LDB(B0, 1, 0); PG8_LDB(B1, 1, 1); PG8_SCHED; PG8_LDA(At, 1, 0); PG8_STAGE(PG8_SA(0, 1), a2 + hA, voffA);
;             PG8_WAIT_V(8); PG8_WAIT_L(0); PG8_BAR; PG8_MMA(0, 0, At, B0); PG8_MMA(0, 1, At, B1); PG8_BAR; PG8_SCHED;
;             PG8_LDA(At, 1, 1); PG8_STAGE(PG8_SB(1, 0), b3, voffB); PG8_STAGE(PG8_SB(1, 1), b3 + hB, voffB); PG8_STAGE(PG8_SA(1, 0), a3, voffA);
;             PG8_WAIT_V(8); PG8_WAIT_L(0); PG8_BAR; PG8_MMA(1, 0, At, B0); PG8_MMA(1, 1, At, B1); PG8_BAR; PG8_SCHED;
;         }
	s_add_i32 s43, 0, 0x18000
	s_add_i32 s44, 0, 0x1c000
	v_add_u32_e32 v92, s43, v157
	v_add_u32_e32 v172, s44, v157
	ds_read_b128 v[64:67], v92
	ds_read_b128 v[68:71], v92 offset:1024
	ds_read_b128 v[80:83], v92 offset:2048
	ds_read_b128 v[92:95], v92 offset:3072
	ds_read_b128 v[160:163], v172
	ds_read_b128 v[164:167], v172 offset:1024
	ds_read_b128 v[168:171], v172 offset:2048
	ds_read_b128 v[172:175], v172 offset:3072
	s_add_u32 s16, s22, 0xb0000
	s_addc_u32 s17, s23, 0
	s_mov_b32 m0, s74
	v_lshl_add_u64 v[218:219], s[16:17], 0, v[148:149]
	ds_read_b128 v[176:179], v159 offset:32768
	ds_read_b128 v[180:183], v159 offset:33792
	ds_read_b128 v[184:187], v159 offset:34816
	ds_read_b128 v[188:191], v159 offset:35840
	ds_read_b128 v[194:197], v159 offset:36864
	ds_read_b128 v[198:201], v159 offset:37888
	ds_read_b128 v[204:207], v159 offset:38912
	ds_read_b128 v[208:211], v159 offset:39936
	global_load_lds_dwordx4 v[218:219], off
	v_lshl_add_u64 v[218:219], s[16:17], 0, v[146:147]
	s_mov_b32 m0, s75
	s_nop 0
	global_load_lds_dwordx4 v[218:219], off
	s_waitcnt vmcnt(8)
	s_waitcnt lgkmcnt(0)
	s_barrier
	s_setprio 1
	s_waitcnt lgkmcnt(0)
	v_mfma_f32_16x16x32_bf16 v[140:143], v[64:67], v[176:179], v[140:143]
	v_mfma_f32_16x16x32_bf16 v[136:139], v[80:83], v[176:179], v[136:139]
	v_mfma_f32_16x16x32_bf16 v[132:135], v[64:67], v[184:187], v[132:135]
	v_mfma_f32_16x16x32_bf16 v[128:131], v[80:83], v[184:187], v[128:131]
	v_mfma_f32_16x16x32_bf16 v[108:111], v[64:67], v[194:197], v[108:111]
	v_mfma_f32_16x16x32_bf16 v[104:107], v[80:83], v[194:197], v[104:107]
	v_mfma_f32_16x16x32_bf16 v[100:103], v[64:67], v[204:207], v[100:103]
	v_mfma_f32_16x16x32_bf16 v[96:99], v[80:83], v[204:207], v[96:99]
	v_mfma_f32_16x16x32_bf16 v[140:143], v[68:71], v[180:183], v[140:143]
	v_mfma_f32_16x16x32_bf16 v[136:139], v[92:95], v[180:183], v[136:139]
	v_mfma_f32_16x16x32_bf16 v[132:135], v[68:71], v[188:191], v[132:135]
	v_mfma_f32_16x16x32_bf16 v[128:131], v[92:95], v[188:191], v[128:131]
	v_mfma_f32_16x16x32_bf16 v[108:111], v[68:71], v[198:201], v[108:111]
	v_mfma_f32_16x16x32_bf16 v[104:107], v[92:95], v[198:201], v[104:107]
	v_mfma_f32_16x16x32_bf16 v[100:103], v[68:71], v[208:211], v[100:103]
	v_mfma_f32_16x16x32_bf16 v[96:99], v[92:95], v[208:211], v[96:99]
	v_mfma_f32_16x16x32_bf16 v[124:127], v[160:163], v[176:179], v[124:127]
	v_mfma_f32_16x16x32_bf16 v[120:123], v[168:171], v[176:179], v[120:123]
	v_mfma_f32_16x16x32_bf16 v[116:119], v[160:163], v[184:187], v[116:119]
	v_mfma_f32_16x16x32_bf16 v[112:115], v[168:171], v[184:187], v[112:115]
	v_mfma_f32_16x16x32_bf16 v[88:91], v[160:163], v[194:197], v[88:91]
	v_mfma_f32_16x16x32_bf16 v[84:87], v[168:171], v[194:197], v[84:87]
	v_mfma_f32_16x16x32_bf16 v[76:79], v[160:163], v[204:207], v[76:79]
	v_mfma_f32_16x16x32_bf16 v[72:75], v[168:171], v[204:207], v[72:75]
	v_mfma_f32_16x16x32_bf16 v[124:127], v[164:167], v[180:183], v[124:127]
	v_mfma_f32_16x16x32_bf16 v[120:123], v[172:175], v[180:183], v[120:123]
	v_mfma_f32_16x16x32_bf16 v[116:119], v[164:167], v[188:191], v[116:119]
	v_mfma_f32_16x16x32_bf16 v[112:115], v[172:175], v[188:191], v[112:115]
	v_mfma_f32_16x16x32_bf16 v[88:91], v[164:167], v[198:201], v[88:91]
	v_mfma_f32_16x16x32_bf16 v[84:87], v[172:175], v[198:201], v[84:87]
	v_mfma_f32_16x16x32_bf16 v[76:79], v[164:167], v[208:211], v[76:79]
	v_mfma_f32_16x16x32_bf16 v[72:75], v[172:175], v[208:211], v[72:75]
	s_setprio 0
	s_barrier
	s_add_i32 s16, s43, s39
	v_lshl_add_u64 v[154:155], v[154:155], 0, s[94:95]
	s_mov_b32 m0, s16
	ds_read_b128 v[176:179], v159 offset:49152
	ds_read_b128 v[180:183], v159 offset:50176
	ds_read_b128 v[184:187], v159 offset:51200
	ds_read_b128 v[188:191], v159 offset:52224
	ds_read_b128 v[194:197], v159 offset:53248
	ds_read_b128 v[198:201], v159 offset:54272
	ds_read_b128 v[204:207], v159 offset:55296
	ds_read_b128 v[208:211], v159 offset:56320
	global_load_lds_dwordx4 v[154:155], off
	s_add_i32 m0, s16, 0x2000
	s_add_u32 s16, s20, 0xb0080
	v_lshl_add_u64 v[154:155], v[212:213], 0, s[94:95]
	s_addc_u32 s17, s21, 0
	s_add_i32 s20, s44, s39
	global_load_lds_dwordx4 v[154:155], off
	v_lshl_add_u64 v[154:155], s[16:17], 0, v[192:193]
	s_mov_b32 m0, s20
	s_nop 0
	global_load_lds_dwordx4 v[154:155], off
	v_lshl_add_u64 v[154:155], s[16:17], 0, v[144:145]
	s_add_i32 m0, s20, 0x2000
	s_nop 0
	global_load_lds_dwordx4 v[154:155], off
	v_lshl_add_u64 v[154:155], v[214:215], 0, s[94:95]
	s_mov_b32 m0, s51
	s_nop 0
	global_load_lds_dwordx4 v[154:155], off
	v_lshl_add_u64 v[154:155], v[216:217], 0, s[94:95]
	s_mov_b32 m0, s76
	s_nop 0
	global_load_lds_dwordx4 v[154:155], off
	s_waitcnt vmcnt(8)
	s_waitcnt lgkmcnt(0)
	s_barrier
	s_setprio 1
	s_waitcnt lgkmcnt(0)
	v_mfma_f32_16x16x32_bf16 v[60:63], v[64:67], v[176:179], v[60:63]
	v_mfma_f32_16x16x32_bf16 v[56:59], v[80:83], v[176:179], v[56:59]
	v_mfma_f32_16x16x32_bf16 v[52:55], v[64:67], v[184:187], v[52:55]
	v_mfma_f32_16x16x32_bf16 v[48:51], v[80:83], v[184:187], v[48:51]
	v_mfma_f32_16x16x32_bf16 v[28:31], v[64:67], v[194:197], v[28:31]
	v_mfma_f32_16x16x32_bf16 v[24:27], v[80:83], v[194:197], v[24:27]
	v_mfma_f32_16x16x32_bf16 v[16:19], v[64:67], v[204:207], v[16:19]
	v_mfma_f32_16x16x32_bf16 v[8:11], v[80:83], v[204:207], v[8:11]
	v_mfma_f32_16x16x32_bf16 v[60:63], v[68:71], v[180:183], v[60:63]
	v_mfma_f32_16x16x32_bf16 v[56:59], v[92:95], v[180:183], v[56:59]
	v_mfma_f32_16x16x32_bf16 v[52:55], v[68:71], v[188:191], v[52:55]
	v_mfma_f32_16x16x32_bf16 v[48:51], v[92:95], v[188:191], v[48:51]
	v_mfma_f32_16x16x32_bf16 v[28:31], v[68:71], v[198:201], v[28:31]
	v_mfma_f32_16x16x32_bf16 v[24:27], v[92:95], v[198:201], v[24:27]
	v_mfma_f32_16x16x32_bf16 v[16:19], v[68:71], v[208:211], v[16:19]
	v_mfma_f32_16x16x32_bf16 v[8:11], v[92:95], v[208:211], v[8:11]
	v_mfma_f32_16x16x32_bf16 v[44:47], v[160:163], v[176:179], v[44:47]
	v_mfma_f32_16x16x32_bf16 v[40:43], v[168:171], v[176:179], v[40:43]
	v_mfma_f32_16x16x32_bf16 v[36:39], v[160:163], v[184:187], v[36:39]
	v_mfma_f32_16x16x32_bf16 v[32:35], v[168:171], v[184:187], v[32:35]
	v_mfma_f32_16x16x32_bf16 v[20:23], v[160:163], v[194:197], v[20:23]
	v_mfma_f32_16x16x32_bf16 v[12:15], v[168:171], v[194:197], v[12:15]
	v_mfma_f32_16x16x32_bf16 v[4:7], v[160:163], v[204:207], v[4:7]
	v_mfma_f32_16x16x32_bf16 v[0:3], v[168:171], v[204:207], v[0:3]
	v_mfma_f32_16x16x32_bf16 v[44:47], v[164:167], v[180:183], v[44:47]
	v_mfma_f32_16x16x32_bf16 v[40:43], v[172:175], v[180:183], v[40:43]
	v_mfma_f32_16x16x32_bf16 v[36:39], v[164:167], v[188:191], v[36:39]
	v_mfma_f32_16x16x32_bf16 v[32:35], v[172:175], v[188:191], v[32:35]
	v_mfma_f32_16x16x32_bf16 v[20:23], v[164:167], v[198:201], v[20:23]
	v_mfma_f32_16x16x32_bf16 v[12:15], v[172:175], v[198:201], v[12:15]
	v_mfma_f32_16x16x32_bf16 v[4:7], v[164:167], v[208:211], v[4:7]
	v_mfma_f32_16x16x32_bf16 v[0:3], v[172:175], v[208:211], v[0:3]
	s_setprio 0
	s_barrier
	s_add_i32 vcc_lo, vcc_lo, 2
	s_add_u32 s80, s80, 0x100
	s_addc_u32 s81, s81, 0
	s_cmp_gt_u32 vcc_lo, 41
	s_mov_b64 s[16:17], s[18:19]
	s_cbranch_scc0 .LBB0_1411
